# v20 + redundant s_waitcnt lgkmcnt(0) after the pre-MFMA barrier removed (the wait before the barrier already covers it)
# speedup vs baseline: 1.0255x; 1.0255x over previous
; #define PG8_STAGE(bufoff, gbase, voff) do { _Pragma("unroll") for (int _i = 0; _i < 2; ++_i) \
;         __builtin_amdgcn_global_load_lds((const unsigned*)((const char*)(gbase) + (voff)[_i]), (PG8_LAS unsigned*)(lds + (bufoff) + ldsw + _i * 8192), 16, 0, 0); } while (0)
; #define PG8_LDA(dst, b, h) do { _Pragma("unroll") for (int m = 0; m < 4; ++m) _Pragma("unroll") for (int k = 0; k < 2; ++k) dst[m][k] = *(const PG8_LAS bf16x8*)(lds + PG8_SA(b, h) + aoff + m * 2048 + k * 1024); } while (0)
; #define PG8_LDB(dst, b, h) do { _Pragma("unroll") for (int n = 0; n < 2; ++n) _Pragma("unroll") for (int k = 0; k < 2; ++k) dst[n][k] = *(const PG8_LAS bf16x8*)(lds + PG8_SB(b, h) + boff + n * 2048 + k * 1024); } while (0)
; #define PG8_WAIT_V(n) asm volatile("s_waitcnt vmcnt(" #n ")" ::: "memory")
; #define PG8_WAIT_L(n) asm volatile("s_waitcnt lgkmcnt(" #n ")" ::: "memory")
; #define PG8_BAR __builtin_amdgcn_s_barrier()
; #define PG8_SCHED __builtin_amdgcn_sched_barrier(0)
; template <class Epi, class Sched, bool ALIGN_EPI = false, bool SP2 = false>
; __device__ __forceinline__ void gemm_phase(PG8_LAS unsigned char* lds, const Gemm g, const Sched& S, const Epi& E) {
;     ...
;     for (;;) {
;         const bool has_next = S.next(ui + 1, nxt);
;         const char* nA = has_next ? (const char*)g.A + (size_t)nxt.pm * tA + (size_t)nxt.pn * pnA : cA; const char* nB = has_next ? (const char*)g.Bt + (size_t)nxt.pn * tB : cB;
; #pragma nounroll
;         for (int t = 0; t < nt; t += 2) {
;             const bool last = (t == nt - 2);
;             const char* a1 = cA + (size_t)(t + 1) * kstep;
;             const char* a2 = last ? nA : cA + (size_t)(t + 2) * kstep; const char* b2 = last ? nB : cB + (size_t)(t + 2) * kstep;
;             const char* a3 = a2 + kstep; const char* b3 = b2 + kstep;
;             if (last && has_next) S.a_ready(nxt);
;             if constexpr (SP2) {
;             PG8_LDB(B0, 0, 0); PG8_LDB(B1, 0, 1); PG8_SCHED; PG8_LDA(At, 0, 0); PG8_STAGE(PG8_SA(1, 1), a1 + hA, voffA);
;             PG8_WAIT_V(8); PG8_WAIT_L(0); PG8_BAR; PG8_MMA(0, 0, At, B0); PG8_MMA(0, 1, At, B1); PG8_BAR; PG8_SCHED;
;             PG8_LDA(At, 0, 1); PG8_STAGE(PG8_SB(0, 0), b2, voffB); PG8_STAGE(PG8_SB(0, 1), b2 + hB, voffB); PG8_STAGE(PG8_SA(0, 0), a2, voffA);
;             PG8_WAIT_V(8); PG8_WAIT_L(0); PG8_BAR; PG8_MMA(1, 0, At, B0); PG8_MMA(1, 1, At, B1); PG8_BAR; PG8_SCHED;
.LBB0_189:
	s_ashr_i32 s55, s54, 31
	s_lshl_b64 s[56:57], s[54:55], 20
	s_add_u32 s56, s69, s56
	s_addc_u32 s57, s70, s57
	s_and_b64 s[58:59], s[8:9], exec
	s_cselect_b32 s11, s57, s63
	s_cselect_b32 s33, s56, s62
	s_ashr_i32 s53, s52, 31
	s_lshl_b64 s[58:59], s[52:53], 20
	s_add_u32 s58, s71, s58
	s_addc_u32 s59, s72, s59
	s_and_b64 s[66:67], s[8:9], exec
	s_cselect_b32 s53, s59, s65
	s_cselect_b32 s55, s58, s64
	s_add_u32 s62, s62, 0x80080
	s_addc_u32 s63, s63, 0
	s_add_u32 s61, s64, 0x100
	v_mov_b32_e32 v2, 0
	s_addc_u32 s96, s65, 0
	s_mov_b32 s97, -2
	v_mov_b32_e32 v3, v2
	ds_read_b128 v[130:133], v229
	ds_read_b128 v[134:137], v229 offset:1024
	ds_read_b128 v[138:141], v229 offset:2048
	ds_read_b128 v[142:145], v229 offset:3072
	ds_read_b128 v[146:149], v230
	ds_read_b128 v[150:153], v230 offset:1024
	ds_read_b128 v[154:157], v230 offset:2048
	ds_read_b128 v[158:161], v230 offset:3072
	s_add_u32 s64, s62, 0xfff80080
	s_addc_u32 s65, s63, -1
	s_cmp_eq_u32 s97, 28
	s_cselect_b32 s67, s11, s65
	s_cselect_b32 s66, s33, s64
	s_cselect_b32 s65, s53, s96
	s_cselect_b32 s64, s55, s61
	s_add_i32 m0, s74, 0xc000
	ds_read_b128 v[162:165], v231
	ds_read_b128 v[166:169], v231 offset:1024
	ds_read_b128 v[170:173], v231 offset:2048
	ds_read_b128 v[174:177], v231 offset:3072
	ds_read_b128 v[178:181], v231 offset:4096
	ds_read_b128 v[182:185], v231 offset:5120
	ds_read_b128 v[186:189], v231 offset:6144
	ds_read_b128 v[190:193], v231 offset:7168
	global_load_lds_dwordx4 v212, s[62:63]
	s_add_i32 m0, s74, 0xe000
	s_nop 0
	global_load_lds_dwordx4 v214, s[62:63]
	s_waitcnt vmcnt(8)
	s_waitcnt lgkmcnt(0)
	s_barrier
	v_mfma_f32_16x16x32_bf16 v[126:129], v[130:133], v[162:165], 0
	v_mfma_f32_16x16x32_bf16 v[122:125], v[138:141], v[162:165], 0
	v_mfma_f32_16x16x32_bf16 v[110:113], v[130:133], v[170:173], 0
	v_mfma_f32_16x16x32_bf16 v[106:109], v[138:141], v[170:173], 0
	v_mfma_f32_16x16x32_bf16 v[94:97], v[130:133], v[178:181], 0
	v_mfma_f32_16x16x32_bf16 v[90:93], v[138:141], v[178:181], 0
	v_mfma_f32_16x16x32_bf16 v[78:81], v[130:133], v[186:189], 0
	v_mfma_f32_16x16x32_bf16 v[74:77], v[138:141], v[186:189], 0
	v_mfma_f32_16x16x32_bf16 v[126:129], v[134:137], v[166:169], v[126:129]
	v_mfma_f32_16x16x32_bf16 v[122:125], v[142:145], v[166:169], v[122:125]
	v_mfma_f32_16x16x32_bf16 v[110:113], v[134:137], v[174:177], v[110:113]
	v_mfma_f32_16x16x32_bf16 v[106:109], v[142:145], v[174:177], v[106:109]
	v_mfma_f32_16x16x32_bf16 v[94:97], v[134:137], v[182:185], v[94:97]
	v_mfma_f32_16x16x32_bf16 v[90:93], v[142:145], v[182:185], v[90:93]
	v_mfma_f32_16x16x32_bf16 v[78:81], v[134:137], v[190:193], v[78:81]
	v_mfma_f32_16x16x32_bf16 v[74:77], v[142:145], v[190:193], v[74:77]
	v_mfma_f32_16x16x32_bf16 v[118:121], v[146:149], v[162:165], 0
	v_mfma_f32_16x16x32_bf16 v[114:117], v[154:157], v[162:165], 0
	v_mfma_f32_16x16x32_bf16 v[102:105], v[146:149], v[170:173], 0
	v_mfma_f32_16x16x32_bf16 v[98:101], v[154:157], v[170:173], 0
	v_mfma_f32_16x16x32_bf16 v[86:89], v[146:149], v[178:181], 0
	v_mfma_f32_16x16x32_bf16 v[82:85], v[154:157], v[178:181], 0
	v_mfma_f32_16x16x32_bf16 v[70:73], v[146:149], v[186:189], 0
	v_mfma_f32_16x16x32_bf16 v[66:69], v[154:157], v[186:189], 0
	v_mfma_f32_16x16x32_bf16 v[118:121], v[150:153], v[166:169], v[118:121]
	v_mfma_f32_16x16x32_bf16 v[114:117], v[158:161], v[166:169], v[114:117]
	v_mfma_f32_16x16x32_bf16 v[102:105], v[150:153], v[174:177], v[102:105]
	v_mfma_f32_16x16x32_bf16 v[98:101], v[158:161], v[174:177], v[98:101]
	v_mfma_f32_16x16x32_bf16 v[86:89], v[150:153], v[182:185], v[86:89]
	v_mfma_f32_16x16x32_bf16 v[82:85], v[158:161], v[182:185], v[82:85]
	v_mfma_f32_16x16x32_bf16 v[70:73], v[150:153], v[190:193], v[70:73]
	v_mfma_f32_16x16x32_bf16 v[66:69], v[158:161], v[190:193], v[66:69]
	s_barrier
	s_add_i32 vcc_lo, s84, s73
	s_add_u32 s34, s64, s38
	s_addc_u32 s35, s65, s39
	s_mov_b32 m0, vcc_lo
	ds_read_b128 v[162:165], v231 offset:16384
	ds_read_b128 v[166:169], v231 offset:17408
	ds_read_b128 v[170:173], v231 offset:18432
	ds_read_b128 v[174:177], v231 offset:19456
	ds_read_b128 v[178:181], v231 offset:20480
	ds_read_b128 v[182:185], v231 offset:21504
	ds_read_b128 v[186:189], v231 offset:22528
	ds_read_b128 v[190:193], v231 offset:23552
	global_load_lds_dwordx4 v196, s[64:65]
	s_add_i32 m0, vcc_lo, 0x2000
	s_add_u32 vcc_lo, s64, 0x80000
	s_addc_u32 vcc_hi, s65, 0
	s_add_i32 s86, s85, s73
	global_load_lds_dwordx4 v200, s[64:65]
	s_mov_b32 m0, s86
	s_nop 0
	global_load_lds_dwordx4 v196, vcc
	s_add_i32 m0, s86, 0x2000
	s_nop 0
	global_load_lds_dwordx4 v200, vcc
	s_add_u32 s98, s66, s38
	s_addc_u32 s99, s67, s39
	s_mov_b32 m0, s74
	s_nop 0
	global_load_lds_dwordx4 v194, s[66:67]
	s_mov_b32 m0, s75
	s_nop 0
	global_load_lds_dwordx4 v198, s[66:67]
	s_waitcnt vmcnt(8)
	s_waitcnt lgkmcnt(0)
	s_barrier
; #define PG8_STAGE(bufoff, gbase, voff) do { _Pragma("unroll") for (int _i = 0; _i < 2; ++_i) \
;         __builtin_amdgcn_global_load_lds((const unsigned*)((const char*)(gbase) + (voff)[_i]), (PG8_LAS unsigned*)(lds + (bufoff) + ldsw + _i * 8192), 16, 0, 0); } while (0)
; #define PG8_LDA(dst, b, h) do { _Pragma("unroll") for (int m = 0; m < 4; ++m) _Pragma("unroll") for (int k = 0; k < 2; ++k) dst[m][k] = *(const PG8_LAS bf16x8*)(lds + PG8_SA(b, h) + aoff + m * 2048 + k * 1024); } while (0)
; #define PG8_LDB(dst, b, h) do { _Pragma("unroll") for (int n = 0; n < 2; ++n) _Pragma("unroll") for (int k = 0; k < 2; ++k) dst[n][k] = *(const PG8_LAS bf16x8*)(lds + PG8_SB(b, h) + boff + n * 2048 + k * 1024); } while (0)
; #define PG8_MMA(ai, bj, At, Bt) do { __builtin_amdgcn_s_setprio(1); _Pragma("unroll") for (int m = 0; m < 4; ++m) _Pragma("unroll") for (int n = 0; n < 2; ++n) _Pragma("unroll") for (int k = 0; k < 2; ++k) \
;         acc[ai][bj][m][n] = __builtin_amdgcn_mfma_f32_16x16x32_bf16(Bt[n][k], At[m][k], acc[ai][bj][m][n], 0, 0, 0); __builtin_amdgcn_s_setprio(0); } while (0)
; #define PG8_WAIT_V(n) asm volatile("s_waitcnt vmcnt(" #n ")" ::: "memory")
; #define PG8_WAIT_L(n) asm volatile("s_waitcnt lgkmcnt(" #n ")" ::: "memory")
; #define PG8_BAR __builtin_amdgcn_s_barrier()
; template <class Epi, class Sched, bool ALIGN_EPI = false, bool SP2 = false>
; __device__ __forceinline__ void gemm_phase(PG8_LAS unsigned char* lds, const Gemm g, const Sched& S, const Epi& E) {
;     ...
;             PG8_LDB(B0, 0, 0); PG8_LDB(B1, 0, 1); PG8_SCHED; PG8_LDA(At, 0, 0); PG8_STAGE(PG8_SA(1, 1), a1 + hA, voffA);
;             PG8_WAIT_V(8); PG8_WAIT_L(0); PG8_BAR; PG8_MMA(0, 0, At, B0); PG8_MMA(0, 1, At, B1); PG8_BAR; PG8_SCHED;
;             PG8_LDA(At, 0, 1); PG8_STAGE(PG8_SB(0, 0), b2, voffB); PG8_STAGE(PG8_SB(0, 1), b2 + hB, voffB); PG8_STAGE(PG8_SA(0, 0), a2, voffA);
;             PG8_WAIT_V(8); PG8_WAIT_L(0); PG8_BAR; PG8_MMA(1, 0, At, B0); PG8_MMA(1, 1, At, B1); PG8_BAR; PG8_SCHED;
;             PG8_LDB(B0, 1, 0); PG8_LDB(B1, 1, 1); PG8_SCHED; PG8_LDA(At, 1, 0); PG8_STAGE(PG8_SA(0, 1), a2 + hA, voffA);
;             PG8_WAIT_V(8); PG8_WAIT_L(0); PG8_BAR; PG8_MMA(0, 0, At, B0); PG8_MMA(0, 1, At, B1); PG8_BAR; PG8_SCHED;
;             PG8_LDA(At, 1, 1); PG8_STAGE(PG8_SB(1, 0), b3, voffB); PG8_STAGE(PG8_SB(1, 1), b3 + hB, voffB); PG8_STAGE(PG8_SA(1, 0), a3, voffA);
	v_mfma_f32_16x16x32_bf16 v[62:65], v[130:133], v[162:165], 0
	v_mfma_f32_16x16x32_bf16 v[58:61], v[138:141], v[162:165], 0
	v_mfma_f32_16x16x32_bf16 v[46:49], v[130:133], v[170:173], 0
	v_mfma_f32_16x16x32_bf16 v[42:45], v[138:141], v[170:173], 0
	v_mfma_f32_16x16x32_bf16 v[30:33], v[130:133], v[178:181], 0
	v_mfma_f32_16x16x32_bf16 v[26:29], v[138:141], v[178:181], 0
	v_mfma_f32_16x16x32_bf16 v[14:17], v[130:133], v[186:189], 0
	v_mfma_f32_16x16x32_bf16 v[10:13], v[138:141], v[186:189], 0
	v_mfma_f32_16x16x32_bf16 v[62:65], v[134:137], v[166:169], v[62:65]
	v_mfma_f32_16x16x32_bf16 v[58:61], v[142:145], v[166:169], v[58:61]
	v_mfma_f32_16x16x32_bf16 v[46:49], v[134:137], v[174:177], v[46:49]
	v_mfma_f32_16x16x32_bf16 v[42:45], v[142:145], v[174:177], v[42:45]
	v_mfma_f32_16x16x32_bf16 v[30:33], v[134:137], v[182:185], v[30:33]
	v_mfma_f32_16x16x32_bf16 v[26:29], v[142:145], v[182:185], v[26:29]
	v_mfma_f32_16x16x32_bf16 v[14:17], v[134:137], v[190:193], v[14:17]
	v_mfma_f32_16x16x32_bf16 v[10:13], v[142:145], v[190:193], v[10:13]
	v_mfma_f32_16x16x32_bf16 v[54:57], v[146:149], v[162:165], 0
	v_mfma_f32_16x16x32_bf16 v[50:53], v[154:157], v[162:165], 0
	v_mfma_f32_16x16x32_bf16 v[38:41], v[146:149], v[170:173], 0
	v_mfma_f32_16x16x32_bf16 v[34:37], v[154:157], v[170:173], 0
	v_mfma_f32_16x16x32_bf16 v[22:25], v[146:149], v[178:181], 0
	v_mfma_f32_16x16x32_bf16 v[18:21], v[154:157], v[178:181], 0
	v_mfma_f32_16x16x32_bf16 v[6:9], v[146:149], v[186:189], 0
	v_mfma_f32_16x16x32_bf16 v[2:5], v[154:157], v[186:189], 0
	v_mfma_f32_16x16x32_bf16 v[54:57], v[150:153], v[166:169], v[54:57]
	v_mfma_f32_16x16x32_bf16 v[50:53], v[158:161], v[166:169], v[50:53]
	v_mfma_f32_16x16x32_bf16 v[38:41], v[150:153], v[174:177], v[38:41]
	v_mfma_f32_16x16x32_bf16 v[34:37], v[158:161], v[174:177], v[34:37]
	v_mfma_f32_16x16x32_bf16 v[22:25], v[150:153], v[182:185], v[22:25]
	v_mfma_f32_16x16x32_bf16 v[18:21], v[158:161], v[182:185], v[18:21]
	v_mfma_f32_16x16x32_bf16 v[6:9], v[150:153], v[190:193], v[6:9]
	v_mfma_f32_16x16x32_bf16 v[2:5], v[158:161], v[190:193], v[2:5]
	s_barrier
	s_add_i32 s86, 0, 0x18000
	s_add_i32 vcc_lo, 0, 0x1c000
	v_add_u32_e32 v142, s86, v223
	v_add_u32_e32 v158, vcc_lo, v223
	ds_read_b128 v[130:133], v142
	ds_read_b128 v[134:137], v142 offset:1024
	ds_read_b128 v[138:141], v142 offset:2048
	ds_read_b128 v[142:145], v142 offset:3072
	ds_read_b128 v[146:149], v158
	ds_read_b128 v[150:153], v158 offset:1024
	ds_read_b128 v[154:157], v158 offset:2048
	ds_read_b128 v[158:161], v158 offset:3072
	s_add_u32 s66, s66, 0x80000
	s_addc_u32 s67, s67, 0
	s_mov_b32 m0, s76
	ds_read_b128 v[162:165], v231 offset:32768
	ds_read_b128 v[166:169], v231 offset:33792
	ds_read_b128 v[170:173], v231 offset:34816
	ds_read_b128 v[174:177], v231 offset:35840
	ds_read_b128 v[178:181], v231 offset:36864
	ds_read_b128 v[182:185], v231 offset:37888
	ds_read_b128 v[186:189], v231 offset:38912
	ds_read_b128 v[190:193], v231 offset:39936
	global_load_lds_dwordx4 v194, s[66:67]
	s_mov_b32 m0, s77
	s_nop 0
	global_load_lds_dwordx4 v198, s[66:67]
	s_waitcnt vmcnt(8)
	s_waitcnt lgkmcnt(0)
	s_barrier
	v_mfma_f32_16x16x32_bf16 v[126:129], v[130:133], v[162:165], v[126:129]
	v_mfma_f32_16x16x32_bf16 v[122:125], v[138:141], v[162:165], v[122:125]
	v_mfma_f32_16x16x32_bf16 v[110:113], v[130:133], v[170:173], v[110:113]
	v_mfma_f32_16x16x32_bf16 v[106:109], v[138:141], v[170:173], v[106:109]
	v_mfma_f32_16x16x32_bf16 v[94:97], v[130:133], v[178:181], v[94:97]
	v_mfma_f32_16x16x32_bf16 v[90:93], v[138:141], v[178:181], v[90:93]
	v_mfma_f32_16x16x32_bf16 v[78:81], v[130:133], v[186:189], v[78:81]
	v_mfma_f32_16x16x32_bf16 v[74:77], v[138:141], v[186:189], v[74:77]
	v_mfma_f32_16x16x32_bf16 v[126:129], v[134:137], v[166:169], v[126:129]
	v_mfma_f32_16x16x32_bf16 v[122:125], v[142:145], v[166:169], v[122:125]
	v_mfma_f32_16x16x32_bf16 v[110:113], v[134:137], v[174:177], v[110:113]
	v_mfma_f32_16x16x32_bf16 v[106:109], v[142:145], v[174:177], v[106:109]
	v_mfma_f32_16x16x32_bf16 v[94:97], v[134:137], v[182:185], v[94:97]
	v_mfma_f32_16x16x32_bf16 v[90:93], v[142:145], v[182:185], v[90:93]
	v_mfma_f32_16x16x32_bf16 v[78:81], v[134:137], v[190:193], v[78:81]
	v_mfma_f32_16x16x32_bf16 v[74:77], v[142:145], v[190:193], v[74:77]
	v_mfma_f32_16x16x32_bf16 v[118:121], v[146:149], v[162:165], v[118:121]
	v_mfma_f32_16x16x32_bf16 v[114:117], v[154:157], v[162:165], v[114:117]
	v_mfma_f32_16x16x32_bf16 v[102:105], v[146:149], v[170:173], v[102:105]
	v_mfma_f32_16x16x32_bf16 v[98:101], v[154:157], v[170:173], v[98:101]
	v_mfma_f32_16x16x32_bf16 v[86:89], v[146:149], v[178:181], v[86:89]
	v_mfma_f32_16x16x32_bf16 v[82:85], v[154:157], v[178:181], v[82:85]
	v_mfma_f32_16x16x32_bf16 v[70:73], v[146:149], v[186:189], v[70:73]
	v_mfma_f32_16x16x32_bf16 v[66:69], v[154:157], v[186:189], v[66:69]
	v_mfma_f32_16x16x32_bf16 v[118:121], v[150:153], v[166:169], v[118:121]
	v_mfma_f32_16x16x32_bf16 v[114:117], v[158:161], v[166:169], v[114:117]
	v_mfma_f32_16x16x32_bf16 v[102:105], v[150:153], v[174:177], v[102:105]
	v_mfma_f32_16x16x32_bf16 v[98:101], v[158:161], v[174:177], v[98:101]
	v_mfma_f32_16x16x32_bf16 v[86:89], v[150:153], v[182:185], v[86:89]
	v_mfma_f32_16x16x32_bf16 v[82:85], v[158:161], v[182:185], v[82:85]
	v_mfma_f32_16x16x32_bf16 v[70:73], v[150:153], v[190:193], v[70:73]
	v_mfma_f32_16x16x32_bf16 v[66:69], v[158:161], v[190:193], v[66:69]
	s_barrier
; #define PG8_STAGE(bufoff, gbase, voff) do { _Pragma("unroll") for (int _i = 0; _i < 2; ++_i) \
;         __builtin_amdgcn_global_load_lds((const unsigned*)((const char*)(gbase) + (voff)[_i]), (PG8_LAS unsigned*)(lds + (bufoff) + ldsw + _i * 8192), 16, 0, 0); } while (0)
; #define PG8_LDA(dst, b, h) do { _Pragma("unroll") for (int m = 0; m < 4; ++m) _Pragma("unroll") for (int k = 0; k < 2; ++k) dst[m][k] = *(const PG8_LAS bf16x8*)(lds + PG8_SA(b, h) + aoff + m * 2048 + k * 1024); } while (0)
; #define PG8_LDB(dst, b, h) do { _Pragma("unroll") for (int n = 0; n < 2; ++n) _Pragma("unroll") for (int k = 0; k < 2; ++k) dst[n][k] = *(const PG8_LAS bf16x8*)(lds + PG8_SB(b, h) + boff + n * 2048 + k * 1024); } while (0)
; template <class Epi, class Sched, bool ALIGN_EPI = false, bool SP2 = false>
; __device__ __forceinline__ void gemm_phase(PG8_LAS unsigned char* lds, const Gemm g, const Sched& S, const Epi& E) {
;     ...
;         for (int t = 0; t < nt; t += 2) {
;             const bool last = (t == nt - 2);
;             const char* a1 = cA + (size_t)(t + 1) * kstep;
;             const char* a2 = last ? nA : cA + (size_t)(t + 2) * kstep; const char* b2 = last ? nB : cB + (size_t)(t + 2) * kstep;
;             const char* a3 = a2 + kstep; const char* b3 = b2 + kstep;
;             if (last && has_next) S.a_ready(nxt);
;             if constexpr (SP2) {
;             PG8_LDB(B0, 0, 0); PG8_LDB(B1, 0, 1); PG8_SCHED; PG8_LDA(At, 0, 0); PG8_STAGE(PG8_SA(1, 1), a1 + hA, voffA);
;             PG8_WAIT_V(8); PG8_WAIT_L(0); PG8_BAR; PG8_MMA(0, 0, At, B0); PG8_MMA(0, 1, At, B1); PG8_BAR; PG8_SCHED;
;             PG8_LDA(At, 0, 1); PG8_STAGE(PG8_SB(0, 0), b2, voffB); PG8_STAGE(PG8_SB(0, 1), b2 + hB, voffB); PG8_STAGE(PG8_SA(0, 0), a2, voffA);
;             PG8_WAIT_V(8); PG8_WAIT_L(0); PG8_BAR; PG8_MMA(1, 0, At, B0); PG8_MMA(1, 1, At, B1); PG8_BAR; PG8_SCHED;
;             PG8_LDB(B0, 1, 0); PG8_LDB(B1, 1, 1); PG8_SCHED; PG8_LDA(At, 1, 0); PG8_STAGE(PG8_SA(0, 1), a2 + hA, voffA);
;             PG8_WAIT_V(8); PG8_WAIT_L(0); PG8_BAR; PG8_MMA(0, 0, At, B0); PG8_MMA(0, 1, At, B1); PG8_BAR; PG8_SCHED;
;             PG8_LDA(At, 1, 1); PG8_STAGE(PG8_SB(1, 0), b3, voffB); PG8_STAGE(PG8_SB(1, 1), b3 + hB, voffB); PG8_STAGE(PG8_SA(1, 0), a3, voffA);
;             PG8_WAIT_V(8); PG8_WAIT_L(0); PG8_BAR; PG8_MMA(1, 0, At, B0); PG8_MMA(1, 1, At, B1); PG8_BAR; PG8_SCHED;
	s_add_i32 s66, s86, s73
	s_mov_b32 m0, s66
	ds_read_b128 v[162:165], v231 offset:49152
	ds_read_b128 v[166:169], v231 offset:50176
	ds_read_b128 v[170:173], v231 offset:51200
	ds_read_b128 v[174:177], v231 offset:52224
	ds_read_b128 v[178:181], v231 offset:53248
	ds_read_b128 v[182:185], v231 offset:54272
	ds_read_b128 v[186:189], v231 offset:55296
	ds_read_b128 v[190:193], v231 offset:56320
	global_load_lds_dwordx4 v196, s[34:35]
	s_add_i32 m0, s66, 0x2000
	s_add_u32 s64, s64, 0x80080
	s_addc_u32 s65, s65, 0
	s_add_i32 s66, vcc_lo, s73
	global_load_lds_dwordx4 v200, s[34:35]
	s_mov_b32 m0, s66
	s_nop 0
	global_load_lds_dwordx4 v196, s[64:65]
	s_add_i32 m0, s66, 0x2000
	s_nop 0
	global_load_lds_dwordx4 v200, s[64:65]
	s_mov_b32 m0, s81
	s_nop 0
	global_load_lds_dwordx4 v194, s[98:99]
	s_mov_b32 m0, s82
	s_nop 0
	global_load_lds_dwordx4 v198, s[98:99]
	s_waitcnt vmcnt(8)
	s_waitcnt lgkmcnt(0)
	s_barrier
	v_mfma_f32_16x16x32_bf16 v[62:65], v[130:133], v[162:165], v[62:65]
	v_mfma_f32_16x16x32_bf16 v[58:61], v[138:141], v[162:165], v[58:61]
	v_mfma_f32_16x16x32_bf16 v[46:49], v[130:133], v[170:173], v[46:49]
	v_mfma_f32_16x16x32_bf16 v[42:45], v[138:141], v[170:173], v[42:45]
	v_mfma_f32_16x16x32_bf16 v[30:33], v[130:133], v[178:181], v[30:33]
	v_mfma_f32_16x16x32_bf16 v[26:29], v[138:141], v[178:181], v[26:29]
	v_mfma_f32_16x16x32_bf16 v[14:17], v[130:133], v[186:189], v[14:17]
	v_mfma_f32_16x16x32_bf16 v[10:13], v[138:141], v[186:189], v[10:13]
	v_mfma_f32_16x16x32_bf16 v[62:65], v[134:137], v[166:169], v[62:65]
	v_mfma_f32_16x16x32_bf16 v[58:61], v[142:145], v[166:169], v[58:61]
	v_mfma_f32_16x16x32_bf16 v[46:49], v[134:137], v[174:177], v[46:49]
	v_mfma_f32_16x16x32_bf16 v[42:45], v[142:145], v[174:177], v[42:45]
	v_mfma_f32_16x16x32_bf16 v[30:33], v[134:137], v[182:185], v[30:33]
	v_mfma_f32_16x16x32_bf16 v[26:29], v[142:145], v[182:185], v[26:29]
	v_mfma_f32_16x16x32_bf16 v[14:17], v[134:137], v[190:193], v[14:17]
	v_mfma_f32_16x16x32_bf16 v[10:13], v[142:145], v[190:193], v[10:13]
	v_mfma_f32_16x16x32_bf16 v[54:57], v[146:149], v[162:165], v[54:57]
	v_mfma_f32_16x16x32_bf16 v[50:53], v[154:157], v[162:165], v[50:53]
	v_mfma_f32_16x16x32_bf16 v[38:41], v[146:149], v[170:173], v[38:41]
	v_mfma_f32_16x16x32_bf16 v[34:37], v[154:157], v[170:173], v[34:37]
	v_mfma_f32_16x16x32_bf16 v[22:25], v[146:149], v[178:181], v[22:25]
	v_mfma_f32_16x16x32_bf16 v[18:21], v[154:157], v[178:181], v[18:21]
	v_mfma_f32_16x16x32_bf16 v[6:9], v[146:149], v[186:189], v[6:9]
	v_mfma_f32_16x16x32_bf16 v[2:5], v[154:157], v[186:189], v[2:5]
	v_mfma_f32_16x16x32_bf16 v[54:57], v[150:153], v[166:169], v[54:57]
	v_mfma_f32_16x16x32_bf16 v[50:53], v[158:161], v[166:169], v[50:53]
	v_mfma_f32_16x16x32_bf16 v[38:41], v[150:153], v[174:177], v[38:41]
	v_mfma_f32_16x16x32_bf16 v[34:37], v[158:161], v[174:177], v[34:37]
	v_mfma_f32_16x16x32_bf16 v[22:25], v[150:153], v[182:185], v[22:25]
	v_mfma_f32_16x16x32_bf16 v[18:21], v[158:161], v[182:185], v[18:21]
	v_mfma_f32_16x16x32_bf16 v[6:9], v[150:153], v[190:193], v[6:9]
	v_mfma_f32_16x16x32_bf16 v[2:5], v[158:161], v[190:193], v[2:5]
	s_barrier
	s_add_i32 s97, s97, 2
	s_add_u32 s62, s62, 0x100
	s_addc_u32 s63, s63, 0
	s_add_u32 s61, s61, 0x100
	s_addc_u32 s96, s96, 0
	s_cmp_gt_u32 s97, 29
.LBB0_190:
	ds_read_b128 v[130:133], v229
	ds_read_b128 v[134:137], v229 offset:1024
	ds_read_b128 v[138:141], v229 offset:2048
	ds_read_b128 v[142:145], v229 offset:3072
	ds_read_b128 v[146:149], v230
	ds_read_b128 v[150:153], v230 offset:1024
	ds_read_b128 v[154:157], v230 offset:2048
	ds_read_b128 v[158:161], v230 offset:3072
	s_add_u32 s64, s62, 0xfff80080
	s_addc_u32 s65, s63, -1
	s_cmp_eq_u32 s97, 28
	s_cselect_b32 s67, s11, s65
	s_cselect_b32 s66, s33, s64
	s_cselect_b32 s65, s53, s96
	s_cselect_b32 s64, s55, s61
	s_add_i32 m0, s74, 0xc000
	ds_read_b128 v[162:165], v231
	ds_read_b128 v[166:169], v231 offset:1024
	ds_read_b128 v[170:173], v231 offset:2048
	ds_read_b128 v[174:177], v231 offset:3072
	ds_read_b128 v[178:181], v231 offset:4096
	ds_read_b128 v[182:185], v231 offset:5120
	ds_read_b128 v[186:189], v231 offset:6144
	ds_read_b128 v[190:193], v231 offset:7168
	global_load_lds_dwordx4 v212, s[62:63]
	s_add_i32 m0, s74, 0xe000
	s_nop 0
	global_load_lds_dwordx4 v214, s[62:63]
	s_waitcnt vmcnt(8)
	s_waitcnt lgkmcnt(0)
	s_barrier
	v_mfma_f32_16x16x32_bf16 v[126:129], v[130:133], v[162:165], v[126:129]
	v_mfma_f32_16x16x32_bf16 v[122:125], v[138:141], v[162:165], v[122:125]
	v_mfma_f32_16x16x32_bf16 v[110:113], v[130:133], v[170:173], v[110:113]
	v_mfma_f32_16x16x32_bf16 v[106:109], v[138:141], v[170:173], v[106:109]
	v_mfma_f32_16x16x32_bf16 v[94:97], v[130:133], v[178:181], v[94:97]
	v_mfma_f32_16x16x32_bf16 v[90:93], v[138:141], v[178:181], v[90:93]
	v_mfma_f32_16x16x32_bf16 v[78:81], v[130:133], v[186:189], v[78:81]
	v_mfma_f32_16x16x32_bf16 v[74:77], v[138:141], v[186:189], v[74:77]
	v_mfma_f32_16x16x32_bf16 v[126:129], v[134:137], v[166:169], v[126:129]
	v_mfma_f32_16x16x32_bf16 v[122:125], v[142:145], v[166:169], v[122:125]
	v_mfma_f32_16x16x32_bf16 v[110:113], v[134:137], v[174:177], v[110:113]
	v_mfma_f32_16x16x32_bf16 v[106:109], v[142:145], v[174:177], v[106:109]
	v_mfma_f32_16x16x32_bf16 v[94:97], v[134:137], v[182:185], v[94:97]
	v_mfma_f32_16x16x32_bf16 v[90:93], v[142:145], v[182:185], v[90:93]
	v_mfma_f32_16x16x32_bf16 v[78:81], v[134:137], v[190:193], v[78:81]
	v_mfma_f32_16x16x32_bf16 v[74:77], v[142:145], v[190:193], v[74:77]
	v_mfma_f32_16x16x32_bf16 v[118:121], v[146:149], v[162:165], v[118:121]
	v_mfma_f32_16x16x32_bf16 v[114:117], v[154:157], v[162:165], v[114:117]
	v_mfma_f32_16x16x32_bf16 v[102:105], v[146:149], v[170:173], v[102:105]
	v_mfma_f32_16x16x32_bf16 v[98:101], v[154:157], v[170:173], v[98:101]
	v_mfma_f32_16x16x32_bf16 v[86:89], v[146:149], v[178:181], v[86:89]
	v_mfma_f32_16x16x32_bf16 v[82:85], v[154:157], v[178:181], v[82:85]
	v_mfma_f32_16x16x32_bf16 v[70:73], v[146:149], v[186:189], v[70:73]
	v_mfma_f32_16x16x32_bf16 v[66:69], v[154:157], v[186:189], v[66:69]
	v_mfma_f32_16x16x32_bf16 v[118:121], v[150:153], v[166:169], v[118:121]
	v_mfma_f32_16x16x32_bf16 v[114:117], v[158:161], v[166:169], v[114:117]
	v_mfma_f32_16x16x32_bf16 v[102:105], v[150:153], v[174:177], v[102:105]
	v_mfma_f32_16x16x32_bf16 v[98:101], v[158:161], v[174:177], v[98:101]
	v_mfma_f32_16x16x32_bf16 v[86:89], v[150:153], v[182:185], v[86:89]
	v_mfma_f32_16x16x32_bf16 v[82:85], v[158:161], v[182:185], v[82:85]
	v_mfma_f32_16x16x32_bf16 v[70:73], v[150:153], v[190:193], v[70:73]
	v_mfma_f32_16x16x32_bf16 v[66:69], v[158:161], v[190:193], v[66:69]
	s_barrier
; #define PG8_STAGE(bufoff, gbase, voff) do { _Pragma("unroll") for (int _i = 0; _i < 2; ++_i) \
;         __builtin_amdgcn_global_load_lds((const unsigned*)((const char*)(gbase) + (voff)[_i]), (PG8_LAS unsigned*)(lds + (bufoff) + ldsw + _i * 8192), 16, 0, 0); } while (0)
; #define PG8_LDA(dst, b, h) do { _Pragma("unroll") for (int m = 0; m < 4; ++m) _Pragma("unroll") for (int k = 0; k < 2; ++k) dst[m][k] = *(const PG8_LAS bf16x8*)(lds + PG8_SA(b, h) + aoff + m * 2048 + k * 1024); } while (0)
; #define PG8_LDB(dst, b, h) do { _Pragma("unroll") for (int n = 0; n < 2; ++n) _Pragma("unroll") for (int k = 0; k < 2; ++k) dst[n][k] = *(const PG8_LAS bf16x8*)(lds + PG8_SB(b, h) + boff + n * 2048 + k * 1024); } while (0)
; #define PG8_MMA(ai, bj, At, Bt) do { __builtin_amdgcn_s_setprio(1); _Pragma("unroll") for (int m = 0; m < 4; ++m) _Pragma("unroll") for (int n = 0; n < 2; ++n) _Pragma("unroll") for (int k = 0; k < 2; ++k) \
;         acc[ai][bj][m][n] = __builtin_amdgcn_mfma_f32_16x16x32_bf16(Bt[n][k], At[m][k], acc[ai][bj][m][n], 0, 0, 0); __builtin_amdgcn_s_setprio(0); } while (0)
; #define PG8_WAIT_V(n) asm volatile("s_waitcnt vmcnt(" #n ")" ::: "memory")
; #define PG8_WAIT_L(n) asm volatile("s_waitcnt lgkmcnt(" #n ")" ::: "memory")
; #define PG8_BAR __builtin_amdgcn_s_barrier()
; template <class Epi, class Sched, bool ALIGN_EPI = false, bool SP2 = false>
; __device__ __forceinline__ void gemm_phase(PG8_LAS unsigned char* lds, const Gemm g, const Sched& S, const Epi& E) {
;     ...
;             PG8_LDB(B0, 0, 0); PG8_LDB(B1, 0, 1); PG8_SCHED; PG8_LDA(At, 0, 0); PG8_STAGE(PG8_SA(1, 1), a1 + hA, voffA);
;             PG8_WAIT_V(8); PG8_WAIT_L(0); PG8_BAR; PG8_MMA(0, 0, At, B0); PG8_MMA(0, 1, At, B1); PG8_BAR; PG8_SCHED;
;             PG8_LDA(At, 0, 1); PG8_STAGE(PG8_SB(0, 0), b2, voffB); PG8_STAGE(PG8_SB(0, 1), b2 + hB, voffB); PG8_STAGE(PG8_SA(0, 0), a2, voffA);
;             PG8_WAIT_V(8); PG8_WAIT_L(0); PG8_BAR; PG8_MMA(1, 0, At, B0); PG8_MMA(1, 1, At, B1); PG8_BAR; PG8_SCHED;
;             PG8_LDB(B0, 1, 0); PG8_LDB(B1, 1, 1); PG8_SCHED; PG8_LDA(At, 1, 0); PG8_STAGE(PG8_SA(0, 1), a2 + hA, voffA);
;             PG8_WAIT_V(8); PG8_WAIT_L(0); PG8_BAR; PG8_MMA(0, 0, At, B0); PG8_MMA(0, 1, At, B1); PG8_BAR; PG8_SCHED;
;             PG8_LDA(At, 1, 1); PG8_STAGE(PG8_SB(1, 0), b3, voffB); PG8_STAGE(PG8_SB(1, 1), b3 + hB, voffB); PG8_STAGE(PG8_SA(1, 0), a3, voffA);
	s_add_i32 vcc_lo, s84, s73
	s_add_u32 s34, s64, s38
	s_addc_u32 s35, s65, s39
	s_mov_b32 m0, vcc_lo
	ds_read_b128 v[162:165], v231 offset:16384
	ds_read_b128 v[166:169], v231 offset:17408
	ds_read_b128 v[170:173], v231 offset:18432
	ds_read_b128 v[174:177], v231 offset:19456
	ds_read_b128 v[178:181], v231 offset:20480
	ds_read_b128 v[182:185], v231 offset:21504
	ds_read_b128 v[186:189], v231 offset:22528
	ds_read_b128 v[190:193], v231 offset:23552
	global_load_lds_dwordx4 v196, s[64:65]
	s_add_i32 m0, vcc_lo, 0x2000
	s_add_u32 vcc_lo, s64, 0x80000
	s_addc_u32 vcc_hi, s65, 0
	s_add_i32 s86, s85, s73
	global_load_lds_dwordx4 v200, s[64:65]
	s_mov_b32 m0, s86
	s_nop 0
	global_load_lds_dwordx4 v196, vcc
	s_add_i32 m0, s86, 0x2000
	s_nop 0
	global_load_lds_dwordx4 v200, vcc
	s_add_u32 s98, s66, s38
	s_addc_u32 s99, s67, s39
	s_mov_b32 m0, s74
	s_nop 0
	global_load_lds_dwordx4 v194, s[66:67]
	s_mov_b32 m0, s75
	s_nop 0
	global_load_lds_dwordx4 v198, s[66:67]
	s_waitcnt vmcnt(8)
	s_waitcnt lgkmcnt(0)
	s_barrier
	v_mfma_f32_16x16x32_bf16 v[62:65], v[130:133], v[162:165], v[62:65]
	v_mfma_f32_16x16x32_bf16 v[58:61], v[138:141], v[162:165], v[58:61]
	v_mfma_f32_16x16x32_bf16 v[46:49], v[130:133], v[170:173], v[46:49]
	v_mfma_f32_16x16x32_bf16 v[42:45], v[138:141], v[170:173], v[42:45]
	v_mfma_f32_16x16x32_bf16 v[30:33], v[130:133], v[178:181], v[30:33]
	v_mfma_f32_16x16x32_bf16 v[26:29], v[138:141], v[178:181], v[26:29]
	v_mfma_f32_16x16x32_bf16 v[14:17], v[130:133], v[186:189], v[14:17]
	v_mfma_f32_16x16x32_bf16 v[10:13], v[138:141], v[186:189], v[10:13]
	v_mfma_f32_16x16x32_bf16 v[62:65], v[134:137], v[166:169], v[62:65]
	v_mfma_f32_16x16x32_bf16 v[58:61], v[142:145], v[166:169], v[58:61]
	v_mfma_f32_16x16x32_bf16 v[46:49], v[134:137], v[174:177], v[46:49]
	v_mfma_f32_16x16x32_bf16 v[42:45], v[142:145], v[174:177], v[42:45]
	v_mfma_f32_16x16x32_bf16 v[30:33], v[134:137], v[182:185], v[30:33]
	v_mfma_f32_16x16x32_bf16 v[26:29], v[142:145], v[182:185], v[26:29]
	v_mfma_f32_16x16x32_bf16 v[14:17], v[134:137], v[190:193], v[14:17]
	v_mfma_f32_16x16x32_bf16 v[10:13], v[142:145], v[190:193], v[10:13]
	v_mfma_f32_16x16x32_bf16 v[54:57], v[146:149], v[162:165], v[54:57]
	v_mfma_f32_16x16x32_bf16 v[50:53], v[154:157], v[162:165], v[50:53]
	v_mfma_f32_16x16x32_bf16 v[38:41], v[146:149], v[170:173], v[38:41]
	v_mfma_f32_16x16x32_bf16 v[34:37], v[154:157], v[170:173], v[34:37]
	v_mfma_f32_16x16x32_bf16 v[22:25], v[146:149], v[178:181], v[22:25]
	v_mfma_f32_16x16x32_bf16 v[18:21], v[154:157], v[178:181], v[18:21]
	v_mfma_f32_16x16x32_bf16 v[6:9], v[146:149], v[186:189], v[6:9]
	v_mfma_f32_16x16x32_bf16 v[2:5], v[154:157], v[186:189], v[2:5]
	v_mfma_f32_16x16x32_bf16 v[54:57], v[150:153], v[166:169], v[54:57]
	v_mfma_f32_16x16x32_bf16 v[50:53], v[158:161], v[166:169], v[50:53]
	v_mfma_f32_16x16x32_bf16 v[38:41], v[150:153], v[174:177], v[38:41]
	v_mfma_f32_16x16x32_bf16 v[34:37], v[158:161], v[174:177], v[34:37]
	v_mfma_f32_16x16x32_bf16 v[22:25], v[150:153], v[182:185], v[22:25]
	v_mfma_f32_16x16x32_bf16 v[18:21], v[158:161], v[182:185], v[18:21]
	v_mfma_f32_16x16x32_bf16 v[6:9], v[150:153], v[190:193], v[6:9]
	v_mfma_f32_16x16x32_bf16 v[2:5], v[158:161], v[190:193], v[2:5]
	s_barrier
	s_add_i32 s86, 0, 0x18000
	s_add_i32 vcc_lo, 0, 0x1c000
	v_add_u32_e32 v142, s86, v223
	v_add_u32_e32 v158, vcc_lo, v223
	ds_read_b128 v[130:133], v142
	ds_read_b128 v[134:137], v142 offset:1024
	ds_read_b128 v[138:141], v142 offset:2048
	ds_read_b128 v[142:145], v142 offset:3072
	ds_read_b128 v[146:149], v158
	ds_read_b128 v[150:153], v158 offset:1024
	ds_read_b128 v[154:157], v158 offset:2048
	ds_read_b128 v[158:161], v158 offset:3072
	s_add_u32 s66, s66, 0x80000
	s_addc_u32 s67, s67, 0
	s_mov_b32 m0, s76
	ds_read_b128 v[162:165], v231 offset:32768
	ds_read_b128 v[166:169], v231 offset:33792
	ds_read_b128 v[170:173], v231 offset:34816
	ds_read_b128 v[174:177], v231 offset:35840
	ds_read_b128 v[178:181], v231 offset:36864
	ds_read_b128 v[182:185], v231 offset:37888
	ds_read_b128 v[186:189], v231 offset:38912
	ds_read_b128 v[190:193], v231 offset:39936
	global_load_lds_dwordx4 v194, s[66:67]
	s_mov_b32 m0, s77
	s_nop 0
	global_load_lds_dwordx4 v198, s[66:67]
	s_waitcnt vmcnt(8)
	s_waitcnt lgkmcnt(0)
	s_barrier
; #define PG8_STAGE(bufoff, gbase, voff) do { _Pragma("unroll") for (int _i = 0; _i < 2; ++_i) \
;         __builtin_amdgcn_global_load_lds((const unsigned*)((const char*)(gbase) + (voff)[_i]), (PG8_LAS unsigned*)(lds + (bufoff) + ldsw + _i * 8192), 16, 0, 0); } while (0)
; #define PG8_LDA(dst, b, h) do { _Pragma("unroll") for (int m = 0; m < 4; ++m) _Pragma("unroll") for (int k = 0; k < 2; ++k) dst[m][k] = *(const PG8_LAS bf16x8*)(lds + PG8_SA(b, h) + aoff + m * 2048 + k * 1024); } while (0)
; #define PG8_LDB(dst, b, h) do { _Pragma("unroll") for (int n = 0; n < 2; ++n) _Pragma("unroll") for (int k = 0; k < 2; ++k) dst[n][k] = *(const PG8_LAS bf16x8*)(lds + PG8_SB(b, h) + boff + n * 2048 + k * 1024); } while (0)
; #define PG8_WAIT_V(n) asm volatile("s_waitcnt vmcnt(" #n ")" ::: "memory")
; #define PG8_WAIT_L(n) asm volatile("s_waitcnt lgkmcnt(" #n ")" ::: "memory")
; template <class Epi, class Sched, bool ALIGN_EPI = false, bool SP2 = false>
; __device__ __forceinline__ void gemm_phase(PG8_LAS unsigned char* lds, const Gemm g, const Sched& S, const Epi& E) {
;     ...
;             PG8_LDB(B0, 0, 0); PG8_LDB(B1, 0, 1); PG8_SCHED; PG8_LDA(At, 0, 0); PG8_STAGE(PG8_SA(1, 1), a1 + hA, voffA);
;             PG8_WAIT_V(8); PG8_WAIT_L(0); PG8_BAR; PG8_MMA(0, 0, At, B0); PG8_MMA(0, 1, At, B1); PG8_BAR; PG8_SCHED;
;             PG8_LDA(At, 0, 1); PG8_STAGE(PG8_SB(0, 0), b2, voffB); PG8_STAGE(PG8_SB(0, 1), b2 + hB, voffB); PG8_STAGE(PG8_SA(0, 0), a2, voffA);
;             PG8_WAIT_V(8); PG8_WAIT_L(0); PG8_BAR; PG8_MMA(1, 0, At, B0); PG8_MMA(1, 1, At, B1); PG8_BAR; PG8_SCHED;
;             PG8_LDB(B0, 1, 0); PG8_LDB(B1, 1, 1); PG8_SCHED; PG8_LDA(At, 1, 0); PG8_STAGE(PG8_SA(0, 1), a2 + hA, voffA);
;             PG8_WAIT_V(8); PG8_WAIT_L(0); PG8_BAR; PG8_MMA(0, 0, At, B0); PG8_MMA(0, 1, At, B1); PG8_BAR; PG8_SCHED;
;             PG8_LDA(At, 1, 1); PG8_STAGE(PG8_SB(1, 0), b3, voffB); PG8_STAGE(PG8_SB(1, 1), b3 + hB, voffB); PG8_STAGE(PG8_SA(1, 0), a3, voffA);
;             PG8_WAIT_V(8); PG8_WAIT_L(0); PG8_BAR; PG8_MMA(1, 0, At, B0); PG8_MMA(1, 1, At, B1); PG8_BAR; PG8_SCHED;
;     ...
;         if constexpr (ALIGN_EPI) { if (wr == 0) PG8_BAR; }
;     __device__ __forceinline__ void operator()(AccRef acc, const pg8::Unit& u, int wr, int wc, int fr, int fq) const {
;         const int pn = u.pn, row0 = u.pm * 256 + wr * 64 + fr, cl = wc * 32 + 8 * fq;
;         if (pn < 16) {
	v_mfma_f32_16x16x32_bf16 v[126:129], v[130:133], v[162:165], v[126:129]
	v_mfma_f32_16x16x32_bf16 v[122:125], v[138:141], v[162:165], v[122:125]
	v_mfma_f32_16x16x32_bf16 v[110:113], v[130:133], v[170:173], v[110:113]
	v_mfma_f32_16x16x32_bf16 v[106:109], v[138:141], v[170:173], v[106:109]
	v_mfma_f32_16x16x32_bf16 v[94:97], v[130:133], v[178:181], v[94:97]
	v_mfma_f32_16x16x32_bf16 v[90:93], v[138:141], v[178:181], v[90:93]
	v_mfma_f32_16x16x32_bf16 v[78:81], v[130:133], v[186:189], v[78:81]
	v_mfma_f32_16x16x32_bf16 v[74:77], v[138:141], v[186:189], v[74:77]
	v_mfma_f32_16x16x32_bf16 v[126:129], v[134:137], v[166:169], v[126:129]
	v_mfma_f32_16x16x32_bf16 v[122:125], v[142:145], v[166:169], v[122:125]
	v_mfma_f32_16x16x32_bf16 v[110:113], v[134:137], v[174:177], v[110:113]
	v_mfma_f32_16x16x32_bf16 v[106:109], v[142:145], v[174:177], v[106:109]
	v_mfma_f32_16x16x32_bf16 v[94:97], v[134:137], v[182:185], v[94:97]
	v_mfma_f32_16x16x32_bf16 v[90:93], v[142:145], v[182:185], v[90:93]
	v_mfma_f32_16x16x32_bf16 v[78:81], v[134:137], v[190:193], v[78:81]
	v_mfma_f32_16x16x32_bf16 v[74:77], v[142:145], v[190:193], v[74:77]
	v_mfma_f32_16x16x32_bf16 v[118:121], v[146:149], v[162:165], v[118:121]
	v_mfma_f32_16x16x32_bf16 v[114:117], v[154:157], v[162:165], v[114:117]
	v_mfma_f32_16x16x32_bf16 v[102:105], v[146:149], v[170:173], v[102:105]
	v_mfma_f32_16x16x32_bf16 v[98:101], v[154:157], v[170:173], v[98:101]
	v_mfma_f32_16x16x32_bf16 v[86:89], v[146:149], v[178:181], v[86:89]
	v_mfma_f32_16x16x32_bf16 v[82:85], v[154:157], v[178:181], v[82:85]
	v_mfma_f32_16x16x32_bf16 v[70:73], v[146:149], v[186:189], v[70:73]
	v_mfma_f32_16x16x32_bf16 v[66:69], v[154:157], v[186:189], v[66:69]
	v_mfma_f32_16x16x32_bf16 v[118:121], v[150:153], v[166:169], v[118:121]
	v_mfma_f32_16x16x32_bf16 v[114:117], v[158:161], v[166:169], v[114:117]
	v_mfma_f32_16x16x32_bf16 v[102:105], v[150:153], v[174:177], v[102:105]
	v_mfma_f32_16x16x32_bf16 v[98:101], v[158:161], v[174:177], v[98:101]
	v_mfma_f32_16x16x32_bf16 v[86:89], v[150:153], v[182:185], v[86:89]
	v_mfma_f32_16x16x32_bf16 v[82:85], v[158:161], v[182:185], v[82:85]
	v_mfma_f32_16x16x32_bf16 v[70:73], v[150:153], v[190:193], v[70:73]
	v_mfma_f32_16x16x32_bf16 v[66:69], v[158:161], v[190:193], v[66:69]
	s_barrier
	s_add_i32 s66, s86, s73
	s_mov_b32 m0, s66
	ds_read_b128 v[162:165], v231 offset:49152
	ds_read_b128 v[166:169], v231 offset:50176
	ds_read_b128 v[170:173], v231 offset:51200
	ds_read_b128 v[174:177], v231 offset:52224
	ds_read_b128 v[178:181], v231 offset:53248
	ds_read_b128 v[182:185], v231 offset:54272
	ds_read_b128 v[186:189], v231 offset:55296
	ds_read_b128 v[190:193], v231 offset:56320
	global_load_lds_dwordx4 v196, s[34:35]
	s_add_i32 m0, s66, 0x2000
	s_add_u32 s64, s64, 0x80080
	s_addc_u32 s65, s65, 0
	s_add_i32 s66, vcc_lo, s73
	global_load_lds_dwordx4 v200, s[34:35]
	s_mov_b32 m0, s66
	s_nop 0
	global_load_lds_dwordx4 v196, s[64:65]
	s_add_i32 m0, s66, 0x2000
	s_nop 0
	global_load_lds_dwordx4 v200, s[64:65]
	s_mov_b32 m0, s81
	s_nop 0
	global_load_lds_dwordx4 v194, s[98:99]
	s_mov_b32 m0, s82
	s_nop 0
	global_load_lds_dwordx4 v198, s[98:99]
	s_waitcnt vmcnt(8)
	s_waitcnt lgkmcnt(0)
	s_barrier
	v_mfma_f32_16x16x32_bf16 v[62:65], v[130:133], v[162:165], v[62:65]
	v_mfma_f32_16x16x32_bf16 v[58:61], v[138:141], v[162:165], v[58:61]
	v_mfma_f32_16x16x32_bf16 v[46:49], v[130:133], v[170:173], v[46:49]
	v_mfma_f32_16x16x32_bf16 v[42:45], v[138:141], v[170:173], v[42:45]
	v_mfma_f32_16x16x32_bf16 v[30:33], v[130:133], v[178:181], v[30:33]
	v_mfma_f32_16x16x32_bf16 v[26:29], v[138:141], v[178:181], v[26:29]
	v_mfma_f32_16x16x32_bf16 v[14:17], v[130:133], v[186:189], v[14:17]
	v_mfma_f32_16x16x32_bf16 v[10:13], v[138:141], v[186:189], v[10:13]
	v_mfma_f32_16x16x32_bf16 v[62:65], v[134:137], v[166:169], v[62:65]
	v_mfma_f32_16x16x32_bf16 v[58:61], v[142:145], v[166:169], v[58:61]
	v_mfma_f32_16x16x32_bf16 v[46:49], v[134:137], v[174:177], v[46:49]
	v_mfma_f32_16x16x32_bf16 v[42:45], v[142:145], v[174:177], v[42:45]
	v_mfma_f32_16x16x32_bf16 v[30:33], v[134:137], v[182:185], v[30:33]
	v_mfma_f32_16x16x32_bf16 v[26:29], v[142:145], v[182:185], v[26:29]
	v_mfma_f32_16x16x32_bf16 v[14:17], v[134:137], v[190:193], v[14:17]
	v_mfma_f32_16x16x32_bf16 v[10:13], v[142:145], v[190:193], v[10:13]
	v_mfma_f32_16x16x32_bf16 v[54:57], v[146:149], v[162:165], v[54:57]
	v_mfma_f32_16x16x32_bf16 v[50:53], v[154:157], v[162:165], v[50:53]
	v_mfma_f32_16x16x32_bf16 v[38:41], v[146:149], v[170:173], v[38:41]
	v_mfma_f32_16x16x32_bf16 v[34:37], v[154:157], v[170:173], v[34:37]
	v_mfma_f32_16x16x32_bf16 v[22:25], v[146:149], v[178:181], v[22:25]
	v_mfma_f32_16x16x32_bf16 v[18:21], v[154:157], v[178:181], v[18:21]
	v_mfma_f32_16x16x32_bf16 v[6:9], v[146:149], v[186:189], v[6:9]
	v_mfma_f32_16x16x32_bf16 v[2:5], v[154:157], v[186:189], v[2:5]
	v_mfma_f32_16x16x32_bf16 v[54:57], v[150:153], v[166:169], v[54:57]
	v_mfma_f32_16x16x32_bf16 v[50:53], v[158:161], v[166:169], v[50:53]
	v_mfma_f32_16x16x32_bf16 v[38:41], v[150:153], v[174:177], v[38:41]
	v_mfma_f32_16x16x32_bf16 v[34:37], v[158:161], v[174:177], v[34:37]
	v_mfma_f32_16x16x32_bf16 v[22:25], v[150:153], v[182:185], v[22:25]
	v_mfma_f32_16x16x32_bf16 v[18:21], v[158:161], v[182:185], v[18:21]
	v_mfma_f32_16x16x32_bf16 v[6:9], v[150:153], v[190:193], v[6:9]
	v_mfma_f32_16x16x32_bf16 v[2:5], v[158:161], v[190:193], v[2:5]
	s_barrier
	s_add_i32 s97, s97, 2
	s_add_u32 s62, s62, 0x100
	s_addc_u32 s63, s63, 0
	s_add_u32 s61, s61, 0x100
	s_addc_u32 s96, s96, 0
	s_cmp_gt_u32 s97, 29
	s_cbranch_scc0 .LBB0_190
	s_and_b64 vcc, exec, s[40:41]
	s_cbranch_vccz .LBB0_211
	s_barrier
	v_lshl_add_u32 v220, s60, 8, v1
	s_cmp_gt_i32 s10, 15
	s_mov_b64 s[60:61], -1
	s_cbranch_scc1 .LBB0_212

; #define PG8_STAGE(bufoff, gbase, voff) do { _Pragma("unroll") for (int _i = 0; _i < 2; ++_i) \
;         __builtin_amdgcn_global_load_lds((const unsigned*)((const char*)(gbase) + (voff)[_i]), (PG8_LAS unsigned*)(lds + (bufoff) + ldsw + _i * 8192), 16, 0, 0); } while (0)
; #define PG8_LDA(dst, b, h) do { _Pragma("unroll") for (int m = 0; m < 4; ++m) _Pragma("unroll") for (int k = 0; k < 2; ++k) dst[m][k] = *(const PG8_LAS bf16x8*)(lds + PG8_SA(b, h) + aoff + m * 2048 + k * 1024); } while (0)
; #define PG8_LDB(dst, b, h) do { _Pragma("unroll") for (int n = 0; n < 2; ++n) _Pragma("unroll") for (int k = 0; k < 2; ++k) dst[n][k] = *(const PG8_LAS bf16x8*)(lds + PG8_SB(b, h) + boff + n * 2048 + k * 1024); } while (0)
; #define PG8_WAIT_V(n) asm volatile("s_waitcnt vmcnt(" #n ")" ::: "memory")
; #define PG8_WAIT_L(n) asm volatile("s_waitcnt lgkmcnt(" #n ")" ::: "memory")
; #define PG8_BAR __builtin_amdgcn_s_barrier()
; #define PG8_SCHED __builtin_amdgcn_sched_barrier(0)
; template <class Epi, class Sched, bool ALIGN_EPI = false, bool SP2 = false>
; __device__ __forceinline__ void gemm_phase(PG8_LAS unsigned char* lds, const Gemm g, const Sched& S, const Epi& E) {
;     ...
;     for (;;) {
;         const bool has_next = S.next(ui + 1, nxt);
;         const char* nA = has_next ? (const char*)g.A + (size_t)nxt.pm * tA + (size_t)nxt.pn * pnA : cA; const char* nB = has_next ? (const char*)g.Bt + (size_t)nxt.pn * tB : cB;
; #pragma nounroll
;         for (int t = 0; t < nt; t += 2) {
;             const bool last = (t == nt - 2);
;             const char* a1 = cA + (size_t)(t + 1) * kstep;
;             const char* a2 = last ? nA : cA + (size_t)(t + 2) * kstep; const char* b2 = last ? nB : cB + (size_t)(t + 2) * kstep;
;             const char* a3 = a2 + kstep; const char* b3 = b2 + kstep;
;             if (last && has_next) S.a_ready(nxt);
;             if constexpr (SP2) {
;             PG8_LDB(B0, 0, 0); PG8_LDB(B1, 0, 1); PG8_SCHED; PG8_LDA(At, 0, 0); PG8_STAGE(PG8_SA(1, 1), a1 + hA, voffA);
;             PG8_WAIT_V(8); PG8_WAIT_L(0); PG8_BAR; PG8_MMA(0, 0, At, B0); PG8_MMA(0, 1, At, B1); PG8_BAR; PG8_SCHED;
;             PG8_LDA(At, 0, 1); PG8_STAGE(PG8_SB(0, 0), b2, voffB); PG8_STAGE(PG8_SB(0, 1), b2 + hB, voffB); PG8_STAGE(PG8_SA(0, 0), a2, voffA);
;             PG8_WAIT_V(8); PG8_WAIT_L(0); PG8_BAR; PG8_MMA(1, 0, At, B0); PG8_MMA(1, 1, At, B1); PG8_BAR; PG8_SCHED;
.LBB0_867:
	s_ashr_i32 s23, s22, 31
	s_lshl_b64 s[24:25], s[22:23], 19
	s_add_u32 s24, s33, s24
	s_addc_u32 s25, s48, s25
	s_and_b64 s[38:39], s[4:5], exec
	s_cselect_b32 s23, s25, s43
	s_cselect_b32 s67, s24, s42
	s_ashr_i32 s21, s20, 31
	s_lshl_b64 s[38:39], s[20:21], 19
	s_add_u32 s38, s49, s38
	s_addc_u32 s39, s51, s39
	s_and_b64 s[46:47], s[4:5], exec
	s_cselect_b32 s21, s39, s45
	s_cselect_b32 s69, s38, s44
	s_add_u32 s42, s42, 0x40080
	s_addc_u32 s43, s43, 0
	s_add_u32 s70, s44, 0x100
	v_mov_b32_e32 v2, 0
	s_addc_u32 s71, s45, 0
	s_mov_b32 s72, -2
	v_mov_b32_e32 v3, v2
	ds_read_b128 v[146:149], v156
	ds_read_b128 v[150:153], v156 offset:1024
	ds_read_b128 v[160:163], v156 offset:2048
	ds_read_b128 v[164:167], v156 offset:3072
	ds_read_b128 v[168:171], v157
	ds_read_b128 v[172:175], v157 offset:1024
	ds_read_b128 v[176:179], v157 offset:2048
	ds_read_b128 v[180:183], v157 offset:3072
	s_add_u32 s18, s42, 0xfffc0080
	s_addc_u32 s19, s43, -1
	s_cmp_eq_u32 s72, 12
	s_cselect_b32 s47, s23, s19
	s_cselect_b32 s46, s67, s18
	s_cselect_b32 s45, s21, s71
	s_cselect_b32 s44, s69, s70
	s_add_i32 m0, s41, 0xc000
	ds_read_b128 v[184:187], v158
	ds_read_b128 v[188:191], v158 offset:1024
	ds_read_b128 v[192:195], v158 offset:2048
	ds_read_b128 v[196:199], v158 offset:3072
	ds_read_b128 v[200:203], v158 offset:4096
	ds_read_b128 v[204:207], v158 offset:5120
	ds_read_b128 v[208:211], v158 offset:6144
	ds_read_b128 v[212:215], v158 offset:7168
	global_load_lds_dwordx4 v138, s[42:43]
	s_add_i32 m0, s41, 0xe000
	s_nop 0
	global_load_lds_dwordx4 v140, s[42:43]
	s_waitcnt vmcnt(8)
	s_waitcnt lgkmcnt(0)
	s_barrier
	v_mfma_f32_16x16x32_bf16 v[126:129], v[146:149], v[184:187], 0
	v_mfma_f32_16x16x32_bf16 v[122:125], v[160:163], v[184:187], 0
	v_mfma_f32_16x16x32_bf16 v[114:117], v[146:149], v[192:195], 0
	v_mfma_f32_16x16x32_bf16 v[106:109], v[160:163], v[192:195], 0
	v_mfma_f32_16x16x32_bf16 v[98:101], v[146:149], v[200:203], 0
	v_mfma_f32_16x16x32_bf16 v[90:93], v[160:163], v[200:203], 0
	v_mfma_f32_16x16x32_bf16 v[82:85], v[146:149], v[208:211], 0
	v_mfma_f32_16x16x32_bf16 v[74:77], v[160:163], v[208:211], 0
	v_mfma_f32_16x16x32_bf16 v[126:129], v[150:153], v[188:191], v[126:129]
	v_mfma_f32_16x16x32_bf16 v[122:125], v[164:167], v[188:191], v[122:125]
	v_mfma_f32_16x16x32_bf16 v[114:117], v[150:153], v[196:199], v[114:117]
	v_mfma_f32_16x16x32_bf16 v[106:109], v[164:167], v[196:199], v[106:109]
	v_mfma_f32_16x16x32_bf16 v[98:101], v[150:153], v[204:207], v[98:101]
	v_mfma_f32_16x16x32_bf16 v[90:93], v[164:167], v[204:207], v[90:93]
	v_mfma_f32_16x16x32_bf16 v[82:85], v[150:153], v[212:215], v[82:85]
	v_mfma_f32_16x16x32_bf16 v[74:77], v[164:167], v[212:215], v[74:77]
	v_mfma_f32_16x16x32_bf16 v[118:121], v[168:171], v[184:187], 0
	v_mfma_f32_16x16x32_bf16 v[110:113], v[176:179], v[184:187], 0
	v_mfma_f32_16x16x32_bf16 v[102:105], v[168:171], v[192:195], 0
	v_mfma_f32_16x16x32_bf16 v[94:97], v[176:179], v[192:195], 0
	v_mfma_f32_16x16x32_bf16 v[86:89], v[168:171], v[200:203], 0
	v_mfma_f32_16x16x32_bf16 v[78:81], v[176:179], v[200:203], 0
	v_mfma_f32_16x16x32_bf16 v[70:73], v[168:171], v[208:211], 0
	v_mfma_f32_16x16x32_bf16 v[66:69], v[176:179], v[208:211], 0
	v_mfma_f32_16x16x32_bf16 v[118:121], v[172:175], v[188:191], v[118:121]
	v_mfma_f32_16x16x32_bf16 v[110:113], v[180:183], v[188:191], v[110:113]
	v_mfma_f32_16x16x32_bf16 v[102:105], v[172:175], v[196:199], v[102:105]
	v_mfma_f32_16x16x32_bf16 v[94:97], v[180:183], v[196:199], v[94:97]
	v_mfma_f32_16x16x32_bf16 v[86:89], v[172:175], v[204:207], v[86:89]
	v_mfma_f32_16x16x32_bf16 v[78:81], v[180:183], v[204:207], v[78:81]
	v_mfma_f32_16x16x32_bf16 v[70:73], v[172:175], v[212:215], v[70:73]
	v_mfma_f32_16x16x32_bf16 v[66:69], v[180:183], v[212:215], v[66:69]
	s_barrier
	s_add_i32 s18, s64, s52
	s_add_u32 s78, s44, s8
	s_addc_u32 s79, s45, s9
	s_mov_b32 m0, s18
	ds_read_b128 v[184:187], v158 offset:16384
	ds_read_b128 v[188:191], v158 offset:17408
	ds_read_b128 v[192:195], v158 offset:18432
	ds_read_b128 v[196:199], v158 offset:19456
	ds_read_b128 v[200:203], v158 offset:20480
	ds_read_b128 v[204:207], v158 offset:21504
	ds_read_b128 v[208:211], v158 offset:22528
	ds_read_b128 v[212:215], v158 offset:23552
	global_load_lds_dwordx4 v134, s[44:45]
	s_add_i32 m0, s18, 0x2000
	s_add_u32 s74, s44, 0x40000
	s_addc_u32 s75, s45, 0
	s_add_i32 s18, s65, s52
	global_load_lds_dwordx4 v130, s[44:45]
	s_mov_b32 m0, s18
	s_nop 0
	global_load_lds_dwordx4 v134, s[74:75]
	s_add_i32 m0, s18, 0x2000
	s_nop 0
	global_load_lds_dwordx4 v130, s[74:75]
	s_add_u32 s80, s46, s8
	s_addc_u32 s81, s47, s9
	s_mov_b32 m0, s41
	s_nop 0
	global_load_lds_dwordx4 v136, s[46:47]
	s_mov_b32 m0, s53
	s_nop 0
	global_load_lds_dwordx4 v132, s[46:47]
	s_waitcnt vmcnt(8)
	s_waitcnt lgkmcnt(0)
	s_barrier
; #define PG8_STAGE(bufoff, gbase, voff) do { _Pragma("unroll") for (int _i = 0; _i < 2; ++_i) \
;         __builtin_amdgcn_global_load_lds((const unsigned*)((const char*)(gbase) + (voff)[_i]), (PG8_LAS unsigned*)(lds + (bufoff) + ldsw + _i * 8192), 16, 0, 0); } while (0)
; #define PG8_LDA(dst, b, h) do { _Pragma("unroll") for (int m = 0; m < 4; ++m) _Pragma("unroll") for (int k = 0; k < 2; ++k) dst[m][k] = *(const PG8_LAS bf16x8*)(lds + PG8_SA(b, h) + aoff + m * 2048 + k * 1024); } while (0)
; #define PG8_LDB(dst, b, h) do { _Pragma("unroll") for (int n = 0; n < 2; ++n) _Pragma("unroll") for (int k = 0; k < 2; ++k) dst[n][k] = *(const PG8_LAS bf16x8*)(lds + PG8_SB(b, h) + boff + n * 2048 + k * 1024); } while (0)
; #define PG8_MMA(ai, bj, At, Bt) do { __builtin_amdgcn_s_setprio(1); _Pragma("unroll") for (int m = 0; m < 4; ++m) _Pragma("unroll") for (int n = 0; n < 2; ++n) _Pragma("unroll") for (int k = 0; k < 2; ++k) \
;         acc[ai][bj][m][n] = __builtin_amdgcn_mfma_f32_16x16x32_bf16(Bt[n][k], At[m][k], acc[ai][bj][m][n], 0, 0, 0); __builtin_amdgcn_s_setprio(0); } while (0)
; #define PG8_WAIT_V(n) asm volatile("s_waitcnt vmcnt(" #n ")" ::: "memory")
; #define PG8_WAIT_L(n) asm volatile("s_waitcnt lgkmcnt(" #n ")" ::: "memory")
; #define PG8_BAR __builtin_amdgcn_s_barrier()
; template <class Epi, class Sched, bool ALIGN_EPI = false, bool SP2 = false>
; __device__ __forceinline__ void gemm_phase(PG8_LAS unsigned char* lds, const Gemm g, const Sched& S, const Epi& E) {
;     ...
;             PG8_LDB(B0, 0, 0); PG8_LDB(B1, 0, 1); PG8_SCHED; PG8_LDA(At, 0, 0); PG8_STAGE(PG8_SA(1, 1), a1 + hA, voffA);
;             PG8_WAIT_V(8); PG8_WAIT_L(0); PG8_BAR; PG8_MMA(0, 0, At, B0); PG8_MMA(0, 1, At, B1); PG8_BAR; PG8_SCHED;
;             PG8_LDA(At, 0, 1); PG8_STAGE(PG8_SB(0, 0), b2, voffB); PG8_STAGE(PG8_SB(0, 1), b2 + hB, voffB); PG8_STAGE(PG8_SA(0, 0), a2, voffA);
;             PG8_WAIT_V(8); PG8_WAIT_L(0); PG8_BAR; PG8_MMA(1, 0, At, B0); PG8_MMA(1, 1, At, B1); PG8_BAR; PG8_SCHED;
;             PG8_LDB(B0, 1, 0); PG8_LDB(B1, 1, 1); PG8_SCHED; PG8_LDA(At, 1, 0); PG8_STAGE(PG8_SA(0, 1), a2 + hA, voffA);
;             PG8_WAIT_V(8); PG8_WAIT_L(0); PG8_BAR; PG8_MMA(0, 0, At, B0); PG8_MMA(0, 1, At, B1); PG8_BAR; PG8_SCHED;
;             PG8_LDA(At, 1, 1); PG8_STAGE(PG8_SB(1, 0), b3, voffB); PG8_STAGE(PG8_SB(1, 1), b3 + hB, voffB); PG8_STAGE(PG8_SA(1, 0), a3, voffA);
	v_mfma_f32_16x16x32_bf16 v[62:65], v[146:149], v[184:187], 0
	v_mfma_f32_16x16x32_bf16 v[58:61], v[160:163], v[184:187], 0
	v_mfma_f32_16x16x32_bf16 v[50:53], v[146:149], v[192:195], 0
	v_mfma_f32_16x16x32_bf16 v[42:45], v[160:163], v[192:195], 0
	v_mfma_f32_16x16x32_bf16 v[34:37], v[146:149], v[200:203], 0
	v_mfma_f32_16x16x32_bf16 v[26:29], v[160:163], v[200:203], 0
	v_mfma_f32_16x16x32_bf16 v[18:21], v[146:149], v[208:211], 0
	v_mfma_f32_16x16x32_bf16 v[10:13], v[160:163], v[208:211], 0
	v_mfma_f32_16x16x32_bf16 v[62:65], v[150:153], v[188:191], v[62:65]
	v_mfma_f32_16x16x32_bf16 v[58:61], v[164:167], v[188:191], v[58:61]
	v_mfma_f32_16x16x32_bf16 v[50:53], v[150:153], v[196:199], v[50:53]
	v_mfma_f32_16x16x32_bf16 v[42:45], v[164:167], v[196:199], v[42:45]
	v_mfma_f32_16x16x32_bf16 v[34:37], v[150:153], v[204:207], v[34:37]
	v_mfma_f32_16x16x32_bf16 v[26:29], v[164:167], v[204:207], v[26:29]
	v_mfma_f32_16x16x32_bf16 v[18:21], v[150:153], v[212:215], v[18:21]
	v_mfma_f32_16x16x32_bf16 v[10:13], v[164:167], v[212:215], v[10:13]
	v_mfma_f32_16x16x32_bf16 v[54:57], v[168:171], v[184:187], 0
	v_mfma_f32_16x16x32_bf16 v[46:49], v[176:179], v[184:187], 0
	v_mfma_f32_16x16x32_bf16 v[38:41], v[168:171], v[192:195], 0
	v_mfma_f32_16x16x32_bf16 v[30:33], v[176:179], v[192:195], 0
	v_mfma_f32_16x16x32_bf16 v[22:25], v[168:171], v[200:203], 0
	v_mfma_f32_16x16x32_bf16 v[14:17], v[176:179], v[200:203], 0
	v_mfma_f32_16x16x32_bf16 v[6:9], v[168:171], v[208:211], 0
	v_mfma_f32_16x16x32_bf16 v[2:5], v[176:179], v[208:211], 0
	v_mfma_f32_16x16x32_bf16 v[54:57], v[172:175], v[188:191], v[54:57]
	v_mfma_f32_16x16x32_bf16 v[46:49], v[180:183], v[188:191], v[46:49]
	v_mfma_f32_16x16x32_bf16 v[38:41], v[172:175], v[196:199], v[38:41]
	v_mfma_f32_16x16x32_bf16 v[30:33], v[180:183], v[196:199], v[30:33]
	v_mfma_f32_16x16x32_bf16 v[22:25], v[172:175], v[204:207], v[22:25]
	v_mfma_f32_16x16x32_bf16 v[14:17], v[180:183], v[204:207], v[14:17]
	v_mfma_f32_16x16x32_bf16 v[6:9], v[172:175], v[212:215], v[6:9]
	v_mfma_f32_16x16x32_bf16 v[2:5], v[180:183], v[212:215], v[2:5]
	s_barrier
	s_add_i32 s18, 0, 0x18000
	v_add_u32_e32 v159, s18, v154
	s_add_i32 s19, 0, 0x1c000
	ds_read_b128 v[146:149], v159
	ds_read_b128 v[150:153], v159 offset:1024
	ds_read_b128 v[160:163], v159 offset:2048
	ds_read_b128 v[164:167], v159 offset:3072
	v_add_u32_e32 v159, s19, v154
	ds_read_b128 v[168:171], v159
	ds_read_b128 v[172:175], v159 offset:1024
	ds_read_b128 v[176:179], v159 offset:2048
	ds_read_b128 v[180:183], v159 offset:3072
	s_add_u32 s46, s46, 0x40000
	s_addc_u32 s47, s47, 0
	s_mov_b32 m0, s58
	ds_read_b128 v[184:187], v158 offset:32768
	ds_read_b128 v[188:191], v158 offset:33792
	ds_read_b128 v[192:195], v158 offset:34816
	ds_read_b128 v[196:199], v158 offset:35840
	ds_read_b128 v[200:203], v158 offset:36864
	ds_read_b128 v[204:207], v158 offset:37888
	ds_read_b128 v[208:211], v158 offset:38912
	ds_read_b128 v[212:215], v158 offset:39936
	global_load_lds_dwordx4 v136, s[46:47]
	s_mov_b32 m0, s59
	s_nop 0
	global_load_lds_dwordx4 v132, s[46:47]
	s_waitcnt vmcnt(8)
	s_waitcnt lgkmcnt(0)
	s_barrier
	v_mfma_f32_16x16x32_bf16 v[126:129], v[146:149], v[184:187], v[126:129]
	v_mfma_f32_16x16x32_bf16 v[122:125], v[160:163], v[184:187], v[122:125]
	v_mfma_f32_16x16x32_bf16 v[114:117], v[146:149], v[192:195], v[114:117]
	v_mfma_f32_16x16x32_bf16 v[106:109], v[160:163], v[192:195], v[106:109]
	v_mfma_f32_16x16x32_bf16 v[98:101], v[146:149], v[200:203], v[98:101]
	v_mfma_f32_16x16x32_bf16 v[90:93], v[160:163], v[200:203], v[90:93]
	v_mfma_f32_16x16x32_bf16 v[82:85], v[146:149], v[208:211], v[82:85]
	v_mfma_f32_16x16x32_bf16 v[74:77], v[160:163], v[208:211], v[74:77]
	v_mfma_f32_16x16x32_bf16 v[126:129], v[150:153], v[188:191], v[126:129]
	v_mfma_f32_16x16x32_bf16 v[122:125], v[164:167], v[188:191], v[122:125]
	v_mfma_f32_16x16x32_bf16 v[114:117], v[150:153], v[196:199], v[114:117]
	v_mfma_f32_16x16x32_bf16 v[106:109], v[164:167], v[196:199], v[106:109]
	v_mfma_f32_16x16x32_bf16 v[98:101], v[150:153], v[204:207], v[98:101]
	v_mfma_f32_16x16x32_bf16 v[90:93], v[164:167], v[204:207], v[90:93]
	v_mfma_f32_16x16x32_bf16 v[82:85], v[150:153], v[212:215], v[82:85]
	v_mfma_f32_16x16x32_bf16 v[74:77], v[164:167], v[212:215], v[74:77]
	v_mfma_f32_16x16x32_bf16 v[118:121], v[168:171], v[184:187], v[118:121]
	v_mfma_f32_16x16x32_bf16 v[110:113], v[176:179], v[184:187], v[110:113]
	v_mfma_f32_16x16x32_bf16 v[102:105], v[168:171], v[192:195], v[102:105]
	v_mfma_f32_16x16x32_bf16 v[94:97], v[176:179], v[192:195], v[94:97]
	v_mfma_f32_16x16x32_bf16 v[86:89], v[168:171], v[200:203], v[86:89]
	v_mfma_f32_16x16x32_bf16 v[78:81], v[176:179], v[200:203], v[78:81]
	v_mfma_f32_16x16x32_bf16 v[70:73], v[168:171], v[208:211], v[70:73]
	v_mfma_f32_16x16x32_bf16 v[66:69], v[176:179], v[208:211], v[66:69]
	v_mfma_f32_16x16x32_bf16 v[118:121], v[172:175], v[188:191], v[118:121]
	v_mfma_f32_16x16x32_bf16 v[110:113], v[180:183], v[188:191], v[110:113]
	v_mfma_f32_16x16x32_bf16 v[102:105], v[172:175], v[196:199], v[102:105]
	v_mfma_f32_16x16x32_bf16 v[94:97], v[180:183], v[196:199], v[94:97]
	v_mfma_f32_16x16x32_bf16 v[86:89], v[172:175], v[204:207], v[86:89]
	v_mfma_f32_16x16x32_bf16 v[78:81], v[180:183], v[204:207], v[78:81]
	v_mfma_f32_16x16x32_bf16 v[70:73], v[172:175], v[212:215], v[70:73]
	v_mfma_f32_16x16x32_bf16 v[66:69], v[180:183], v[212:215], v[66:69]
	s_barrier
; #define PG8_STAGE(bufoff, gbase, voff) do { _Pragma("unroll") for (int _i = 0; _i < 2; ++_i) \
;         __builtin_amdgcn_global_load_lds((const unsigned*)((const char*)(gbase) + (voff)[_i]), (PG8_LAS unsigned*)(lds + (bufoff) + ldsw + _i * 8192), 16, 0, 0); } while (0)
; #define PG8_LDA(dst, b, h) do { _Pragma("unroll") for (int m = 0; m < 4; ++m) _Pragma("unroll") for (int k = 0; k < 2; ++k) dst[m][k] = *(const PG8_LAS bf16x8*)(lds + PG8_SA(b, h) + aoff + m * 2048 + k * 1024); } while (0)
; #define PG8_LDB(dst, b, h) do { _Pragma("unroll") for (int n = 0; n < 2; ++n) _Pragma("unroll") for (int k = 0; k < 2; ++k) dst[n][k] = *(const PG8_LAS bf16x8*)(lds + PG8_SB(b, h) + boff + n * 2048 + k * 1024); } while (0)
; template <class Epi, class Sched, bool ALIGN_EPI = false, bool SP2 = false>
; __device__ __forceinline__ void gemm_phase(PG8_LAS unsigned char* lds, const Gemm g, const Sched& S, const Epi& E) {
;     ...
;         for (int t = 0; t < nt; t += 2) {
;             const bool last = (t == nt - 2);
;             const char* a1 = cA + (size_t)(t + 1) * kstep;
;             const char* a2 = last ? nA : cA + (size_t)(t + 2) * kstep; const char* b2 = last ? nB : cB + (size_t)(t + 2) * kstep;
;             const char* a3 = a2 + kstep; const char* b3 = b2 + kstep;
;             if (last && has_next) S.a_ready(nxt);
;             if constexpr (SP2) {
;             PG8_LDB(B0, 0, 0); PG8_LDB(B1, 0, 1); PG8_SCHED; PG8_LDA(At, 0, 0); PG8_STAGE(PG8_SA(1, 1), a1 + hA, voffA);
;             PG8_WAIT_V(8); PG8_WAIT_L(0); PG8_BAR; PG8_MMA(0, 0, At, B0); PG8_MMA(0, 1, At, B1); PG8_BAR; PG8_SCHED;
;             PG8_LDA(At, 0, 1); PG8_STAGE(PG8_SB(0, 0), b2, voffB); PG8_STAGE(PG8_SB(0, 1), b2 + hB, voffB); PG8_STAGE(PG8_SA(0, 0), a2, voffA);
;             PG8_WAIT_V(8); PG8_WAIT_L(0); PG8_BAR; PG8_MMA(1, 0, At, B0); PG8_MMA(1, 1, At, B1); PG8_BAR; PG8_SCHED;
;             PG8_LDB(B0, 1, 0); PG8_LDB(B1, 1, 1); PG8_SCHED; PG8_LDA(At, 1, 0); PG8_STAGE(PG8_SA(0, 1), a2 + hA, voffA);
;             PG8_WAIT_V(8); PG8_WAIT_L(0); PG8_BAR; PG8_MMA(0, 0, At, B0); PG8_MMA(0, 1, At, B1); PG8_BAR; PG8_SCHED;
;             PG8_LDA(At, 1, 1); PG8_STAGE(PG8_SB(1, 0), b3, voffB); PG8_STAGE(PG8_SB(1, 1), b3 + hB, voffB); PG8_STAGE(PG8_SA(1, 0), a3, voffA);
;             PG8_WAIT_V(8); PG8_WAIT_L(0); PG8_BAR; PG8_MMA(1, 0, At, B0); PG8_MMA(1, 1, At, B1); PG8_BAR; PG8_SCHED;
	s_add_i32 s18, s18, s52
	s_mov_b32 m0, s18
	ds_read_b128 v[184:187], v158 offset:49152
	ds_read_b128 v[188:191], v158 offset:50176
	ds_read_b128 v[192:195], v158 offset:51200
	ds_read_b128 v[196:199], v158 offset:52224
	ds_read_b128 v[200:203], v158 offset:53248
	ds_read_b128 v[204:207], v158 offset:54272
	ds_read_b128 v[208:211], v158 offset:55296
	ds_read_b128 v[212:215], v158 offset:56320
	global_load_lds_dwordx4 v134, s[78:79]
	s_add_i32 m0, s18, 0x2000
	s_add_u32 s44, s44, 0x40080
	s_addc_u32 s45, s45, 0
	s_add_i32 s18, s19, s52
	global_load_lds_dwordx4 v130, s[78:79]
	s_mov_b32 m0, s18
	s_nop 0
	global_load_lds_dwordx4 v134, s[44:45]
	s_add_i32 m0, s18, 0x2000
	s_nop 0
	global_load_lds_dwordx4 v130, s[44:45]
	s_mov_b32 m0, s60
	s_nop 0
	global_load_lds_dwordx4 v136, s[80:81]
	s_mov_b32 m0, s61
	s_nop 0
	global_load_lds_dwordx4 v132, s[80:81]
	s_waitcnt vmcnt(8)
	s_waitcnt lgkmcnt(0)
	s_barrier
	v_mfma_f32_16x16x32_bf16 v[62:65], v[146:149], v[184:187], v[62:65]
	v_mfma_f32_16x16x32_bf16 v[58:61], v[160:163], v[184:187], v[58:61]
	v_mfma_f32_16x16x32_bf16 v[50:53], v[146:149], v[192:195], v[50:53]
	v_mfma_f32_16x16x32_bf16 v[42:45], v[160:163], v[192:195], v[42:45]
	v_mfma_f32_16x16x32_bf16 v[34:37], v[146:149], v[200:203], v[34:37]
	v_mfma_f32_16x16x32_bf16 v[26:29], v[160:163], v[200:203], v[26:29]
	v_mfma_f32_16x16x32_bf16 v[18:21], v[146:149], v[208:211], v[18:21]
	v_mfma_f32_16x16x32_bf16 v[10:13], v[160:163], v[208:211], v[10:13]
	v_mfma_f32_16x16x32_bf16 v[62:65], v[150:153], v[188:191], v[62:65]
	v_mfma_f32_16x16x32_bf16 v[58:61], v[164:167], v[188:191], v[58:61]
	v_mfma_f32_16x16x32_bf16 v[50:53], v[150:153], v[196:199], v[50:53]
	v_mfma_f32_16x16x32_bf16 v[42:45], v[164:167], v[196:199], v[42:45]
	v_mfma_f32_16x16x32_bf16 v[34:37], v[150:153], v[204:207], v[34:37]
	v_mfma_f32_16x16x32_bf16 v[26:29], v[164:167], v[204:207], v[26:29]
	v_mfma_f32_16x16x32_bf16 v[18:21], v[150:153], v[212:215], v[18:21]
	v_mfma_f32_16x16x32_bf16 v[10:13], v[164:167], v[212:215], v[10:13]
	v_mfma_f32_16x16x32_bf16 v[54:57], v[168:171], v[184:187], v[54:57]
	v_mfma_f32_16x16x32_bf16 v[46:49], v[176:179], v[184:187], v[46:49]
	v_mfma_f32_16x16x32_bf16 v[38:41], v[168:171], v[192:195], v[38:41]
	v_mfma_f32_16x16x32_bf16 v[30:33], v[176:179], v[192:195], v[30:33]
	v_mfma_f32_16x16x32_bf16 v[22:25], v[168:171], v[200:203], v[22:25]
	v_mfma_f32_16x16x32_bf16 v[14:17], v[176:179], v[200:203], v[14:17]
	v_mfma_f32_16x16x32_bf16 v[6:9], v[168:171], v[208:211], v[6:9]
	v_mfma_f32_16x16x32_bf16 v[2:5], v[176:179], v[208:211], v[2:5]
	v_mfma_f32_16x16x32_bf16 v[54:57], v[172:175], v[188:191], v[54:57]
	v_mfma_f32_16x16x32_bf16 v[46:49], v[180:183], v[188:191], v[46:49]
	v_mfma_f32_16x16x32_bf16 v[38:41], v[172:175], v[196:199], v[38:41]
	v_mfma_f32_16x16x32_bf16 v[30:33], v[180:183], v[196:199], v[30:33]
	v_mfma_f32_16x16x32_bf16 v[22:25], v[172:175], v[204:207], v[22:25]
	v_mfma_f32_16x16x32_bf16 v[14:17], v[180:183], v[204:207], v[14:17]
	v_mfma_f32_16x16x32_bf16 v[6:9], v[172:175], v[212:215], v[6:9]
	v_mfma_f32_16x16x32_bf16 v[2:5], v[180:183], v[212:215], v[2:5]
	s_barrier
	s_add_i32 s72, s72, 2
	s_add_u32 s42, s42, 0x100
	s_addc_u32 s43, s43, 0
	s_add_u32 s70, s70, 0x100
	s_addc_u32 s71, s71, 0
	s_cmp_gt_u32 s72, 13
.LBB0_868:
	ds_read_b128 v[146:149], v156
	ds_read_b128 v[150:153], v156 offset:1024
	ds_read_b128 v[160:163], v156 offset:2048
	ds_read_b128 v[164:167], v156 offset:3072
	ds_read_b128 v[168:171], v157
	ds_read_b128 v[172:175], v157 offset:1024
	ds_read_b128 v[176:179], v157 offset:2048
	ds_read_b128 v[180:183], v157 offset:3072
	s_add_u32 s18, s42, 0xfffc0080
	s_addc_u32 s19, s43, -1
	s_cmp_eq_u32 s72, 12
	s_cselect_b32 s47, s23, s19
	s_cselect_b32 s46, s67, s18
	s_cselect_b32 s45, s21, s71
	s_cselect_b32 s44, s69, s70
	s_add_i32 m0, s41, 0xc000
	ds_read_b128 v[184:187], v158
	ds_read_b128 v[188:191], v158 offset:1024
	ds_read_b128 v[192:195], v158 offset:2048
	ds_read_b128 v[196:199], v158 offset:3072
	ds_read_b128 v[200:203], v158 offset:4096
	ds_read_b128 v[204:207], v158 offset:5120
	ds_read_b128 v[208:211], v158 offset:6144
	ds_read_b128 v[212:215], v158 offset:7168
	global_load_lds_dwordx4 v138, s[42:43]
	s_add_i32 m0, s41, 0xe000
	s_nop 0
	global_load_lds_dwordx4 v140, s[42:43]
	s_waitcnt vmcnt(8)
	s_waitcnt lgkmcnt(0)
	s_barrier
	v_mfma_f32_16x16x32_bf16 v[126:129], v[146:149], v[184:187], v[126:129]
	v_mfma_f32_16x16x32_bf16 v[122:125], v[160:163], v[184:187], v[122:125]
	v_mfma_f32_16x16x32_bf16 v[114:117], v[146:149], v[192:195], v[114:117]
	v_mfma_f32_16x16x32_bf16 v[106:109], v[160:163], v[192:195], v[106:109]
	v_mfma_f32_16x16x32_bf16 v[98:101], v[146:149], v[200:203], v[98:101]
	v_mfma_f32_16x16x32_bf16 v[90:93], v[160:163], v[200:203], v[90:93]
	v_mfma_f32_16x16x32_bf16 v[82:85], v[146:149], v[208:211], v[82:85]
	v_mfma_f32_16x16x32_bf16 v[74:77], v[160:163], v[208:211], v[74:77]
	v_mfma_f32_16x16x32_bf16 v[126:129], v[150:153], v[188:191], v[126:129]
	v_mfma_f32_16x16x32_bf16 v[122:125], v[164:167], v[188:191], v[122:125]
	v_mfma_f32_16x16x32_bf16 v[114:117], v[150:153], v[196:199], v[114:117]
	v_mfma_f32_16x16x32_bf16 v[106:109], v[164:167], v[196:199], v[106:109]
	v_mfma_f32_16x16x32_bf16 v[98:101], v[150:153], v[204:207], v[98:101]
	v_mfma_f32_16x16x32_bf16 v[90:93], v[164:167], v[204:207], v[90:93]
	v_mfma_f32_16x16x32_bf16 v[82:85], v[150:153], v[212:215], v[82:85]
	v_mfma_f32_16x16x32_bf16 v[74:77], v[164:167], v[212:215], v[74:77]
	v_mfma_f32_16x16x32_bf16 v[118:121], v[168:171], v[184:187], v[118:121]
	v_mfma_f32_16x16x32_bf16 v[110:113], v[176:179], v[184:187], v[110:113]
	v_mfma_f32_16x16x32_bf16 v[102:105], v[168:171], v[192:195], v[102:105]
	v_mfma_f32_16x16x32_bf16 v[94:97], v[176:179], v[192:195], v[94:97]
	v_mfma_f32_16x16x32_bf16 v[86:89], v[168:171], v[200:203], v[86:89]
	v_mfma_f32_16x16x32_bf16 v[78:81], v[176:179], v[200:203], v[78:81]
	v_mfma_f32_16x16x32_bf16 v[70:73], v[168:171], v[208:211], v[70:73]
	v_mfma_f32_16x16x32_bf16 v[66:69], v[176:179], v[208:211], v[66:69]
	v_mfma_f32_16x16x32_bf16 v[118:121], v[172:175], v[188:191], v[118:121]
	v_mfma_f32_16x16x32_bf16 v[110:113], v[180:183], v[188:191], v[110:113]
	v_mfma_f32_16x16x32_bf16 v[102:105], v[172:175], v[196:199], v[102:105]
	v_mfma_f32_16x16x32_bf16 v[94:97], v[180:183], v[196:199], v[94:97]
	v_mfma_f32_16x16x32_bf16 v[86:89], v[172:175], v[204:207], v[86:89]
	v_mfma_f32_16x16x32_bf16 v[78:81], v[180:183], v[204:207], v[78:81]
	v_mfma_f32_16x16x32_bf16 v[70:73], v[172:175], v[212:215], v[70:73]
	v_mfma_f32_16x16x32_bf16 v[66:69], v[180:183], v[212:215], v[66:69]
	s_barrier
; #define PG8_STAGE(bufoff, gbase, voff) do { _Pragma("unroll") for (int _i = 0; _i < 2; ++_i) \
;         __builtin_amdgcn_global_load_lds((const unsigned*)((const char*)(gbase) + (voff)[_i]), (PG8_LAS unsigned*)(lds + (bufoff) + ldsw + _i * 8192), 16, 0, 0); } while (0)
; #define PG8_LDA(dst, b, h) do { _Pragma("unroll") for (int m = 0; m < 4; ++m) _Pragma("unroll") for (int k = 0; k < 2; ++k) dst[m][k] = *(const PG8_LAS bf16x8*)(lds + PG8_SA(b, h) + aoff + m * 2048 + k * 1024); } while (0)
; #define PG8_LDB(dst, b, h) do { _Pragma("unroll") for (int n = 0; n < 2; ++n) _Pragma("unroll") for (int k = 0; k < 2; ++k) dst[n][k] = *(const PG8_LAS bf16x8*)(lds + PG8_SB(b, h) + boff + n * 2048 + k * 1024); } while (0)
; #define PG8_MMA(ai, bj, At, Bt) do { __builtin_amdgcn_s_setprio(1); _Pragma("unroll") for (int m = 0; m < 4; ++m) _Pragma("unroll") for (int n = 0; n < 2; ++n) _Pragma("unroll") for (int k = 0; k < 2; ++k) \
;         acc[ai][bj][m][n] = __builtin_amdgcn_mfma_f32_16x16x32_bf16(Bt[n][k], At[m][k], acc[ai][bj][m][n], 0, 0, 0); __builtin_amdgcn_s_setprio(0); } while (0)
; #define PG8_WAIT_V(n) asm volatile("s_waitcnt vmcnt(" #n ")" ::: "memory")
; #define PG8_WAIT_L(n) asm volatile("s_waitcnt lgkmcnt(" #n ")" ::: "memory")
; #define PG8_BAR __builtin_amdgcn_s_barrier()
; template <class Epi, class Sched, bool ALIGN_EPI = false, bool SP2 = false>
; __device__ __forceinline__ void gemm_phase(PG8_LAS unsigned char* lds, const Gemm g, const Sched& S, const Epi& E) {
;     ...
;             PG8_LDB(B0, 0, 0); PG8_LDB(B1, 0, 1); PG8_SCHED; PG8_LDA(At, 0, 0); PG8_STAGE(PG8_SA(1, 1), a1 + hA, voffA);
;             PG8_WAIT_V(8); PG8_WAIT_L(0); PG8_BAR; PG8_MMA(0, 0, At, B0); PG8_MMA(0, 1, At, B1); PG8_BAR; PG8_SCHED;
;             PG8_LDA(At, 0, 1); PG8_STAGE(PG8_SB(0, 0), b2, voffB); PG8_STAGE(PG8_SB(0, 1), b2 + hB, voffB); PG8_STAGE(PG8_SA(0, 0), a2, voffA);
;             PG8_WAIT_V(8); PG8_WAIT_L(0); PG8_BAR; PG8_MMA(1, 0, At, B0); PG8_MMA(1, 1, At, B1); PG8_BAR; PG8_SCHED;
;             PG8_LDB(B0, 1, 0); PG8_LDB(B1, 1, 1); PG8_SCHED; PG8_LDA(At, 1, 0); PG8_STAGE(PG8_SA(0, 1), a2 + hA, voffA);
;             PG8_WAIT_V(8); PG8_WAIT_L(0); PG8_BAR; PG8_MMA(0, 0, At, B0); PG8_MMA(0, 1, At, B1); PG8_BAR; PG8_SCHED;
;             PG8_LDA(At, 1, 1); PG8_STAGE(PG8_SB(1, 0), b3, voffB); PG8_STAGE(PG8_SB(1, 1), b3 + hB, voffB); PG8_STAGE(PG8_SA(1, 0), a3, voffA);
	s_add_i32 s18, s64, s52
	s_add_u32 s78, s44, s8
	s_addc_u32 s79, s45, s9
	s_mov_b32 m0, s18
	ds_read_b128 v[184:187], v158 offset:16384
	ds_read_b128 v[188:191], v158 offset:17408
	ds_read_b128 v[192:195], v158 offset:18432
	ds_read_b128 v[196:199], v158 offset:19456
	ds_read_b128 v[200:203], v158 offset:20480
	ds_read_b128 v[204:207], v158 offset:21504
	ds_read_b128 v[208:211], v158 offset:22528
	ds_read_b128 v[212:215], v158 offset:23552
	global_load_lds_dwordx4 v134, s[44:45]
	s_add_i32 m0, s18, 0x2000
	s_add_u32 s74, s44, 0x40000
	s_addc_u32 s75, s45, 0
	s_add_i32 s18, s65, s52
	global_load_lds_dwordx4 v130, s[44:45]
	s_mov_b32 m0, s18
	s_nop 0
	global_load_lds_dwordx4 v134, s[74:75]
	s_add_i32 m0, s18, 0x2000
	s_nop 0
	global_load_lds_dwordx4 v130, s[74:75]
	s_add_u32 s80, s46, s8
	s_addc_u32 s81, s47, s9
	s_mov_b32 m0, s41
	s_nop 0
	global_load_lds_dwordx4 v136, s[46:47]
	s_mov_b32 m0, s53
	s_nop 0
	global_load_lds_dwordx4 v132, s[46:47]
	s_waitcnt vmcnt(8)
	s_waitcnt lgkmcnt(0)
	s_barrier
	v_mfma_f32_16x16x32_bf16 v[62:65], v[146:149], v[184:187], v[62:65]
	v_mfma_f32_16x16x32_bf16 v[58:61], v[160:163], v[184:187], v[58:61]
	v_mfma_f32_16x16x32_bf16 v[50:53], v[146:149], v[192:195], v[50:53]
	v_mfma_f32_16x16x32_bf16 v[42:45], v[160:163], v[192:195], v[42:45]
	v_mfma_f32_16x16x32_bf16 v[34:37], v[146:149], v[200:203], v[34:37]
	v_mfma_f32_16x16x32_bf16 v[26:29], v[160:163], v[200:203], v[26:29]
	v_mfma_f32_16x16x32_bf16 v[18:21], v[146:149], v[208:211], v[18:21]
	v_mfma_f32_16x16x32_bf16 v[10:13], v[160:163], v[208:211], v[10:13]
	v_mfma_f32_16x16x32_bf16 v[62:65], v[150:153], v[188:191], v[62:65]
	v_mfma_f32_16x16x32_bf16 v[58:61], v[164:167], v[188:191], v[58:61]
	v_mfma_f32_16x16x32_bf16 v[50:53], v[150:153], v[196:199], v[50:53]
	v_mfma_f32_16x16x32_bf16 v[42:45], v[164:167], v[196:199], v[42:45]
	v_mfma_f32_16x16x32_bf16 v[34:37], v[150:153], v[204:207], v[34:37]
	v_mfma_f32_16x16x32_bf16 v[26:29], v[164:167], v[204:207], v[26:29]
	v_mfma_f32_16x16x32_bf16 v[18:21], v[150:153], v[212:215], v[18:21]
	v_mfma_f32_16x16x32_bf16 v[10:13], v[164:167], v[212:215], v[10:13]
	v_mfma_f32_16x16x32_bf16 v[54:57], v[168:171], v[184:187], v[54:57]
	v_mfma_f32_16x16x32_bf16 v[46:49], v[176:179], v[184:187], v[46:49]
	v_mfma_f32_16x16x32_bf16 v[38:41], v[168:171], v[192:195], v[38:41]
	v_mfma_f32_16x16x32_bf16 v[30:33], v[176:179], v[192:195], v[30:33]
	v_mfma_f32_16x16x32_bf16 v[22:25], v[168:171], v[200:203], v[22:25]
	v_mfma_f32_16x16x32_bf16 v[14:17], v[176:179], v[200:203], v[14:17]
	v_mfma_f32_16x16x32_bf16 v[6:9], v[168:171], v[208:211], v[6:9]
	v_mfma_f32_16x16x32_bf16 v[2:5], v[176:179], v[208:211], v[2:5]
	v_mfma_f32_16x16x32_bf16 v[54:57], v[172:175], v[188:191], v[54:57]
	v_mfma_f32_16x16x32_bf16 v[46:49], v[180:183], v[188:191], v[46:49]
	v_mfma_f32_16x16x32_bf16 v[38:41], v[172:175], v[196:199], v[38:41]
	v_mfma_f32_16x16x32_bf16 v[30:33], v[180:183], v[196:199], v[30:33]
	v_mfma_f32_16x16x32_bf16 v[22:25], v[172:175], v[204:207], v[22:25]
	v_mfma_f32_16x16x32_bf16 v[14:17], v[180:183], v[204:207], v[14:17]
	v_mfma_f32_16x16x32_bf16 v[6:9], v[172:175], v[212:215], v[6:9]
	v_mfma_f32_16x16x32_bf16 v[2:5], v[180:183], v[212:215], v[2:5]
	s_barrier
	s_add_i32 s18, 0, 0x18000
	v_add_u32_e32 v159, s18, v154
	s_add_i32 s19, 0, 0x1c000
	ds_read_b128 v[146:149], v159
	ds_read_b128 v[150:153], v159 offset:1024
	ds_read_b128 v[160:163], v159 offset:2048
	ds_read_b128 v[164:167], v159 offset:3072
	v_add_u32_e32 v159, s19, v154
	ds_read_b128 v[168:171], v159
	ds_read_b128 v[172:175], v159 offset:1024
	ds_read_b128 v[176:179], v159 offset:2048
	ds_read_b128 v[180:183], v159 offset:3072
	s_add_u32 s46, s46, 0x40000
	s_addc_u32 s47, s47, 0
	s_mov_b32 m0, s58
	ds_read_b128 v[184:187], v158 offset:32768
	ds_read_b128 v[188:191], v158 offset:33792
	ds_read_b128 v[192:195], v158 offset:34816
	ds_read_b128 v[196:199], v158 offset:35840
	ds_read_b128 v[200:203], v158 offset:36864
	ds_read_b128 v[204:207], v158 offset:37888
	ds_read_b128 v[208:211], v158 offset:38912
	ds_read_b128 v[212:215], v158 offset:39936
	global_load_lds_dwordx4 v136, s[46:47]
	s_mov_b32 m0, s59
	s_nop 0
	global_load_lds_dwordx4 v132, s[46:47]
	s_waitcnt vmcnt(8)
	s_waitcnt lgkmcnt(0)
	s_barrier
; #define PG8_STAGE(bufoff, gbase, voff) do { _Pragma("unroll") for (int _i = 0; _i < 2; ++_i) \
;         __builtin_amdgcn_global_load_lds((const unsigned*)((const char*)(gbase) + (voff)[_i]), (PG8_LAS unsigned*)(lds + (bufoff) + ldsw + _i * 8192), 16, 0, 0); } while (0)
; #define PG8_LDA(dst, b, h) do { _Pragma("unroll") for (int m = 0; m < 4; ++m) _Pragma("unroll") for (int k = 0; k < 2; ++k) dst[m][k] = *(const PG8_LAS bf16x8*)(lds + PG8_SA(b, h) + aoff + m * 2048 + k * 1024); } while (0)
; #define PG8_LDB(dst, b, h) do { _Pragma("unroll") for (int n = 0; n < 2; ++n) _Pragma("unroll") for (int k = 0; k < 2; ++k) dst[n][k] = *(const PG8_LAS bf16x8*)(lds + PG8_SB(b, h) + boff + n * 2048 + k * 1024); } while (0)
; #define PG8_MMA(ai, bj, At, Bt) do { __builtin_amdgcn_s_setprio(1); _Pragma("unroll") for (int m = 0; m < 4; ++m) _Pragma("unroll") for (int n = 0; n < 2; ++n) _Pragma("unroll") for (int k = 0; k < 2; ++k) \
;         acc[ai][bj][m][n] = __builtin_amdgcn_mfma_f32_16x16x32_bf16(Bt[n][k], At[m][k], acc[ai][bj][m][n], 0, 0, 0); __builtin_amdgcn_s_setprio(0); } while (0)
; template <class Epi, class Sched, bool ALIGN_EPI = false, bool SP2 = false>
; __device__ __forceinline__ void gemm_phase(PG8_LAS unsigned char* lds, const Gemm g, const Sched& S, const Epi& E) {
;     ...
;             PG8_LDB(B0, 0, 0); PG8_LDB(B1, 0, 1); PG8_SCHED; PG8_LDA(At, 0, 0); PG8_STAGE(PG8_SA(1, 1), a1 + hA, voffA);
;             PG8_WAIT_V(8); PG8_WAIT_L(0); PG8_BAR; PG8_MMA(0, 0, At, B0); PG8_MMA(0, 1, At, B1); PG8_BAR; PG8_SCHED;
;             PG8_LDA(At, 0, 1); PG8_STAGE(PG8_SB(0, 0), b2, voffB); PG8_STAGE(PG8_SB(0, 1), b2 + hB, voffB); PG8_STAGE(PG8_SA(0, 0), a2, voffA);
;             PG8_WAIT_V(8); PG8_WAIT_L(0); PG8_BAR; PG8_MMA(1, 0, At, B0); PG8_MMA(1, 1, At, B1); PG8_BAR; PG8_SCHED;
;             PG8_LDB(B0, 1, 0); PG8_LDB(B1, 1, 1); PG8_SCHED; PG8_LDA(At, 1, 0); PG8_STAGE(PG8_SA(0, 1), a2 + hA, voffA);
;             PG8_WAIT_V(8); PG8_WAIT_L(0); PG8_BAR; PG8_MMA(0, 0, At, B0); PG8_MMA(0, 1, At, B1); PG8_BAR; PG8_SCHED;
;             PG8_LDA(At, 1, 1); PG8_STAGE(PG8_SB(1, 0), b3, voffB); PG8_STAGE(PG8_SB(1, 1), b3 + hB, voffB); PG8_STAGE(PG8_SA(1, 0), a3, voffA);
;             PG8_WAIT_V(8); PG8_WAIT_L(0); PG8_BAR; PG8_MMA(1, 0, At, B0); PG8_MMA(1, 1, At, B1); PG8_BAR; PG8_SCHED;
;     ...
;         if constexpr (ALIGN_EPI) { if (wr == 0) PG8_BAR; }
	v_mfma_f32_16x16x32_bf16 v[126:129], v[146:149], v[184:187], v[126:129]
	v_mfma_f32_16x16x32_bf16 v[122:125], v[160:163], v[184:187], v[122:125]
	v_mfma_f32_16x16x32_bf16 v[114:117], v[146:149], v[192:195], v[114:117]
	v_mfma_f32_16x16x32_bf16 v[106:109], v[160:163], v[192:195], v[106:109]
	v_mfma_f32_16x16x32_bf16 v[98:101], v[146:149], v[200:203], v[98:101]
	v_mfma_f32_16x16x32_bf16 v[90:93], v[160:163], v[200:203], v[90:93]
	v_mfma_f32_16x16x32_bf16 v[82:85], v[146:149], v[208:211], v[82:85]
	v_mfma_f32_16x16x32_bf16 v[74:77], v[160:163], v[208:211], v[74:77]
	v_mfma_f32_16x16x32_bf16 v[126:129], v[150:153], v[188:191], v[126:129]
	v_mfma_f32_16x16x32_bf16 v[122:125], v[164:167], v[188:191], v[122:125]
	v_mfma_f32_16x16x32_bf16 v[114:117], v[150:153], v[196:199], v[114:117]
	v_mfma_f32_16x16x32_bf16 v[106:109], v[164:167], v[196:199], v[106:109]
	v_mfma_f32_16x16x32_bf16 v[98:101], v[150:153], v[204:207], v[98:101]
	v_mfma_f32_16x16x32_bf16 v[90:93], v[164:167], v[204:207], v[90:93]
	v_mfma_f32_16x16x32_bf16 v[82:85], v[150:153], v[212:215], v[82:85]
	v_mfma_f32_16x16x32_bf16 v[74:77], v[164:167], v[212:215], v[74:77]
	v_mfma_f32_16x16x32_bf16 v[118:121], v[168:171], v[184:187], v[118:121]
	v_mfma_f32_16x16x32_bf16 v[110:113], v[176:179], v[184:187], v[110:113]
	v_mfma_f32_16x16x32_bf16 v[102:105], v[168:171], v[192:195], v[102:105]
	v_mfma_f32_16x16x32_bf16 v[94:97], v[176:179], v[192:195], v[94:97]
	v_mfma_f32_16x16x32_bf16 v[86:89], v[168:171], v[200:203], v[86:89]
	v_mfma_f32_16x16x32_bf16 v[78:81], v[176:179], v[200:203], v[78:81]
	v_mfma_f32_16x16x32_bf16 v[70:73], v[168:171], v[208:211], v[70:73]
	v_mfma_f32_16x16x32_bf16 v[66:69], v[176:179], v[208:211], v[66:69]
	v_mfma_f32_16x16x32_bf16 v[118:121], v[172:175], v[188:191], v[118:121]
	v_mfma_f32_16x16x32_bf16 v[110:113], v[180:183], v[188:191], v[110:113]
	v_mfma_f32_16x16x32_bf16 v[102:105], v[172:175], v[196:199], v[102:105]
	v_mfma_f32_16x16x32_bf16 v[94:97], v[180:183], v[196:199], v[94:97]
	v_mfma_f32_16x16x32_bf16 v[86:89], v[172:175], v[204:207], v[86:89]
	v_mfma_f32_16x16x32_bf16 v[78:81], v[180:183], v[204:207], v[78:81]
	v_mfma_f32_16x16x32_bf16 v[70:73], v[172:175], v[212:215], v[70:73]
	v_mfma_f32_16x16x32_bf16 v[66:69], v[180:183], v[212:215], v[66:69]
	s_barrier
	s_add_i32 s18, s18, s52
	s_mov_b32 m0, s18
	ds_read_b128 v[184:187], v158 offset:49152
	ds_read_b128 v[188:191], v158 offset:50176
	ds_read_b128 v[192:195], v158 offset:51200
	ds_read_b128 v[196:199], v158 offset:52224
	ds_read_b128 v[200:203], v158 offset:53248
	ds_read_b128 v[204:207], v158 offset:54272
	ds_read_b128 v[208:211], v158 offset:55296
	ds_read_b128 v[212:215], v158 offset:56320
	global_load_lds_dwordx4 v134, s[78:79]
	s_add_i32 m0, s18, 0x2000
	s_add_u32 s44, s44, 0x40080
	s_addc_u32 s45, s45, 0
	s_add_i32 s18, s19, s52
	global_load_lds_dwordx4 v130, s[78:79]
	s_mov_b32 m0, s18
	s_nop 0
	global_load_lds_dwordx4 v134, s[44:45]
	s_add_i32 m0, s18, 0x2000
	s_nop 0
	global_load_lds_dwordx4 v130, s[44:45]
	s_mov_b32 m0, s60
	s_nop 0
	global_load_lds_dwordx4 v136, s[80:81]
	s_mov_b32 m0, s61
	s_nop 0
	global_load_lds_dwordx4 v132, s[80:81]
	s_waitcnt vmcnt(8)
	s_waitcnt lgkmcnt(0)
	s_barrier
	v_mfma_f32_16x16x32_bf16 v[62:65], v[146:149], v[184:187], v[62:65]
	v_mfma_f32_16x16x32_bf16 v[58:61], v[160:163], v[184:187], v[58:61]
	v_mfma_f32_16x16x32_bf16 v[50:53], v[146:149], v[192:195], v[50:53]
	v_mfma_f32_16x16x32_bf16 v[42:45], v[160:163], v[192:195], v[42:45]
	v_mfma_f32_16x16x32_bf16 v[34:37], v[146:149], v[200:203], v[34:37]
	v_mfma_f32_16x16x32_bf16 v[26:29], v[160:163], v[200:203], v[26:29]
	v_mfma_f32_16x16x32_bf16 v[18:21], v[146:149], v[208:211], v[18:21]
	v_mfma_f32_16x16x32_bf16 v[10:13], v[160:163], v[208:211], v[10:13]
	v_mfma_f32_16x16x32_bf16 v[62:65], v[150:153], v[188:191], v[62:65]
	v_mfma_f32_16x16x32_bf16 v[58:61], v[164:167], v[188:191], v[58:61]
	v_mfma_f32_16x16x32_bf16 v[50:53], v[150:153], v[196:199], v[50:53]
	v_mfma_f32_16x16x32_bf16 v[42:45], v[164:167], v[196:199], v[42:45]
	v_mfma_f32_16x16x32_bf16 v[34:37], v[150:153], v[204:207], v[34:37]
	v_mfma_f32_16x16x32_bf16 v[26:29], v[164:167], v[204:207], v[26:29]
	v_mfma_f32_16x16x32_bf16 v[18:21], v[150:153], v[212:215], v[18:21]
	v_mfma_f32_16x16x32_bf16 v[10:13], v[164:167], v[212:215], v[10:13]
	v_mfma_f32_16x16x32_bf16 v[54:57], v[168:171], v[184:187], v[54:57]
	v_mfma_f32_16x16x32_bf16 v[46:49], v[176:179], v[184:187], v[46:49]
	v_mfma_f32_16x16x32_bf16 v[38:41], v[168:171], v[192:195], v[38:41]
	v_mfma_f32_16x16x32_bf16 v[30:33], v[176:179], v[192:195], v[30:33]
	v_mfma_f32_16x16x32_bf16 v[22:25], v[168:171], v[200:203], v[22:25]
	v_mfma_f32_16x16x32_bf16 v[14:17], v[176:179], v[200:203], v[14:17]
	v_mfma_f32_16x16x32_bf16 v[6:9], v[168:171], v[208:211], v[6:9]
	v_mfma_f32_16x16x32_bf16 v[2:5], v[176:179], v[208:211], v[2:5]
	v_mfma_f32_16x16x32_bf16 v[54:57], v[172:175], v[188:191], v[54:57]
	v_mfma_f32_16x16x32_bf16 v[46:49], v[180:183], v[188:191], v[46:49]
	v_mfma_f32_16x16x32_bf16 v[38:41], v[172:175], v[196:199], v[38:41]
	v_mfma_f32_16x16x32_bf16 v[30:33], v[180:183], v[196:199], v[30:33]
	v_mfma_f32_16x16x32_bf16 v[22:25], v[172:175], v[204:207], v[22:25]
	v_mfma_f32_16x16x32_bf16 v[14:17], v[180:183], v[204:207], v[14:17]
	v_mfma_f32_16x16x32_bf16 v[6:9], v[172:175], v[212:215], v[6:9]
	v_mfma_f32_16x16x32_bf16 v[2:5], v[180:183], v[212:215], v[2:5]
	s_barrier
	s_add_i32 s72, s72, 2
	s_add_u32 s42, s42, 0x100
	s_addc_u32 s43, s43, 0
	s_add_u32 s70, s70, 0x100
	s_addc_u32 s71, s71, 0
	s_cmp_gt_u32 s72, 13
	s_cbranch_scc0 .LBB0_868
	s_and_b64 vcc, exec, s[14:15]
	s_cbranch_vccz .LBB0_871
	s_barrier

; #define PG8_STAGE(bufoff, gbase, voff) do { _Pragma("unroll") for (int _i = 0; _i < 2; ++_i) \
;         __builtin_amdgcn_global_load_lds((const unsigned*)((const char*)(gbase) + (voff)[_i]), (PG8_LAS unsigned*)(lds + (bufoff) + ldsw + _i * 8192), 16, 0, 0); } while (0)
; #define PG8_LDA(dst, b, h) do { _Pragma("unroll") for (int m = 0; m < 4; ++m) _Pragma("unroll") for (int k = 0; k < 2; ++k) dst[m][k] = *(const PG8_LAS bf16x8*)(lds + PG8_SA(b, h) + aoff + m * 2048 + k * 1024); } while (0)
; #define PG8_LDB(dst, b, h) do { _Pragma("unroll") for (int n = 0; n < 2; ++n) _Pragma("unroll") for (int k = 0; k < 2; ++k) dst[n][k] = *(const PG8_LAS bf16x8*)(lds + PG8_SB(b, h) + boff + n * 2048 + k * 1024); } while (0)
; #define PG8_WAIT_V(n) asm volatile("s_waitcnt vmcnt(" #n ")" ::: "memory")
; #define PG8_WAIT_L(n) asm volatile("s_waitcnt lgkmcnt(" #n ")" ::: "memory")
; #define PG8_BAR __builtin_amdgcn_s_barrier()
; #define PG8_SCHED __builtin_amdgcn_sched_barrier(0)
; template <class Epi, class Sched, bool ALIGN_EPI = false, bool SP2 = false>
; __device__ __forceinline__ void gemm_phase(PG8_LAS unsigned char* lds, const Gemm g, const Sched& S, const Epi& E) {
;     ...
;     for (;;) {
;         const bool has_next = S.next(ui + 1, nxt);
;         const char* nA = has_next ? (const char*)g.A + (size_t)nxt.pm * tA + (size_t)nxt.pn * pnA : cA; const char* nB = has_next ? (const char*)g.Bt + (size_t)nxt.pn * tB : cB;
; #pragma nounroll
;         for (int t = 0; t < nt; t += 2) {
;             const bool last = (t == nt - 2);
;             const char* a1 = cA + (size_t)(t + 1) * kstep;
;             const char* a2 = last ? nA : cA + (size_t)(t + 2) * kstep; const char* b2 = last ? nB : cB + (size_t)(t + 2) * kstep;
;             const char* a3 = a2 + kstep; const char* b3 = b2 + kstep;
;             if (last && has_next) S.a_ready(nxt);
;             if constexpr (SP2) {
;             PG8_LDB(B0, 0, 0); PG8_LDB(B1, 0, 1); PG8_SCHED; PG8_LDA(At, 0, 0); PG8_STAGE(PG8_SA(1, 1), a1 + hA, voffA);
;             PG8_WAIT_V(8); PG8_WAIT_L(0); PG8_BAR; PG8_MMA(0, 0, At, B0); PG8_MMA(0, 1, At, B1); PG8_BAR; PG8_SCHED;
;             PG8_LDA(At, 0, 1); PG8_STAGE(PG8_SB(0, 0), b2, voffB); PG8_STAGE(PG8_SB(0, 1), b2 + hB, voffB); PG8_STAGE(PG8_SA(0, 0), a2, voffA);
;             PG8_WAIT_V(8); PG8_WAIT_L(0); PG8_BAR; PG8_MMA(1, 0, At, B0); PG8_MMA(1, 1, At, B1); PG8_BAR; PG8_SCHED;
.LBB0_887:
	s_ashr_i32 s25, s24, 31
	s_lshl_b64 s[38:39], s[24:25], 20
	s_add_u32 s38, s33, s38
	s_addc_u32 s39, s51, s39
	s_and_b64 s[40:41], s[6:7], exec
	s_cselect_b32 s25, s39, s45
	s_cselect_b32 s70, s38, s44
	s_ashr_i32 s23, s22, 31
	s_lshl_b64 s[40:41], s[22:23], 20
	s_add_u32 s40, s52, s40
	s_addc_u32 s41, s53, s41
	s_and_b64 s[48:49], s[6:7], exec
	s_cselect_b32 s23, s41, s47
	s_cselect_b32 s71, s40, s46
	s_add_u32 s44, s44, 0x80080
	s_addc_u32 s45, s45, 0
	s_add_u32 s72, s46, 0x100
	v_mov_b32_e32 v2, 0
	s_addc_u32 s73, s47, 0
	s_mov_b32 s74, -2
	v_mov_b32_e32 v3, v2
	ds_read_b128 v[130:133], v172
	ds_read_b128 v[134:137], v172 offset:1024
	ds_read_b128 v[138:141], v172 offset:2048
	ds_read_b128 v[142:145], v172 offset:3072
	ds_read_b128 v[162:165], v173
	ds_read_b128 v[166:169], v173 offset:1024
	ds_read_b128 v[176:179], v173 offset:2048
	ds_read_b128 v[180:183], v173 offset:3072
	s_add_u32 s18, s44, 0xfff80080
	s_addc_u32 s19, s45, -1
	s_cmp_eq_u32 s74, 28
	s_cselect_b32 s49, s25, s19
	s_cselect_b32 s48, s70, s18
	s_cselect_b32 s47, s23, s73
	s_cselect_b32 s46, s71, s72
	s_add_i32 m0, s43, 0xc000
	ds_read_b128 v[184:187], v174
	ds_read_b128 v[188:191], v174 offset:1024
	ds_read_b128 v[192:195], v174 offset:2048
	ds_read_b128 v[196:199], v174 offset:3072
	ds_read_b128 v[200:203], v174 offset:4096
	ds_read_b128 v[204:207], v174 offset:5120
	ds_read_b128 v[208:211], v174 offset:6144
	ds_read_b128 v[212:215], v174 offset:7168
	global_load_lds_dwordx4 v154, s[44:45]
	s_add_i32 m0, s43, 0xe000
	s_nop 0
	global_load_lds_dwordx4 v156, s[44:45]
	s_waitcnt vmcnt(8)
	s_waitcnt lgkmcnt(0)
	s_barrier
	v_mfma_f32_16x16x32_bf16 v[126:129], v[130:133], v[184:187], 0
	v_mfma_f32_16x16x32_bf16 v[122:125], v[138:141], v[184:187], 0
	v_mfma_f32_16x16x32_bf16 v[110:113], v[130:133], v[192:195], 0
	v_mfma_f32_16x16x32_bf16 v[106:109], v[138:141], v[192:195], 0
	v_mfma_f32_16x16x32_bf16 v[94:97], v[130:133], v[200:203], 0
	v_mfma_f32_16x16x32_bf16 v[90:93], v[138:141], v[200:203], 0
	v_mfma_f32_16x16x32_bf16 v[78:81], v[130:133], v[208:211], 0
	v_mfma_f32_16x16x32_bf16 v[74:77], v[138:141], v[208:211], 0
	v_mfma_f32_16x16x32_bf16 v[126:129], v[134:137], v[188:191], v[126:129]
	v_mfma_f32_16x16x32_bf16 v[122:125], v[142:145], v[188:191], v[122:125]
	v_mfma_f32_16x16x32_bf16 v[110:113], v[134:137], v[196:199], v[110:113]
	v_mfma_f32_16x16x32_bf16 v[106:109], v[142:145], v[196:199], v[106:109]
	v_mfma_f32_16x16x32_bf16 v[94:97], v[134:137], v[204:207], v[94:97]
	v_mfma_f32_16x16x32_bf16 v[90:93], v[142:145], v[204:207], v[90:93]
	v_mfma_f32_16x16x32_bf16 v[78:81], v[134:137], v[212:215], v[78:81]
	v_mfma_f32_16x16x32_bf16 v[74:77], v[142:145], v[212:215], v[74:77]
	v_mfma_f32_16x16x32_bf16 v[118:121], v[162:165], v[184:187], 0
	v_mfma_f32_16x16x32_bf16 v[114:117], v[176:179], v[184:187], 0
	v_mfma_f32_16x16x32_bf16 v[102:105], v[162:165], v[192:195], 0
	v_mfma_f32_16x16x32_bf16 v[98:101], v[176:179], v[192:195], 0
	v_mfma_f32_16x16x32_bf16 v[86:89], v[162:165], v[200:203], 0
	v_mfma_f32_16x16x32_bf16 v[82:85], v[176:179], v[200:203], 0
	v_mfma_f32_16x16x32_bf16 v[70:73], v[162:165], v[208:211], 0
	v_mfma_f32_16x16x32_bf16 v[66:69], v[176:179], v[208:211], 0
	v_mfma_f32_16x16x32_bf16 v[118:121], v[166:169], v[188:191], v[118:121]
	v_mfma_f32_16x16x32_bf16 v[114:117], v[180:183], v[188:191], v[114:117]
	v_mfma_f32_16x16x32_bf16 v[102:105], v[166:169], v[196:199], v[102:105]
	v_mfma_f32_16x16x32_bf16 v[98:101], v[180:183], v[196:199], v[98:101]
	v_mfma_f32_16x16x32_bf16 v[86:89], v[166:169], v[204:207], v[86:89]
	v_mfma_f32_16x16x32_bf16 v[82:85], v[180:183], v[204:207], v[82:85]
	v_mfma_f32_16x16x32_bf16 v[70:73], v[166:169], v[212:215], v[70:73]
	v_mfma_f32_16x16x32_bf16 v[66:69], v[180:183], v[212:215], v[66:69]
	s_barrier
	s_add_i32 s18, s66, s58
	s_add_u32 s78, s46, s16
	s_addc_u32 s79, s47, s17
	s_mov_b32 m0, s18
	ds_read_b128 v[184:187], v174 offset:16384
	ds_read_b128 v[188:191], v174 offset:17408
	ds_read_b128 v[192:195], v174 offset:18432
	ds_read_b128 v[196:199], v174 offset:19456
	ds_read_b128 v[200:203], v174 offset:20480
	ds_read_b128 v[204:207], v174 offset:21504
	ds_read_b128 v[208:211], v174 offset:22528
	ds_read_b128 v[212:215], v174 offset:23552
	global_load_lds_dwordx4 v150, s[46:47]
	s_add_i32 m0, s18, 0x2000
	s_add_u32 s76, s46, 0x80000
	s_addc_u32 s77, s47, 0
	s_add_i32 s18, s67, s58
	global_load_lds_dwordx4 v146, s[46:47]
	s_mov_b32 m0, s18
	s_nop 0
	global_load_lds_dwordx4 v150, s[76:77]
	s_add_i32 m0, s18, 0x2000
	s_nop 0
	global_load_lds_dwordx4 v146, s[76:77]
	s_add_u32 s80, s48, s16
	s_addc_u32 s81, s49, s17
	s_mov_b32 m0, s43
	s_nop 0
	global_load_lds_dwordx4 v152, s[48:49]
	s_mov_b32 m0, s59
	s_nop 0
	global_load_lds_dwordx4 v148, s[48:49]
	s_waitcnt vmcnt(8)
	s_waitcnt lgkmcnt(0)
	s_barrier
; #define PG8_STAGE(bufoff, gbase, voff) do { _Pragma("unroll") for (int _i = 0; _i < 2; ++_i) \
;         __builtin_amdgcn_global_load_lds((const unsigned*)((const char*)(gbase) + (voff)[_i]), (PG8_LAS unsigned*)(lds + (bufoff) + ldsw + _i * 8192), 16, 0, 0); } while (0)
; #define PG8_LDA(dst, b, h) do { _Pragma("unroll") for (int m = 0; m < 4; ++m) _Pragma("unroll") for (int k = 0; k < 2; ++k) dst[m][k] = *(const PG8_LAS bf16x8*)(lds + PG8_SA(b, h) + aoff + m * 2048 + k * 1024); } while (0)
; #define PG8_LDB(dst, b, h) do { _Pragma("unroll") for (int n = 0; n < 2; ++n) _Pragma("unroll") for (int k = 0; k < 2; ++k) dst[n][k] = *(const PG8_LAS bf16x8*)(lds + PG8_SB(b, h) + boff + n * 2048 + k * 1024); } while (0)
; #define PG8_MMA(ai, bj, At, Bt) do { __builtin_amdgcn_s_setprio(1); _Pragma("unroll") for (int m = 0; m < 4; ++m) _Pragma("unroll") for (int n = 0; n < 2; ++n) _Pragma("unroll") for (int k = 0; k < 2; ++k) \
;         acc[ai][bj][m][n] = __builtin_amdgcn_mfma_f32_16x16x32_bf16(Bt[n][k], At[m][k], acc[ai][bj][m][n], 0, 0, 0); __builtin_amdgcn_s_setprio(0); } while (0)
; #define PG8_WAIT_V(n) asm volatile("s_waitcnt vmcnt(" #n ")" ::: "memory")
; #define PG8_WAIT_L(n) asm volatile("s_waitcnt lgkmcnt(" #n ")" ::: "memory")
; #define PG8_BAR __builtin_amdgcn_s_barrier()
; template <class Epi, class Sched, bool ALIGN_EPI = false, bool SP2 = false>
; __device__ __forceinline__ void gemm_phase(PG8_LAS unsigned char* lds, const Gemm g, const Sched& S, const Epi& E) {
;     ...
;             PG8_LDB(B0, 0, 0); PG8_LDB(B1, 0, 1); PG8_SCHED; PG8_LDA(At, 0, 0); PG8_STAGE(PG8_SA(1, 1), a1 + hA, voffA);
;             PG8_WAIT_V(8); PG8_WAIT_L(0); PG8_BAR; PG8_MMA(0, 0, At, B0); PG8_MMA(0, 1, At, B1); PG8_BAR; PG8_SCHED;
;             PG8_LDA(At, 0, 1); PG8_STAGE(PG8_SB(0, 0), b2, voffB); PG8_STAGE(PG8_SB(0, 1), b2 + hB, voffB); PG8_STAGE(PG8_SA(0, 0), a2, voffA);
;             PG8_WAIT_V(8); PG8_WAIT_L(0); PG8_BAR; PG8_MMA(1, 0, At, B0); PG8_MMA(1, 1, At, B1); PG8_BAR; PG8_SCHED;
;             PG8_LDB(B0, 1, 0); PG8_LDB(B1, 1, 1); PG8_SCHED; PG8_LDA(At, 1, 0); PG8_STAGE(PG8_SA(0, 1), a2 + hA, voffA);
;             PG8_WAIT_V(8); PG8_WAIT_L(0); PG8_BAR; PG8_MMA(0, 0, At, B0); PG8_MMA(0, 1, At, B1); PG8_BAR; PG8_SCHED;
;             PG8_LDA(At, 1, 1); PG8_STAGE(PG8_SB(1, 0), b3, voffB); PG8_STAGE(PG8_SB(1, 1), b3 + hB, voffB); PG8_STAGE(PG8_SA(1, 0), a3, voffA);
	v_mfma_f32_16x16x32_bf16 v[62:65], v[130:133], v[184:187], 0
	v_mfma_f32_16x16x32_bf16 v[58:61], v[138:141], v[184:187], 0
	v_mfma_f32_16x16x32_bf16 v[46:49], v[130:133], v[192:195], 0
	v_mfma_f32_16x16x32_bf16 v[42:45], v[138:141], v[192:195], 0
	v_mfma_f32_16x16x32_bf16 v[30:33], v[130:133], v[200:203], 0
	v_mfma_f32_16x16x32_bf16 v[26:29], v[138:141], v[200:203], 0
	v_mfma_f32_16x16x32_bf16 v[14:17], v[130:133], v[208:211], 0
	v_mfma_f32_16x16x32_bf16 v[10:13], v[138:141], v[208:211], 0
	v_mfma_f32_16x16x32_bf16 v[62:65], v[134:137], v[188:191], v[62:65]
	v_mfma_f32_16x16x32_bf16 v[58:61], v[142:145], v[188:191], v[58:61]
	v_mfma_f32_16x16x32_bf16 v[46:49], v[134:137], v[196:199], v[46:49]
	v_mfma_f32_16x16x32_bf16 v[42:45], v[142:145], v[196:199], v[42:45]
	v_mfma_f32_16x16x32_bf16 v[30:33], v[134:137], v[204:207], v[30:33]
	v_mfma_f32_16x16x32_bf16 v[26:29], v[142:145], v[204:207], v[26:29]
	v_mfma_f32_16x16x32_bf16 v[14:17], v[134:137], v[212:215], v[14:17]
	v_mfma_f32_16x16x32_bf16 v[10:13], v[142:145], v[212:215], v[10:13]
	v_mfma_f32_16x16x32_bf16 v[54:57], v[162:165], v[184:187], 0
	v_mfma_f32_16x16x32_bf16 v[50:53], v[176:179], v[184:187], 0
	v_mfma_f32_16x16x32_bf16 v[38:41], v[162:165], v[192:195], 0
	v_mfma_f32_16x16x32_bf16 v[34:37], v[176:179], v[192:195], 0
	v_mfma_f32_16x16x32_bf16 v[22:25], v[162:165], v[200:203], 0
	v_mfma_f32_16x16x32_bf16 v[18:21], v[176:179], v[200:203], 0
	v_mfma_f32_16x16x32_bf16 v[6:9], v[162:165], v[208:211], 0
	v_mfma_f32_16x16x32_bf16 v[2:5], v[176:179], v[208:211], 0
	v_mfma_f32_16x16x32_bf16 v[54:57], v[166:169], v[188:191], v[54:57]
	v_mfma_f32_16x16x32_bf16 v[50:53], v[180:183], v[188:191], v[50:53]
	v_mfma_f32_16x16x32_bf16 v[38:41], v[166:169], v[196:199], v[38:41]
	v_mfma_f32_16x16x32_bf16 v[34:37], v[180:183], v[196:199], v[34:37]
	v_mfma_f32_16x16x32_bf16 v[22:25], v[166:169], v[204:207], v[22:25]
	v_mfma_f32_16x16x32_bf16 v[18:21], v[180:183], v[204:207], v[18:21]
	v_mfma_f32_16x16x32_bf16 v[6:9], v[166:169], v[212:215], v[6:9]
	v_mfma_f32_16x16x32_bf16 v[2:5], v[180:183], v[212:215], v[2:5]
	s_barrier
	s_add_i32 s18, 0, 0x18000
	s_add_i32 s19, 0, 0x1c000
	v_add_u32_e32 v142, s18, v170
	v_add_u32_e32 v175, s19, v170
	ds_read_b128 v[130:133], v142
	ds_read_b128 v[134:137], v142 offset:1024
	ds_read_b128 v[138:141], v142 offset:2048
	ds_read_b128 v[142:145], v142 offset:3072
	ds_read_b128 v[162:165], v175
	ds_read_b128 v[166:169], v175 offset:1024
	ds_read_b128 v[176:179], v175 offset:2048
	ds_read_b128 v[180:183], v175 offset:3072
	s_add_u32 s48, s48, 0x80000
	s_addc_u32 s49, s49, 0
	s_mov_b32 m0, s60
	ds_read_b128 v[184:187], v174 offset:32768
	ds_read_b128 v[188:191], v174 offset:33792
	ds_read_b128 v[192:195], v174 offset:34816
	ds_read_b128 v[196:199], v174 offset:35840
	ds_read_b128 v[200:203], v174 offset:36864
	ds_read_b128 v[204:207], v174 offset:37888
	ds_read_b128 v[208:211], v174 offset:38912
	ds_read_b128 v[212:215], v174 offset:39936
	global_load_lds_dwordx4 v152, s[48:49]
	s_mov_b32 m0, s61
	s_nop 0
	global_load_lds_dwordx4 v148, s[48:49]
	s_waitcnt vmcnt(8)
	s_waitcnt lgkmcnt(0)
	s_barrier
	v_mfma_f32_16x16x32_bf16 v[126:129], v[130:133], v[184:187], v[126:129]
	v_mfma_f32_16x16x32_bf16 v[122:125], v[138:141], v[184:187], v[122:125]
	v_mfma_f32_16x16x32_bf16 v[110:113], v[130:133], v[192:195], v[110:113]
	v_mfma_f32_16x16x32_bf16 v[106:109], v[138:141], v[192:195], v[106:109]
	v_mfma_f32_16x16x32_bf16 v[94:97], v[130:133], v[200:203], v[94:97]
	v_mfma_f32_16x16x32_bf16 v[90:93], v[138:141], v[200:203], v[90:93]
	v_mfma_f32_16x16x32_bf16 v[78:81], v[130:133], v[208:211], v[78:81]
	v_mfma_f32_16x16x32_bf16 v[74:77], v[138:141], v[208:211], v[74:77]
	v_mfma_f32_16x16x32_bf16 v[126:129], v[134:137], v[188:191], v[126:129]
	v_mfma_f32_16x16x32_bf16 v[122:125], v[142:145], v[188:191], v[122:125]
	v_mfma_f32_16x16x32_bf16 v[110:113], v[134:137], v[196:199], v[110:113]
	v_mfma_f32_16x16x32_bf16 v[106:109], v[142:145], v[196:199], v[106:109]
	v_mfma_f32_16x16x32_bf16 v[94:97], v[134:137], v[204:207], v[94:97]
	v_mfma_f32_16x16x32_bf16 v[90:93], v[142:145], v[204:207], v[90:93]
	v_mfma_f32_16x16x32_bf16 v[78:81], v[134:137], v[212:215], v[78:81]
	v_mfma_f32_16x16x32_bf16 v[74:77], v[142:145], v[212:215], v[74:77]
	v_mfma_f32_16x16x32_bf16 v[118:121], v[162:165], v[184:187], v[118:121]
	v_mfma_f32_16x16x32_bf16 v[114:117], v[176:179], v[184:187], v[114:117]
	v_mfma_f32_16x16x32_bf16 v[102:105], v[162:165], v[192:195], v[102:105]
	v_mfma_f32_16x16x32_bf16 v[98:101], v[176:179], v[192:195], v[98:101]
	v_mfma_f32_16x16x32_bf16 v[86:89], v[162:165], v[200:203], v[86:89]
	v_mfma_f32_16x16x32_bf16 v[82:85], v[176:179], v[200:203], v[82:85]
	v_mfma_f32_16x16x32_bf16 v[70:73], v[162:165], v[208:211], v[70:73]
	v_mfma_f32_16x16x32_bf16 v[66:69], v[176:179], v[208:211], v[66:69]
	v_mfma_f32_16x16x32_bf16 v[118:121], v[166:169], v[188:191], v[118:121]
	v_mfma_f32_16x16x32_bf16 v[114:117], v[180:183], v[188:191], v[114:117]
	v_mfma_f32_16x16x32_bf16 v[102:105], v[166:169], v[196:199], v[102:105]
	v_mfma_f32_16x16x32_bf16 v[98:101], v[180:183], v[196:199], v[98:101]
	v_mfma_f32_16x16x32_bf16 v[86:89], v[166:169], v[204:207], v[86:89]
	v_mfma_f32_16x16x32_bf16 v[82:85], v[180:183], v[204:207], v[82:85]
	v_mfma_f32_16x16x32_bf16 v[70:73], v[166:169], v[212:215], v[70:73]
	v_mfma_f32_16x16x32_bf16 v[66:69], v[180:183], v[212:215], v[66:69]
	s_barrier
; #define PG8_STAGE(bufoff, gbase, voff) do { _Pragma("unroll") for (int _i = 0; _i < 2; ++_i) \
;         __builtin_amdgcn_global_load_lds((const unsigned*)((const char*)(gbase) + (voff)[_i]), (PG8_LAS unsigned*)(lds + (bufoff) + ldsw + _i * 8192), 16, 0, 0); } while (0)
; #define PG8_LDA(dst, b, h) do { _Pragma("unroll") for (int m = 0; m < 4; ++m) _Pragma("unroll") for (int k = 0; k < 2; ++k) dst[m][k] = *(const PG8_LAS bf16x8*)(lds + PG8_SA(b, h) + aoff + m * 2048 + k * 1024); } while (0)
; #define PG8_LDB(dst, b, h) do { _Pragma("unroll") for (int n = 0; n < 2; ++n) _Pragma("unroll") for (int k = 0; k < 2; ++k) dst[n][k] = *(const PG8_LAS bf16x8*)(lds + PG8_SB(b, h) + boff + n * 2048 + k * 1024); } while (0)
; #define PG8_MMA(ai, bj, At, Bt) do { __builtin_amdgcn_s_setprio(1); _Pragma("unroll") for (int m = 0; m < 4; ++m) _Pragma("unroll") for (int n = 0; n < 2; ++n) _Pragma("unroll") for (int k = 0; k < 2; ++k) \
;         acc[ai][bj][m][n] = __builtin_amdgcn_mfma_f32_16x16x32_bf16(Bt[n][k], At[m][k], acc[ai][bj][m][n], 0, 0, 0); __builtin_amdgcn_s_setprio(0); } while (0)
; #define PG8_WAIT_V(n) asm volatile("s_waitcnt vmcnt(" #n ")" ::: "memory")
; template <class Epi, class Sched, bool ALIGN_EPI = false, bool SP2 = false>
; __device__ __forceinline__ void gemm_phase(PG8_LAS unsigned char* lds, const Gemm g, const Sched& S, const Epi& E) {
;     ...
;             PG8_LDB(B0, 0, 0); PG8_LDB(B1, 0, 1); PG8_SCHED; PG8_LDA(At, 0, 0); PG8_STAGE(PG8_SA(1, 1), a1 + hA, voffA);
;             PG8_WAIT_V(8); PG8_WAIT_L(0); PG8_BAR; PG8_MMA(0, 0, At, B0); PG8_MMA(0, 1, At, B1); PG8_BAR; PG8_SCHED;
;             PG8_LDA(At, 0, 1); PG8_STAGE(PG8_SB(0, 0), b2, voffB); PG8_STAGE(PG8_SB(0, 1), b2 + hB, voffB); PG8_STAGE(PG8_SA(0, 0), a2, voffA);
;             PG8_WAIT_V(8); PG8_WAIT_L(0); PG8_BAR; PG8_MMA(1, 0, At, B0); PG8_MMA(1, 1, At, B1); PG8_BAR; PG8_SCHED;
;             PG8_LDB(B0, 1, 0); PG8_LDB(B1, 1, 1); PG8_SCHED; PG8_LDA(At, 1, 0); PG8_STAGE(PG8_SA(0, 1), a2 + hA, voffA);
;             PG8_WAIT_V(8); PG8_WAIT_L(0); PG8_BAR; PG8_MMA(0, 0, At, B0); PG8_MMA(0, 1, At, B1); PG8_BAR; PG8_SCHED;
;             PG8_LDA(At, 1, 1); PG8_STAGE(PG8_SB(1, 0), b3, voffB); PG8_STAGE(PG8_SB(1, 1), b3 + hB, voffB); PG8_STAGE(PG8_SA(1, 0), a3, voffA);
;             PG8_WAIT_V(8); PG8_WAIT_L(0); PG8_BAR; PG8_MMA(1, 0, At, B0); PG8_MMA(1, 1, At, B1); PG8_BAR; PG8_SCHED;
	s_add_i32 s18, s18, s58
	s_mov_b32 m0, s18
	ds_read_b128 v[184:187], v174 offset:49152
	ds_read_b128 v[188:191], v174 offset:50176
	ds_read_b128 v[192:195], v174 offset:51200
	ds_read_b128 v[196:199], v174 offset:52224
	ds_read_b128 v[200:203], v174 offset:53248
	ds_read_b128 v[204:207], v174 offset:54272
	ds_read_b128 v[208:211], v174 offset:55296
	ds_read_b128 v[212:215], v174 offset:56320
	global_load_lds_dwordx4 v150, s[78:79]
	s_add_i32 m0, s18, 0x2000
	s_add_u32 s46, s46, 0x80080
	s_addc_u32 s47, s47, 0
	s_add_i32 s18, s19, s58
	global_load_lds_dwordx4 v146, s[78:79]
	s_mov_b32 m0, s18
	s_nop 0
	global_load_lds_dwordx4 v150, s[46:47]
	s_add_i32 m0, s18, 0x2000
	s_nop 0
	global_load_lds_dwordx4 v146, s[46:47]
	s_mov_b32 m0, s63
	s_nop 0
	global_load_lds_dwordx4 v152, s[80:81]
	s_mov_b32 m0, s64
	s_nop 0
	global_load_lds_dwordx4 v148, s[80:81]
	s_waitcnt vmcnt(8)
	s_waitcnt lgkmcnt(0)
	s_barrier
	v_mfma_f32_16x16x32_bf16 v[62:65], v[130:133], v[184:187], v[62:65]
	v_mfma_f32_16x16x32_bf16 v[58:61], v[138:141], v[184:187], v[58:61]
	v_mfma_f32_16x16x32_bf16 v[46:49], v[130:133], v[192:195], v[46:49]
	v_mfma_f32_16x16x32_bf16 v[42:45], v[138:141], v[192:195], v[42:45]
	v_mfma_f32_16x16x32_bf16 v[30:33], v[130:133], v[200:203], v[30:33]
	v_mfma_f32_16x16x32_bf16 v[26:29], v[138:141], v[200:203], v[26:29]
	v_mfma_f32_16x16x32_bf16 v[14:17], v[130:133], v[208:211], v[14:17]
	v_mfma_f32_16x16x32_bf16 v[10:13], v[138:141], v[208:211], v[10:13]
	v_mfma_f32_16x16x32_bf16 v[62:65], v[134:137], v[188:191], v[62:65]
	v_mfma_f32_16x16x32_bf16 v[58:61], v[142:145], v[188:191], v[58:61]
	v_mfma_f32_16x16x32_bf16 v[46:49], v[134:137], v[196:199], v[46:49]
	v_mfma_f32_16x16x32_bf16 v[42:45], v[142:145], v[196:199], v[42:45]
	v_mfma_f32_16x16x32_bf16 v[30:33], v[134:137], v[204:207], v[30:33]
	v_mfma_f32_16x16x32_bf16 v[26:29], v[142:145], v[204:207], v[26:29]
	v_mfma_f32_16x16x32_bf16 v[14:17], v[134:137], v[212:215], v[14:17]
	v_mfma_f32_16x16x32_bf16 v[10:13], v[142:145], v[212:215], v[10:13]
	v_mfma_f32_16x16x32_bf16 v[54:57], v[162:165], v[184:187], v[54:57]
	v_mfma_f32_16x16x32_bf16 v[50:53], v[176:179], v[184:187], v[50:53]
	v_mfma_f32_16x16x32_bf16 v[38:41], v[162:165], v[192:195], v[38:41]
	v_mfma_f32_16x16x32_bf16 v[34:37], v[176:179], v[192:195], v[34:37]
	v_mfma_f32_16x16x32_bf16 v[22:25], v[162:165], v[200:203], v[22:25]
	v_mfma_f32_16x16x32_bf16 v[18:21], v[176:179], v[200:203], v[18:21]
	v_mfma_f32_16x16x32_bf16 v[6:9], v[162:165], v[208:211], v[6:9]
	v_mfma_f32_16x16x32_bf16 v[2:5], v[176:179], v[208:211], v[2:5]
	v_mfma_f32_16x16x32_bf16 v[54:57], v[166:169], v[188:191], v[54:57]
	v_mfma_f32_16x16x32_bf16 v[50:53], v[180:183], v[188:191], v[50:53]
	v_mfma_f32_16x16x32_bf16 v[38:41], v[166:169], v[196:199], v[38:41]
	v_mfma_f32_16x16x32_bf16 v[34:37], v[180:183], v[196:199], v[34:37]
	v_mfma_f32_16x16x32_bf16 v[22:25], v[166:169], v[204:207], v[22:25]
	v_mfma_f32_16x16x32_bf16 v[18:21], v[180:183], v[204:207], v[18:21]
	v_mfma_f32_16x16x32_bf16 v[6:9], v[166:169], v[212:215], v[6:9]
	v_mfma_f32_16x16x32_bf16 v[2:5], v[180:183], v[212:215], v[2:5]
	s_barrier
	s_add_i32 s74, s74, 2
	s_add_u32 s44, s44, 0x100
	s_addc_u32 s45, s45, 0
	s_add_u32 s72, s72, 0x100
	s_addc_u32 s73, s73, 0
	s_cmp_gt_u32 s74, 29
.LBB0_888:
	ds_read_b128 v[130:133], v172
	ds_read_b128 v[134:137], v172 offset:1024
	ds_read_b128 v[138:141], v172 offset:2048
	ds_read_b128 v[142:145], v172 offset:3072
	ds_read_b128 v[162:165], v173
	ds_read_b128 v[166:169], v173 offset:1024
	ds_read_b128 v[176:179], v173 offset:2048
	ds_read_b128 v[180:183], v173 offset:3072
	s_add_u32 s18, s44, 0xfff80080
	s_addc_u32 s19, s45, -1
	s_cmp_eq_u32 s74, 28
	s_cselect_b32 s49, s25, s19
	s_cselect_b32 s48, s70, s18
	s_cselect_b32 s47, s23, s73
	s_cselect_b32 s46, s71, s72
	s_add_i32 m0, s43, 0xc000
	ds_read_b128 v[184:187], v174
	ds_read_b128 v[188:191], v174 offset:1024
	ds_read_b128 v[192:195], v174 offset:2048
	ds_read_b128 v[196:199], v174 offset:3072
	ds_read_b128 v[200:203], v174 offset:4096
	ds_read_b128 v[204:207], v174 offset:5120
	ds_read_b128 v[208:211], v174 offset:6144
	ds_read_b128 v[212:215], v174 offset:7168
	global_load_lds_dwordx4 v154, s[44:45]
	s_add_i32 m0, s43, 0xe000
	s_nop 0
	global_load_lds_dwordx4 v156, s[44:45]
	s_waitcnt vmcnt(8)
	s_waitcnt lgkmcnt(0)
	s_barrier
	v_mfma_f32_16x16x32_bf16 v[126:129], v[130:133], v[184:187], v[126:129]
	v_mfma_f32_16x16x32_bf16 v[122:125], v[138:141], v[184:187], v[122:125]
	v_mfma_f32_16x16x32_bf16 v[110:113], v[130:133], v[192:195], v[110:113]
	v_mfma_f32_16x16x32_bf16 v[106:109], v[138:141], v[192:195], v[106:109]
	v_mfma_f32_16x16x32_bf16 v[94:97], v[130:133], v[200:203], v[94:97]
	v_mfma_f32_16x16x32_bf16 v[90:93], v[138:141], v[200:203], v[90:93]
	v_mfma_f32_16x16x32_bf16 v[78:81], v[130:133], v[208:211], v[78:81]
	v_mfma_f32_16x16x32_bf16 v[74:77], v[138:141], v[208:211], v[74:77]
	v_mfma_f32_16x16x32_bf16 v[126:129], v[134:137], v[188:191], v[126:129]
	v_mfma_f32_16x16x32_bf16 v[122:125], v[142:145], v[188:191], v[122:125]
	v_mfma_f32_16x16x32_bf16 v[110:113], v[134:137], v[196:199], v[110:113]
	v_mfma_f32_16x16x32_bf16 v[106:109], v[142:145], v[196:199], v[106:109]
	v_mfma_f32_16x16x32_bf16 v[94:97], v[134:137], v[204:207], v[94:97]
	v_mfma_f32_16x16x32_bf16 v[90:93], v[142:145], v[204:207], v[90:93]
	v_mfma_f32_16x16x32_bf16 v[78:81], v[134:137], v[212:215], v[78:81]
	v_mfma_f32_16x16x32_bf16 v[74:77], v[142:145], v[212:215], v[74:77]
	v_mfma_f32_16x16x32_bf16 v[118:121], v[162:165], v[184:187], v[118:121]
	v_mfma_f32_16x16x32_bf16 v[114:117], v[176:179], v[184:187], v[114:117]
	v_mfma_f32_16x16x32_bf16 v[102:105], v[162:165], v[192:195], v[102:105]
	v_mfma_f32_16x16x32_bf16 v[98:101], v[176:179], v[192:195], v[98:101]
	v_mfma_f32_16x16x32_bf16 v[86:89], v[162:165], v[200:203], v[86:89]
	v_mfma_f32_16x16x32_bf16 v[82:85], v[176:179], v[200:203], v[82:85]
	v_mfma_f32_16x16x32_bf16 v[70:73], v[162:165], v[208:211], v[70:73]
	v_mfma_f32_16x16x32_bf16 v[66:69], v[176:179], v[208:211], v[66:69]
	v_mfma_f32_16x16x32_bf16 v[118:121], v[166:169], v[188:191], v[118:121]
	v_mfma_f32_16x16x32_bf16 v[114:117], v[180:183], v[188:191], v[114:117]
	v_mfma_f32_16x16x32_bf16 v[102:105], v[166:169], v[196:199], v[102:105]
	v_mfma_f32_16x16x32_bf16 v[98:101], v[180:183], v[196:199], v[98:101]
	v_mfma_f32_16x16x32_bf16 v[86:89], v[166:169], v[204:207], v[86:89]
	v_mfma_f32_16x16x32_bf16 v[82:85], v[180:183], v[204:207], v[82:85]
	v_mfma_f32_16x16x32_bf16 v[70:73], v[166:169], v[212:215], v[70:73]
	v_mfma_f32_16x16x32_bf16 v[66:69], v[180:183], v[212:215], v[66:69]
	s_barrier
; #define PG8_STAGE(bufoff, gbase, voff) do { _Pragma("unroll") for (int _i = 0; _i < 2; ++_i) \
;         __builtin_amdgcn_global_load_lds((const unsigned*)((const char*)(gbase) + (voff)[_i]), (PG8_LAS unsigned*)(lds + (bufoff) + ldsw + _i * 8192), 16, 0, 0); } while (0)
; #define PG8_LDA(dst, b, h) do { _Pragma("unroll") for (int m = 0; m < 4; ++m) _Pragma("unroll") for (int k = 0; k < 2; ++k) dst[m][k] = *(const PG8_LAS bf16x8*)(lds + PG8_SA(b, h) + aoff + m * 2048 + k * 1024); } while (0)
; #define PG8_LDB(dst, b, h) do { _Pragma("unroll") for (int n = 0; n < 2; ++n) _Pragma("unroll") for (int k = 0; k < 2; ++k) dst[n][k] = *(const PG8_LAS bf16x8*)(lds + PG8_SB(b, h) + boff + n * 2048 + k * 1024); } while (0)
; #define PG8_MMA(ai, bj, At, Bt) do { __builtin_amdgcn_s_setprio(1); _Pragma("unroll") for (int m = 0; m < 4; ++m) _Pragma("unroll") for (int n = 0; n < 2; ++n) _Pragma("unroll") for (int k = 0; k < 2; ++k) \
;         acc[ai][bj][m][n] = __builtin_amdgcn_mfma_f32_16x16x32_bf16(Bt[n][k], At[m][k], acc[ai][bj][m][n], 0, 0, 0); __builtin_amdgcn_s_setprio(0); } while (0)
; #define PG8_WAIT_V(n) asm volatile("s_waitcnt vmcnt(" #n ")" ::: "memory")
; #define PG8_WAIT_L(n) asm volatile("s_waitcnt lgkmcnt(" #n ")" ::: "memory")
; #define PG8_BAR __builtin_amdgcn_s_barrier()
; #define PG8_SCHED __builtin_amdgcn_sched_barrier(0)
; template <class Epi, class Sched, bool ALIGN_EPI = false, bool SP2 = false>
; __device__ __forceinline__ void gemm_phase(PG8_LAS unsigned char* lds, const Gemm g, const Sched& S, const Epi& E) {
;     ...
;             PG8_LDA(At, 0, 1); PG8_STAGE(PG8_SB(0, 0), b2, voffB); PG8_STAGE(PG8_SB(0, 1), b2 + hB, voffB); PG8_STAGE(PG8_SA(0, 0), a2, voffA);
;             PG8_WAIT_V(8); PG8_WAIT_L(0); PG8_BAR; PG8_MMA(1, 0, At, B0); PG8_MMA(1, 1, At, B1); PG8_BAR; PG8_SCHED;
;             PG8_LDB(B0, 1, 0); PG8_LDB(B1, 1, 1); PG8_SCHED; PG8_LDA(At, 1, 0); PG8_STAGE(PG8_SA(0, 1), a2 + hA, voffA);
;             PG8_WAIT_V(8); PG8_WAIT_L(0); PG8_BAR; PG8_MMA(0, 0, At, B0); PG8_MMA(0, 1, At, B1); PG8_BAR; PG8_SCHED;
	s_add_i32 s18, s66, s58
	s_add_u32 s78, s46, s16
	s_addc_u32 s79, s47, s17
	s_mov_b32 m0, s18
	ds_read_b128 v[184:187], v174 offset:16384
	ds_read_b128 v[188:191], v174 offset:17408
	ds_read_b128 v[192:195], v174 offset:18432
	ds_read_b128 v[196:199], v174 offset:19456
	ds_read_b128 v[200:203], v174 offset:20480
	ds_read_b128 v[204:207], v174 offset:21504
	ds_read_b128 v[208:211], v174 offset:22528
	ds_read_b128 v[212:215], v174 offset:23552
	global_load_lds_dwordx4 v150, s[46:47]
	s_add_i32 m0, s18, 0x2000
	s_add_u32 s76, s46, 0x80000
	s_addc_u32 s77, s47, 0
	s_add_i32 s18, s67, s58
	global_load_lds_dwordx4 v146, s[46:47]
	s_mov_b32 m0, s18
	s_nop 0
	global_load_lds_dwordx4 v150, s[76:77]
	s_add_i32 m0, s18, 0x2000
	s_nop 0
	global_load_lds_dwordx4 v146, s[76:77]
	s_add_u32 s80, s48, s16
	s_addc_u32 s81, s49, s17
	s_mov_b32 m0, s43
	s_nop 0
	global_load_lds_dwordx4 v152, s[48:49]
	s_mov_b32 m0, s59
	s_nop 0
	global_load_lds_dwordx4 v148, s[48:49]
	s_waitcnt vmcnt(8)
	s_waitcnt lgkmcnt(0)
	s_barrier
	v_mfma_f32_16x16x32_bf16 v[62:65], v[130:133], v[184:187], v[62:65]
	v_mfma_f32_16x16x32_bf16 v[58:61], v[138:141], v[184:187], v[58:61]
	v_mfma_f32_16x16x32_bf16 v[46:49], v[130:133], v[192:195], v[46:49]
	v_mfma_f32_16x16x32_bf16 v[42:45], v[138:141], v[192:195], v[42:45]
	v_mfma_f32_16x16x32_bf16 v[30:33], v[130:133], v[200:203], v[30:33]
	v_mfma_f32_16x16x32_bf16 v[26:29], v[138:141], v[200:203], v[26:29]
	v_mfma_f32_16x16x32_bf16 v[14:17], v[130:133], v[208:211], v[14:17]
	v_mfma_f32_16x16x32_bf16 v[10:13], v[138:141], v[208:211], v[10:13]
	v_mfma_f32_16x16x32_bf16 v[62:65], v[134:137], v[188:191], v[62:65]
	v_mfma_f32_16x16x32_bf16 v[58:61], v[142:145], v[188:191], v[58:61]
	v_mfma_f32_16x16x32_bf16 v[46:49], v[134:137], v[196:199], v[46:49]
	v_mfma_f32_16x16x32_bf16 v[42:45], v[142:145], v[196:199], v[42:45]
	v_mfma_f32_16x16x32_bf16 v[30:33], v[134:137], v[204:207], v[30:33]
	v_mfma_f32_16x16x32_bf16 v[26:29], v[142:145], v[204:207], v[26:29]
	v_mfma_f32_16x16x32_bf16 v[14:17], v[134:137], v[212:215], v[14:17]
	v_mfma_f32_16x16x32_bf16 v[10:13], v[142:145], v[212:215], v[10:13]
	v_mfma_f32_16x16x32_bf16 v[54:57], v[162:165], v[184:187], v[54:57]
	v_mfma_f32_16x16x32_bf16 v[50:53], v[176:179], v[184:187], v[50:53]
	v_mfma_f32_16x16x32_bf16 v[38:41], v[162:165], v[192:195], v[38:41]
	v_mfma_f32_16x16x32_bf16 v[34:37], v[176:179], v[192:195], v[34:37]
	v_mfma_f32_16x16x32_bf16 v[22:25], v[162:165], v[200:203], v[22:25]
	v_mfma_f32_16x16x32_bf16 v[18:21], v[176:179], v[200:203], v[18:21]
	v_mfma_f32_16x16x32_bf16 v[6:9], v[162:165], v[208:211], v[6:9]
	v_mfma_f32_16x16x32_bf16 v[2:5], v[176:179], v[208:211], v[2:5]
	v_mfma_f32_16x16x32_bf16 v[54:57], v[166:169], v[188:191], v[54:57]
	v_mfma_f32_16x16x32_bf16 v[50:53], v[180:183], v[188:191], v[50:53]
	v_mfma_f32_16x16x32_bf16 v[38:41], v[166:169], v[196:199], v[38:41]
	v_mfma_f32_16x16x32_bf16 v[34:37], v[180:183], v[196:199], v[34:37]
	v_mfma_f32_16x16x32_bf16 v[22:25], v[166:169], v[204:207], v[22:25]
	v_mfma_f32_16x16x32_bf16 v[18:21], v[180:183], v[204:207], v[18:21]
	v_mfma_f32_16x16x32_bf16 v[6:9], v[166:169], v[212:215], v[6:9]
	v_mfma_f32_16x16x32_bf16 v[2:5], v[180:183], v[212:215], v[2:5]
	s_barrier
	s_add_i32 s18, 0, 0x18000
	s_add_i32 s19, 0, 0x1c000
	v_add_u32_e32 v142, s18, v170
	v_add_u32_e32 v175, s19, v170
	ds_read_b128 v[130:133], v142
	ds_read_b128 v[134:137], v142 offset:1024
	ds_read_b128 v[138:141], v142 offset:2048
	ds_read_b128 v[142:145], v142 offset:3072
	ds_read_b128 v[162:165], v175
	ds_read_b128 v[166:169], v175 offset:1024
	ds_read_b128 v[176:179], v175 offset:2048
	ds_read_b128 v[180:183], v175 offset:3072
	s_add_u32 s48, s48, 0x80000
	s_addc_u32 s49, s49, 0
	s_mov_b32 m0, s60
	ds_read_b128 v[184:187], v174 offset:32768
	ds_read_b128 v[188:191], v174 offset:33792
	ds_read_b128 v[192:195], v174 offset:34816
	ds_read_b128 v[196:199], v174 offset:35840
	ds_read_b128 v[200:203], v174 offset:36864
	ds_read_b128 v[204:207], v174 offset:37888
	ds_read_b128 v[208:211], v174 offset:38912
	ds_read_b128 v[212:215], v174 offset:39936
	global_load_lds_dwordx4 v152, s[48:49]
	s_mov_b32 m0, s61
	s_nop 0
	global_load_lds_dwordx4 v148, s[48:49]
	s_waitcnt vmcnt(8)
	s_waitcnt lgkmcnt(0)
	s_barrier
; #define PG8_STAGE(bufoff, gbase, voff) do { _Pragma("unroll") for (int _i = 0; _i < 2; ++_i) \
;         __builtin_amdgcn_global_load_lds((const unsigned*)((const char*)(gbase) + (voff)[_i]), (PG8_LAS unsigned*)(lds + (bufoff) + ldsw + _i * 8192), 16, 0, 0); } while (0)
; #define PG8_LDA(dst, b, h) do { _Pragma("unroll") for (int m = 0; m < 4; ++m) _Pragma("unroll") for (int k = 0; k < 2; ++k) dst[m][k] = *(const PG8_LAS bf16x8*)(lds + PG8_SA(b, h) + aoff + m * 2048 + k * 1024); } while (0)
; #define PG8_LDB(dst, b, h) do { _Pragma("unroll") for (int n = 0; n < 2; ++n) _Pragma("unroll") for (int k = 0; k < 2; ++k) dst[n][k] = *(const PG8_LAS bf16x8*)(lds + PG8_SB(b, h) + boff + n * 2048 + k * 1024); } while (0)
; #define PG8_MMA(ai, bj, At, Bt) do { __builtin_amdgcn_s_setprio(1); _Pragma("unroll") for (int m = 0; m < 4; ++m) _Pragma("unroll") for (int n = 0; n < 2; ++n) _Pragma("unroll") for (int k = 0; k < 2; ++k) \
;         acc[ai][bj][m][n] = __builtin_amdgcn_mfma_f32_16x16x32_bf16(Bt[n][k], At[m][k], acc[ai][bj][m][n], 0, 0, 0); __builtin_amdgcn_s_setprio(0); } while (0)
; #define PG8_WAIT_V(n) asm volatile("s_waitcnt vmcnt(" #n ")" ::: "memory")
; #define PG8_WAIT_L(n) asm volatile("s_waitcnt lgkmcnt(" #n ")" ::: "memory")
; #define PG8_BAR __builtin_amdgcn_s_barrier()
; #define PG8_SCHED __builtin_amdgcn_sched_barrier(0)
; template <class Epi, class Sched, bool ALIGN_EPI = false, bool SP2 = false>
; __device__ __forceinline__ void gemm_phase(PG8_LAS unsigned char* lds, const Gemm g, const Sched& S, const Epi& E) {
;     ...
;             PG8_LDB(B0, 1, 0); PG8_LDB(B1, 1, 1); PG8_SCHED; PG8_LDA(At, 1, 0); PG8_STAGE(PG8_SA(0, 1), a2 + hA, voffA);
;             PG8_WAIT_V(8); PG8_WAIT_L(0); PG8_BAR; PG8_MMA(0, 0, At, B0); PG8_MMA(0, 1, At, B1); PG8_BAR; PG8_SCHED;
;             PG8_LDA(At, 1, 1); PG8_STAGE(PG8_SB(1, 0), b3, voffB); PG8_STAGE(PG8_SB(1, 1), b3 + hB, voffB); PG8_STAGE(PG8_SA(1, 0), a3, voffA);
;             PG8_WAIT_V(8); PG8_WAIT_L(0); PG8_BAR; PG8_MMA(1, 0, At, B0); PG8_MMA(1, 1, At, B1); PG8_BAR; PG8_SCHED;
;     ...
;         if constexpr (ALIGN_EPI) { if (wr == 0) PG8_BAR; }
	v_mfma_f32_16x16x32_bf16 v[126:129], v[130:133], v[184:187], v[126:129]
	v_mfma_f32_16x16x32_bf16 v[122:125], v[138:141], v[184:187], v[122:125]
	v_mfma_f32_16x16x32_bf16 v[110:113], v[130:133], v[192:195], v[110:113]
	v_mfma_f32_16x16x32_bf16 v[106:109], v[138:141], v[192:195], v[106:109]
	v_mfma_f32_16x16x32_bf16 v[94:97], v[130:133], v[200:203], v[94:97]
	v_mfma_f32_16x16x32_bf16 v[90:93], v[138:141], v[200:203], v[90:93]
	v_mfma_f32_16x16x32_bf16 v[78:81], v[130:133], v[208:211], v[78:81]
	v_mfma_f32_16x16x32_bf16 v[74:77], v[138:141], v[208:211], v[74:77]
	v_mfma_f32_16x16x32_bf16 v[126:129], v[134:137], v[188:191], v[126:129]
	v_mfma_f32_16x16x32_bf16 v[122:125], v[142:145], v[188:191], v[122:125]
	v_mfma_f32_16x16x32_bf16 v[110:113], v[134:137], v[196:199], v[110:113]
	v_mfma_f32_16x16x32_bf16 v[106:109], v[142:145], v[196:199], v[106:109]
	v_mfma_f32_16x16x32_bf16 v[94:97], v[134:137], v[204:207], v[94:97]
	v_mfma_f32_16x16x32_bf16 v[90:93], v[142:145], v[204:207], v[90:93]
	v_mfma_f32_16x16x32_bf16 v[78:81], v[134:137], v[212:215], v[78:81]
	v_mfma_f32_16x16x32_bf16 v[74:77], v[142:145], v[212:215], v[74:77]
	v_mfma_f32_16x16x32_bf16 v[118:121], v[162:165], v[184:187], v[118:121]
	v_mfma_f32_16x16x32_bf16 v[114:117], v[176:179], v[184:187], v[114:117]
	v_mfma_f32_16x16x32_bf16 v[102:105], v[162:165], v[192:195], v[102:105]
	v_mfma_f32_16x16x32_bf16 v[98:101], v[176:179], v[192:195], v[98:101]
	v_mfma_f32_16x16x32_bf16 v[86:89], v[162:165], v[200:203], v[86:89]
	v_mfma_f32_16x16x32_bf16 v[82:85], v[176:179], v[200:203], v[82:85]
	v_mfma_f32_16x16x32_bf16 v[70:73], v[162:165], v[208:211], v[70:73]
	v_mfma_f32_16x16x32_bf16 v[66:69], v[176:179], v[208:211], v[66:69]
	v_mfma_f32_16x16x32_bf16 v[118:121], v[166:169], v[188:191], v[118:121]
	v_mfma_f32_16x16x32_bf16 v[114:117], v[180:183], v[188:191], v[114:117]
	v_mfma_f32_16x16x32_bf16 v[102:105], v[166:169], v[196:199], v[102:105]
	v_mfma_f32_16x16x32_bf16 v[98:101], v[180:183], v[196:199], v[98:101]
	v_mfma_f32_16x16x32_bf16 v[86:89], v[166:169], v[204:207], v[86:89]
	v_mfma_f32_16x16x32_bf16 v[82:85], v[180:183], v[204:207], v[82:85]
	v_mfma_f32_16x16x32_bf16 v[70:73], v[166:169], v[212:215], v[70:73]
	v_mfma_f32_16x16x32_bf16 v[66:69], v[180:183], v[212:215], v[66:69]
	s_barrier
	s_add_i32 s18, s18, s58
	s_mov_b32 m0, s18
	ds_read_b128 v[184:187], v174 offset:49152
	ds_read_b128 v[188:191], v174 offset:50176
	ds_read_b128 v[192:195], v174 offset:51200
	ds_read_b128 v[196:199], v174 offset:52224
	ds_read_b128 v[200:203], v174 offset:53248
	ds_read_b128 v[204:207], v174 offset:54272
	ds_read_b128 v[208:211], v174 offset:55296
	ds_read_b128 v[212:215], v174 offset:56320
	global_load_lds_dwordx4 v150, s[78:79]
	s_add_i32 m0, s18, 0x2000
	s_add_u32 s46, s46, 0x80080
	s_addc_u32 s47, s47, 0
	s_add_i32 s18, s19, s58
	global_load_lds_dwordx4 v146, s[78:79]
	s_mov_b32 m0, s18
	s_nop 0
	global_load_lds_dwordx4 v150, s[46:47]
	s_add_i32 m0, s18, 0x2000
	s_nop 0
	global_load_lds_dwordx4 v146, s[46:47]
	s_mov_b32 m0, s63
	s_nop 0
	global_load_lds_dwordx4 v152, s[80:81]
	s_mov_b32 m0, s64
	s_nop 0
	global_load_lds_dwordx4 v148, s[80:81]
	s_waitcnt vmcnt(8)
	s_waitcnt lgkmcnt(0)
	s_barrier
	v_mfma_f32_16x16x32_bf16 v[62:65], v[130:133], v[184:187], v[62:65]
	v_mfma_f32_16x16x32_bf16 v[58:61], v[138:141], v[184:187], v[58:61]
	v_mfma_f32_16x16x32_bf16 v[46:49], v[130:133], v[192:195], v[46:49]
	v_mfma_f32_16x16x32_bf16 v[42:45], v[138:141], v[192:195], v[42:45]
	v_mfma_f32_16x16x32_bf16 v[30:33], v[130:133], v[200:203], v[30:33]
	v_mfma_f32_16x16x32_bf16 v[26:29], v[138:141], v[200:203], v[26:29]
	v_mfma_f32_16x16x32_bf16 v[14:17], v[130:133], v[208:211], v[14:17]
	v_mfma_f32_16x16x32_bf16 v[10:13], v[138:141], v[208:211], v[10:13]
	v_mfma_f32_16x16x32_bf16 v[62:65], v[134:137], v[188:191], v[62:65]
	v_mfma_f32_16x16x32_bf16 v[58:61], v[142:145], v[188:191], v[58:61]
	v_mfma_f32_16x16x32_bf16 v[46:49], v[134:137], v[196:199], v[46:49]
	v_mfma_f32_16x16x32_bf16 v[42:45], v[142:145], v[196:199], v[42:45]
	v_mfma_f32_16x16x32_bf16 v[30:33], v[134:137], v[204:207], v[30:33]
	v_mfma_f32_16x16x32_bf16 v[26:29], v[142:145], v[204:207], v[26:29]
	v_mfma_f32_16x16x32_bf16 v[14:17], v[134:137], v[212:215], v[14:17]
	v_mfma_f32_16x16x32_bf16 v[10:13], v[142:145], v[212:215], v[10:13]
	v_mfma_f32_16x16x32_bf16 v[54:57], v[162:165], v[184:187], v[54:57]
	v_mfma_f32_16x16x32_bf16 v[50:53], v[176:179], v[184:187], v[50:53]
	v_mfma_f32_16x16x32_bf16 v[38:41], v[162:165], v[192:195], v[38:41]
	v_mfma_f32_16x16x32_bf16 v[34:37], v[176:179], v[192:195], v[34:37]
	v_mfma_f32_16x16x32_bf16 v[22:25], v[162:165], v[200:203], v[22:25]
	v_mfma_f32_16x16x32_bf16 v[18:21], v[176:179], v[200:203], v[18:21]
	v_mfma_f32_16x16x32_bf16 v[6:9], v[162:165], v[208:211], v[6:9]
	v_mfma_f32_16x16x32_bf16 v[2:5], v[176:179], v[208:211], v[2:5]
	v_mfma_f32_16x16x32_bf16 v[54:57], v[166:169], v[188:191], v[54:57]
	v_mfma_f32_16x16x32_bf16 v[50:53], v[180:183], v[188:191], v[50:53]
	v_mfma_f32_16x16x32_bf16 v[38:41], v[166:169], v[196:199], v[38:41]
	v_mfma_f32_16x16x32_bf16 v[34:37], v[180:183], v[196:199], v[34:37]
	v_mfma_f32_16x16x32_bf16 v[22:25], v[166:169], v[204:207], v[22:25]
	v_mfma_f32_16x16x32_bf16 v[18:21], v[180:183], v[204:207], v[18:21]
	v_mfma_f32_16x16x32_bf16 v[6:9], v[166:169], v[212:215], v[6:9]
	v_mfma_f32_16x16x32_bf16 v[2:5], v[180:183], v[212:215], v[2:5]
	s_barrier
	s_add_i32 s74, s74, 2
	s_add_u32 s44, s44, 0x100
	s_addc_u32 s45, s45, 0
	s_add_u32 s72, s72, 0x100
	s_addc_u32 s73, s73, 0
	s_cmp_gt_u32 s74, 29
	s_cbranch_scc0 .LBB0_888
	s_and_b64 vcc, exec, s[20:21]
	s_cbranch_vccz .LBB0_891
	s_barrier

; #define PG8_STAGE(bufoff, gbase, voff) do { _Pragma("unroll") for (int _i = 0; _i < 2; ++_i) \
;         __builtin_amdgcn_global_load_lds((const unsigned*)((const char*)(gbase) + (voff)[_i]), (PG8_LAS unsigned*)(lds + (bufoff) + ldsw + _i * 8192), 16, 0, 0); } while (0)
; #define PG8_LDA(dst, b, h) do { _Pragma("unroll") for (int m = 0; m < 4; ++m) _Pragma("unroll") for (int k = 0; k < 2; ++k) dst[m][k] = *(const PG8_LAS bf16x8*)(lds + PG8_SA(b, h) + aoff + m * 2048 + k * 1024); } while (0)
; #define PG8_LDB(dst, b, h) do { _Pragma("unroll") for (int n = 0; n < 2; ++n) _Pragma("unroll") for (int k = 0; k < 2; ++k) dst[n][k] = *(const PG8_LAS bf16x8*)(lds + PG8_SB(b, h) + boff + n * 2048 + k * 1024); } while (0)
; #define PG8_MMA(ai, bj, At, Bt) do { __builtin_amdgcn_s_setprio(1); _Pragma("unroll") for (int m = 0; m < 4; ++m) _Pragma("unroll") for (int n = 0; n < 2; ++n) _Pragma("unroll") for (int k = 0; k < 2; ++k) \
;         acc[ai][bj][m][n] = __builtin_amdgcn_mfma_f32_16x16x32_bf16(Bt[n][k], At[m][k], acc[ai][bj][m][n], 0, 0, 0); __builtin_amdgcn_s_setprio(0); } while (0)
; #define PG8_WAIT_V(n) asm volatile("s_waitcnt vmcnt(" #n ")" ::: "memory")
; #define PG8_BAR __builtin_amdgcn_s_barrier()
; template <class Epi, class Sched, bool ALIGN_EPI = false, bool SP2 = false>
; __device__ __forceinline__ void gemm_phase(PG8_LAS unsigned char* lds, const Gemm g, const Sched& S, const Epi& E) {
;     ...
;     for (;;) {
;         const bool has_next = S.next(ui + 1, nxt);
;         const char* nA = has_next ? (const char*)g.A + (size_t)nxt.pm * tA + (size_t)nxt.pn * pnA : cA; const char* nB = has_next ? (const char*)g.Bt + (size_t)nxt.pn * tB : cB;
; #pragma nounroll
;         for (int t = 0; t < nt; t += 2) {
;             const bool last = (t == nt - 2);
;             const char* a1 = cA + (size_t)(t + 1) * kstep;
;             const char* a2 = last ? nA : cA + (size_t)(t + 2) * kstep; const char* b2 = last ? nB : cB + (size_t)(t + 2) * kstep;
;             const char* a3 = a2 + kstep; const char* b3 = b2 + kstep;
;             if (last && has_next) S.a_ready(nxt);
;             if constexpr (SP2) {
;             PG8_LDB(B0, 0, 0); PG8_LDB(B1, 0, 1); PG8_SCHED; PG8_LDA(At, 0, 0); PG8_STAGE(PG8_SA(1, 1), a1 + hA, voffA);
;             PG8_WAIT_V(8); PG8_WAIT_L(0); PG8_BAR; PG8_MMA(0, 0, At, B0); PG8_MMA(0, 1, At, B1); PG8_BAR; PG8_SCHED;
.LBB0_962:
	s_ashr_i32 s41, s40, 31
	s_lshl_b64 s[42:43], s[40:41], 20
	s_add_u32 s42, s33, s42
	s_addc_u32 s43, s58, s43
	s_and_b64 s[44:45], s[8:9], exec
	s_cselect_b32 s41, s43, s49
	s_cselect_b32 s47, s42, s48
	s_ashr_i32 s39, s38, 31
	s_lshl_b64 s[44:45], s[38:39], 20
	s_add_u32 s44, s59, s44
	s_addc_u32 s45, s60, s45
	s_and_b64 s[52:53], s[8:9], exec
	s_cselect_b32 s39, s45, s51
	s_cselect_b32 s75, s44, s50
	s_add_u32 s48, s48, 0x80080
	s_addc_u32 s49, s49, 0
	s_add_u32 s76, s50, 0x100
	v_mov_b32_e32 v2, 0
	s_addc_u32 s77, s51, 0
	s_mov_b32 s78, -2
	s_waitcnt lgkmcnt(0)
	v_mov_b32_e32 v3, v2
	ds_read_b128 v[130:133], v208
	ds_read_b128 v[134:137], v208 offset:1024
	ds_read_b128 v[138:141], v208 offset:2048
	ds_read_b128 v[142:145], v208 offset:3072
	ds_read_b128 v[146:149], v209
	ds_read_b128 v[150:153], v209 offset:1024
	ds_read_b128 v[154:157], v209 offset:2048
	ds_read_b128 v[158:161], v209 offset:3072
	s_add_u32 s18, s48, 0xfff80080
	s_addc_u32 s19, s49, -1
	s_cmp_eq_u32 s78, 28
	s_cselect_b32 s53, s41, s19
	s_cselect_b32 s52, s47, s18
	s_cselect_b32 s51, s39, s77
	s_cselect_b32 s50, s75, s76
	s_add_i32 m0, s62, 0xc000
	ds_read_b128 v[162:165], v210
	ds_read_b128 v[166:169], v210 offset:1024
	ds_read_b128 v[170:173], v210 offset:2048
	ds_read_b128 v[174:177], v210 offset:3072
	ds_read_b128 v[194:197], v210 offset:4096
	ds_read_b128 v[198:201], v210 offset:5120
	ds_read_b128 v[202:205], v210 offset:6144
	ds_read_b128 v[212:215], v210 offset:7168
	global_load_lds_dwordx4 v186, s[48:49]
	s_add_i32 m0, s62, 0xe000
	s_nop 0
	global_load_lds_dwordx4 v188, s[48:49]
	s_waitcnt vmcnt(8)
	s_waitcnt lgkmcnt(0)
	s_barrier
	v_mfma_f32_16x16x32_bf16 v[126:129], v[130:133], v[162:165], 0
	v_mfma_f32_16x16x32_bf16 v[122:125], v[138:141], v[162:165], 0
	v_mfma_f32_16x16x32_bf16 v[110:113], v[130:133], v[170:173], 0
	v_mfma_f32_16x16x32_bf16 v[106:109], v[138:141], v[170:173], 0
	v_mfma_f32_16x16x32_bf16 v[94:97], v[130:133], v[194:197], 0
	v_mfma_f32_16x16x32_bf16 v[90:93], v[138:141], v[194:197], 0
	v_mfma_f32_16x16x32_bf16 v[78:81], v[130:133], v[202:205], 0
	v_mfma_f32_16x16x32_bf16 v[74:77], v[138:141], v[202:205], 0
	v_mfma_f32_16x16x32_bf16 v[126:129], v[134:137], v[166:169], v[126:129]
	v_mfma_f32_16x16x32_bf16 v[122:125], v[142:145], v[166:169], v[122:125]
	v_mfma_f32_16x16x32_bf16 v[110:113], v[134:137], v[174:177], v[110:113]
	v_mfma_f32_16x16x32_bf16 v[106:109], v[142:145], v[174:177], v[106:109]
	v_mfma_f32_16x16x32_bf16 v[94:97], v[134:137], v[198:201], v[94:97]
	v_mfma_f32_16x16x32_bf16 v[90:93], v[142:145], v[198:201], v[90:93]
	v_mfma_f32_16x16x32_bf16 v[78:81], v[134:137], v[212:215], v[78:81]
	v_mfma_f32_16x16x32_bf16 v[74:77], v[142:145], v[212:215], v[74:77]
	v_mfma_f32_16x16x32_bf16 v[118:121], v[146:149], v[162:165], 0
	v_mfma_f32_16x16x32_bf16 v[114:117], v[154:157], v[162:165], 0
	v_mfma_f32_16x16x32_bf16 v[102:105], v[146:149], v[170:173], 0
	v_mfma_f32_16x16x32_bf16 v[98:101], v[154:157], v[170:173], 0
	v_mfma_f32_16x16x32_bf16 v[86:89], v[146:149], v[194:197], 0
	v_mfma_f32_16x16x32_bf16 v[82:85], v[154:157], v[194:197], 0
	v_mfma_f32_16x16x32_bf16 v[70:73], v[146:149], v[202:205], 0
	v_mfma_f32_16x16x32_bf16 v[66:69], v[154:157], v[202:205], 0
	v_mfma_f32_16x16x32_bf16 v[118:121], v[150:153], v[166:169], v[118:121]
	v_mfma_f32_16x16x32_bf16 v[114:117], v[158:161], v[166:169], v[114:117]
	v_mfma_f32_16x16x32_bf16 v[102:105], v[150:153], v[174:177], v[102:105]
	v_mfma_f32_16x16x32_bf16 v[98:101], v[158:161], v[174:177], v[98:101]
	v_mfma_f32_16x16x32_bf16 v[86:89], v[150:153], v[198:201], v[86:89]
	v_mfma_f32_16x16x32_bf16 v[82:85], v[158:161], v[198:201], v[82:85]
	v_mfma_f32_16x16x32_bf16 v[70:73], v[150:153], v[212:215], v[70:73]
	v_mfma_f32_16x16x32_bf16 v[66:69], v[158:161], v[212:215], v[66:69]
	s_barrier
	s_add_i32 s18, s72, s61
	s_add_u32 s82, s50, s22
	s_addc_u32 s83, s51, s23
	s_mov_b32 m0, s18
	ds_read_b128 v[162:165], v210 offset:16384
	ds_read_b128 v[166:169], v210 offset:17408
	ds_read_b128 v[170:173], v210 offset:18432
	ds_read_b128 v[174:177], v210 offset:19456
	ds_read_b128 v[194:197], v210 offset:20480
	ds_read_b128 v[198:201], v210 offset:21504
	ds_read_b128 v[202:205], v210 offset:22528
	ds_read_b128 v[212:215], v210 offset:23552
	global_load_lds_dwordx4 v180, s[50:51]
	s_add_i32 m0, s18, 0x2000
	s_add_u32 s80, s50, 0x80000
	s_addc_u32 s81, s51, 0
	s_add_i32 s18, s73, s61
	global_load_lds_dwordx4 v184, s[50:51]
	s_mov_b32 m0, s18
	s_nop 0
	global_load_lds_dwordx4 v180, s[80:81]
	s_add_i32 m0, s18, 0x2000
	s_nop 0
	global_load_lds_dwordx4 v184, s[80:81]
	s_add_u32 s88, s52, s22
	s_addc_u32 s89, s53, s23
	s_mov_b32 m0, s62
	s_nop 0
	global_load_lds_dwordx4 v178, s[52:53]
	s_mov_b32 m0, s63
	s_nop 0
	global_load_lds_dwordx4 v182, s[52:53]
	s_waitcnt vmcnt(8)
	s_waitcnt lgkmcnt(0)
	s_barrier
; #define PG8_STAGE(bufoff, gbase, voff) do { _Pragma("unroll") for (int _i = 0; _i < 2; ++_i) \
;         __builtin_amdgcn_global_load_lds((const unsigned*)((const char*)(gbase) + (voff)[_i]), (PG8_LAS unsigned*)(lds + (bufoff) + ldsw + _i * 8192), 16, 0, 0); } while (0)
; #define PG8_LDA(dst, b, h) do { _Pragma("unroll") for (int m = 0; m < 4; ++m) _Pragma("unroll") for (int k = 0; k < 2; ++k) dst[m][k] = *(const PG8_LAS bf16x8*)(lds + PG8_SA(b, h) + aoff + m * 2048 + k * 1024); } while (0)
; #define PG8_LDB(dst, b, h) do { _Pragma("unroll") for (int n = 0; n < 2; ++n) _Pragma("unroll") for (int k = 0; k < 2; ++k) dst[n][k] = *(const PG8_LAS bf16x8*)(lds + PG8_SB(b, h) + boff + n * 2048 + k * 1024); } while (0)
; #define PG8_MMA(ai, bj, At, Bt) do { __builtin_amdgcn_s_setprio(1); _Pragma("unroll") for (int m = 0; m < 4; ++m) _Pragma("unroll") for (int n = 0; n < 2; ++n) _Pragma("unroll") for (int k = 0; k < 2; ++k) \
;         acc[ai][bj][m][n] = __builtin_amdgcn_mfma_f32_16x16x32_bf16(Bt[n][k], At[m][k], acc[ai][bj][m][n], 0, 0, 0); __builtin_amdgcn_s_setprio(0); } while (0)
; #define PG8_WAIT_V(n) asm volatile("s_waitcnt vmcnt(" #n ")" ::: "memory")
; #define PG8_WAIT_L(n) asm volatile("s_waitcnt lgkmcnt(" #n ")" ::: "memory")
; #define PG8_BAR __builtin_amdgcn_s_barrier()
; #define PG8_SCHED __builtin_amdgcn_sched_barrier(0)
; template <class Epi, class Sched, bool ALIGN_EPI = false, bool SP2 = false>
; __device__ __forceinline__ void gemm_phase(PG8_LAS unsigned char* lds, const Gemm g, const Sched& S, const Epi& E) {
;     ...
;             PG8_LDA(At, 0, 1); PG8_STAGE(PG8_SB(0, 0), b2, voffB); PG8_STAGE(PG8_SB(0, 1), b2 + hB, voffB); PG8_STAGE(PG8_SA(0, 0), a2, voffA);
;             PG8_WAIT_V(8); PG8_WAIT_L(0); PG8_BAR; PG8_MMA(1, 0, At, B0); PG8_MMA(1, 1, At, B1); PG8_BAR; PG8_SCHED;
;             PG8_LDB(B0, 1, 0); PG8_LDB(B1, 1, 1); PG8_SCHED; PG8_LDA(At, 1, 0); PG8_STAGE(PG8_SA(0, 1), a2 + hA, voffA);
;             PG8_WAIT_V(8); PG8_WAIT_L(0); PG8_BAR; PG8_MMA(0, 0, At, B0); PG8_MMA(0, 1, At, B1); PG8_BAR; PG8_SCHED;
	v_mfma_f32_16x16x32_bf16 v[62:65], v[130:133], v[162:165], 0
	v_mfma_f32_16x16x32_bf16 v[58:61], v[138:141], v[162:165], 0
	v_mfma_f32_16x16x32_bf16 v[46:49], v[130:133], v[170:173], 0
	v_mfma_f32_16x16x32_bf16 v[42:45], v[138:141], v[170:173], 0
	v_mfma_f32_16x16x32_bf16 v[30:33], v[130:133], v[194:197], 0
	v_mfma_f32_16x16x32_bf16 v[26:29], v[138:141], v[194:197], 0
	v_mfma_f32_16x16x32_bf16 v[14:17], v[130:133], v[202:205], 0
	v_mfma_f32_16x16x32_bf16 v[10:13], v[138:141], v[202:205], 0
	v_mfma_f32_16x16x32_bf16 v[62:65], v[134:137], v[166:169], v[62:65]
	v_mfma_f32_16x16x32_bf16 v[58:61], v[142:145], v[166:169], v[58:61]
	v_mfma_f32_16x16x32_bf16 v[46:49], v[134:137], v[174:177], v[46:49]
	v_mfma_f32_16x16x32_bf16 v[42:45], v[142:145], v[174:177], v[42:45]
	v_mfma_f32_16x16x32_bf16 v[30:33], v[134:137], v[198:201], v[30:33]
	v_mfma_f32_16x16x32_bf16 v[26:29], v[142:145], v[198:201], v[26:29]
	v_mfma_f32_16x16x32_bf16 v[14:17], v[134:137], v[212:215], v[14:17]
	v_mfma_f32_16x16x32_bf16 v[10:13], v[142:145], v[212:215], v[10:13]
	v_mfma_f32_16x16x32_bf16 v[54:57], v[146:149], v[162:165], 0
	v_mfma_f32_16x16x32_bf16 v[50:53], v[154:157], v[162:165], 0
	v_mfma_f32_16x16x32_bf16 v[38:41], v[146:149], v[170:173], 0
	v_mfma_f32_16x16x32_bf16 v[34:37], v[154:157], v[170:173], 0
	v_mfma_f32_16x16x32_bf16 v[22:25], v[146:149], v[194:197], 0
	v_mfma_f32_16x16x32_bf16 v[18:21], v[154:157], v[194:197], 0
	v_mfma_f32_16x16x32_bf16 v[6:9], v[146:149], v[202:205], 0
	v_mfma_f32_16x16x32_bf16 v[2:5], v[154:157], v[202:205], 0
	v_mfma_f32_16x16x32_bf16 v[54:57], v[150:153], v[166:169], v[54:57]
	v_mfma_f32_16x16x32_bf16 v[50:53], v[158:161], v[166:169], v[50:53]
	v_mfma_f32_16x16x32_bf16 v[38:41], v[150:153], v[174:177], v[38:41]
	v_mfma_f32_16x16x32_bf16 v[34:37], v[158:161], v[174:177], v[34:37]
	v_mfma_f32_16x16x32_bf16 v[22:25], v[150:153], v[198:201], v[22:25]
	v_mfma_f32_16x16x32_bf16 v[18:21], v[158:161], v[198:201], v[18:21]
	v_mfma_f32_16x16x32_bf16 v[6:9], v[150:153], v[212:215], v[6:9]
	v_mfma_f32_16x16x32_bf16 v[2:5], v[158:161], v[212:215], v[2:5]
	s_barrier
	s_add_i32 s18, 0, 0x18000
	s_add_i32 s19, 0, 0x1c000
	v_add_u32_e32 v142, s18, v206
	v_add_u32_e32 v158, s19, v206
	ds_read_b128 v[130:133], v142
	ds_read_b128 v[134:137], v142 offset:1024
	ds_read_b128 v[138:141], v142 offset:2048
	ds_read_b128 v[142:145], v142 offset:3072
	ds_read_b128 v[146:149], v158
	ds_read_b128 v[150:153], v158 offset:1024
	ds_read_b128 v[154:157], v158 offset:2048
	ds_read_b128 v[158:161], v158 offset:3072
	s_add_u32 s52, s52, 0x80000
	s_addc_u32 s53, s53, 0
	s_mov_b32 m0, s64
	ds_read_b128 v[162:165], v210 offset:32768
	ds_read_b128 v[166:169], v210 offset:33792
	ds_read_b128 v[170:173], v210 offset:34816
	ds_read_b128 v[174:177], v210 offset:35840
	ds_read_b128 v[194:197], v210 offset:36864
	ds_read_b128 v[198:201], v210 offset:37888
	ds_read_b128 v[202:205], v210 offset:38912
	ds_read_b128 v[212:215], v210 offset:39936
	global_load_lds_dwordx4 v178, s[52:53]
	s_mov_b32 m0, s65
	s_nop 0
	global_load_lds_dwordx4 v182, s[52:53]
	s_waitcnt vmcnt(8)
	s_waitcnt lgkmcnt(0)
	s_barrier
	v_mfma_f32_16x16x32_bf16 v[126:129], v[130:133], v[162:165], v[126:129]
	v_mfma_f32_16x16x32_bf16 v[122:125], v[138:141], v[162:165], v[122:125]
	v_mfma_f32_16x16x32_bf16 v[110:113], v[130:133], v[170:173], v[110:113]
	v_mfma_f32_16x16x32_bf16 v[106:109], v[138:141], v[170:173], v[106:109]
	v_mfma_f32_16x16x32_bf16 v[94:97], v[130:133], v[194:197], v[94:97]
	v_mfma_f32_16x16x32_bf16 v[90:93], v[138:141], v[194:197], v[90:93]
	v_mfma_f32_16x16x32_bf16 v[78:81], v[130:133], v[202:205], v[78:81]
	v_mfma_f32_16x16x32_bf16 v[74:77], v[138:141], v[202:205], v[74:77]
	v_mfma_f32_16x16x32_bf16 v[126:129], v[134:137], v[166:169], v[126:129]
	v_mfma_f32_16x16x32_bf16 v[122:125], v[142:145], v[166:169], v[122:125]
	v_mfma_f32_16x16x32_bf16 v[110:113], v[134:137], v[174:177], v[110:113]
	v_mfma_f32_16x16x32_bf16 v[106:109], v[142:145], v[174:177], v[106:109]
	v_mfma_f32_16x16x32_bf16 v[94:97], v[134:137], v[198:201], v[94:97]
	v_mfma_f32_16x16x32_bf16 v[90:93], v[142:145], v[198:201], v[90:93]
	v_mfma_f32_16x16x32_bf16 v[78:81], v[134:137], v[212:215], v[78:81]
	v_mfma_f32_16x16x32_bf16 v[74:77], v[142:145], v[212:215], v[74:77]
	v_mfma_f32_16x16x32_bf16 v[118:121], v[146:149], v[162:165], v[118:121]
	v_mfma_f32_16x16x32_bf16 v[114:117], v[154:157], v[162:165], v[114:117]
	v_mfma_f32_16x16x32_bf16 v[102:105], v[146:149], v[170:173], v[102:105]
	v_mfma_f32_16x16x32_bf16 v[98:101], v[154:157], v[170:173], v[98:101]
	v_mfma_f32_16x16x32_bf16 v[86:89], v[146:149], v[194:197], v[86:89]
	v_mfma_f32_16x16x32_bf16 v[82:85], v[154:157], v[194:197], v[82:85]
	v_mfma_f32_16x16x32_bf16 v[70:73], v[146:149], v[202:205], v[70:73]
	v_mfma_f32_16x16x32_bf16 v[66:69], v[154:157], v[202:205], v[66:69]
	v_mfma_f32_16x16x32_bf16 v[118:121], v[150:153], v[166:169], v[118:121]
	v_mfma_f32_16x16x32_bf16 v[114:117], v[158:161], v[166:169], v[114:117]
	v_mfma_f32_16x16x32_bf16 v[102:105], v[150:153], v[174:177], v[102:105]
	v_mfma_f32_16x16x32_bf16 v[98:101], v[158:161], v[174:177], v[98:101]
	v_mfma_f32_16x16x32_bf16 v[86:89], v[150:153], v[198:201], v[86:89]
	v_mfma_f32_16x16x32_bf16 v[82:85], v[158:161], v[198:201], v[82:85]
	v_mfma_f32_16x16x32_bf16 v[70:73], v[150:153], v[212:215], v[70:73]
	v_mfma_f32_16x16x32_bf16 v[66:69], v[158:161], v[212:215], v[66:69]
	s_barrier
; #define PG8_STAGE(bufoff, gbase, voff) do { _Pragma("unroll") for (int _i = 0; _i < 2; ++_i) \
;         __builtin_amdgcn_global_load_lds((const unsigned*)((const char*)(gbase) + (voff)[_i]), (PG8_LAS unsigned*)(lds + (bufoff) + ldsw + _i * 8192), 16, 0, 0); } while (0)
; #define PG8_LDA(dst, b, h) do { _Pragma("unroll") for (int m = 0; m < 4; ++m) _Pragma("unroll") for (int k = 0; k < 2; ++k) dst[m][k] = *(const PG8_LAS bf16x8*)(lds + PG8_SA(b, h) + aoff + m * 2048 + k * 1024); } while (0)
; #define PG8_LDB(dst, b, h) do { _Pragma("unroll") for (int n = 0; n < 2; ++n) _Pragma("unroll") for (int k = 0; k < 2; ++k) dst[n][k] = *(const PG8_LAS bf16x8*)(lds + PG8_SB(b, h) + boff + n * 2048 + k * 1024); } while (0)
; #define PG8_MMA(ai, bj, At, Bt) do { __builtin_amdgcn_s_setprio(1); _Pragma("unroll") for (int m = 0; m < 4; ++m) _Pragma("unroll") for (int n = 0; n < 2; ++n) _Pragma("unroll") for (int k = 0; k < 2; ++k) \
;         acc[ai][bj][m][n] = __builtin_amdgcn_mfma_f32_16x16x32_bf16(Bt[n][k], At[m][k], acc[ai][bj][m][n], 0, 0, 0); __builtin_amdgcn_s_setprio(0); } while (0)
; #define PG8_WAIT_V(n) asm volatile("s_waitcnt vmcnt(" #n ")" ::: "memory")
; template <class Epi, class Sched, bool ALIGN_EPI = false, bool SP2 = false>
; __device__ __forceinline__ void gemm_phase(PG8_LAS unsigned char* lds, const Gemm g, const Sched& S, const Epi& E) {
;     ...
;             PG8_LDB(B0, 0, 0); PG8_LDB(B1, 0, 1); PG8_SCHED; PG8_LDA(At, 0, 0); PG8_STAGE(PG8_SA(1, 1), a1 + hA, voffA);
;             PG8_WAIT_V(8); PG8_WAIT_L(0); PG8_BAR; PG8_MMA(0, 0, At, B0); PG8_MMA(0, 1, At, B1); PG8_BAR; PG8_SCHED;
;             PG8_LDA(At, 0, 1); PG8_STAGE(PG8_SB(0, 0), b2, voffB); PG8_STAGE(PG8_SB(0, 1), b2 + hB, voffB); PG8_STAGE(PG8_SA(0, 0), a2, voffA);
;             PG8_WAIT_V(8); PG8_WAIT_L(0); PG8_BAR; PG8_MMA(1, 0, At, B0); PG8_MMA(1, 1, At, B1); PG8_BAR; PG8_SCHED;
;             PG8_LDB(B0, 1, 0); PG8_LDB(B1, 1, 1); PG8_SCHED; PG8_LDA(At, 1, 0); PG8_STAGE(PG8_SA(0, 1), a2 + hA, voffA);
;             PG8_WAIT_V(8); PG8_WAIT_L(0); PG8_BAR; PG8_MMA(0, 0, At, B0); PG8_MMA(0, 1, At, B1); PG8_BAR; PG8_SCHED;
;             PG8_LDA(At, 1, 1); PG8_STAGE(PG8_SB(1, 0), b3, voffB); PG8_STAGE(PG8_SB(1, 1), b3 + hB, voffB); PG8_STAGE(PG8_SA(1, 0), a3, voffA);
;             PG8_WAIT_V(8); PG8_WAIT_L(0); PG8_BAR; PG8_MMA(1, 0, At, B0); PG8_MMA(1, 1, At, B1); PG8_BAR; PG8_SCHED;
	s_add_i32 s18, s18, s61
	s_mov_b32 m0, s18
	ds_read_b128 v[162:165], v210 offset:49152
	ds_read_b128 v[166:169], v210 offset:50176
	ds_read_b128 v[170:173], v210 offset:51200
	ds_read_b128 v[174:177], v210 offset:52224
	ds_read_b128 v[194:197], v210 offset:53248
	ds_read_b128 v[198:201], v210 offset:54272
	ds_read_b128 v[202:205], v210 offset:55296
	ds_read_b128 v[212:215], v210 offset:56320
	global_load_lds_dwordx4 v180, s[82:83]
	s_add_i32 m0, s18, 0x2000
	s_add_u32 s50, s50, 0x80080
	s_addc_u32 s51, s51, 0
	s_add_i32 s18, s19, s61
	global_load_lds_dwordx4 v184, s[82:83]
	s_mov_b32 m0, s18
	s_nop 0
	global_load_lds_dwordx4 v180, s[50:51]
	s_add_i32 m0, s18, 0x2000
	s_nop 0
	global_load_lds_dwordx4 v184, s[50:51]
	s_mov_b32 m0, s69
	s_nop 0
	global_load_lds_dwordx4 v178, s[88:89]
	s_mov_b32 m0, s70
	s_nop 0
	global_load_lds_dwordx4 v182, s[88:89]
	s_waitcnt vmcnt(8)
	s_waitcnt lgkmcnt(0)
	s_barrier
	v_mfma_f32_16x16x32_bf16 v[62:65], v[130:133], v[162:165], v[62:65]
	v_mfma_f32_16x16x32_bf16 v[58:61], v[138:141], v[162:165], v[58:61]
	v_mfma_f32_16x16x32_bf16 v[46:49], v[130:133], v[170:173], v[46:49]
	v_mfma_f32_16x16x32_bf16 v[42:45], v[138:141], v[170:173], v[42:45]
	v_mfma_f32_16x16x32_bf16 v[30:33], v[130:133], v[194:197], v[30:33]
	v_mfma_f32_16x16x32_bf16 v[26:29], v[138:141], v[194:197], v[26:29]
	v_mfma_f32_16x16x32_bf16 v[14:17], v[130:133], v[202:205], v[14:17]
	v_mfma_f32_16x16x32_bf16 v[10:13], v[138:141], v[202:205], v[10:13]
	v_mfma_f32_16x16x32_bf16 v[62:65], v[134:137], v[166:169], v[62:65]
	v_mfma_f32_16x16x32_bf16 v[58:61], v[142:145], v[166:169], v[58:61]
	v_mfma_f32_16x16x32_bf16 v[46:49], v[134:137], v[174:177], v[46:49]
	v_mfma_f32_16x16x32_bf16 v[42:45], v[142:145], v[174:177], v[42:45]
	v_mfma_f32_16x16x32_bf16 v[30:33], v[134:137], v[198:201], v[30:33]
	v_mfma_f32_16x16x32_bf16 v[26:29], v[142:145], v[198:201], v[26:29]
	v_mfma_f32_16x16x32_bf16 v[14:17], v[134:137], v[212:215], v[14:17]
	v_mfma_f32_16x16x32_bf16 v[10:13], v[142:145], v[212:215], v[10:13]
	v_mfma_f32_16x16x32_bf16 v[54:57], v[146:149], v[162:165], v[54:57]
	v_mfma_f32_16x16x32_bf16 v[50:53], v[154:157], v[162:165], v[50:53]
	v_mfma_f32_16x16x32_bf16 v[38:41], v[146:149], v[170:173], v[38:41]
	v_mfma_f32_16x16x32_bf16 v[34:37], v[154:157], v[170:173], v[34:37]
	v_mfma_f32_16x16x32_bf16 v[22:25], v[146:149], v[194:197], v[22:25]
	v_mfma_f32_16x16x32_bf16 v[18:21], v[154:157], v[194:197], v[18:21]
	v_mfma_f32_16x16x32_bf16 v[6:9], v[146:149], v[202:205], v[6:9]
	v_mfma_f32_16x16x32_bf16 v[2:5], v[154:157], v[202:205], v[2:5]
	v_mfma_f32_16x16x32_bf16 v[54:57], v[150:153], v[166:169], v[54:57]
	v_mfma_f32_16x16x32_bf16 v[50:53], v[158:161], v[166:169], v[50:53]
	v_mfma_f32_16x16x32_bf16 v[38:41], v[150:153], v[174:177], v[38:41]
	v_mfma_f32_16x16x32_bf16 v[34:37], v[158:161], v[174:177], v[34:37]
	v_mfma_f32_16x16x32_bf16 v[22:25], v[150:153], v[198:201], v[22:25]
	v_mfma_f32_16x16x32_bf16 v[18:21], v[158:161], v[198:201], v[18:21]
	v_mfma_f32_16x16x32_bf16 v[6:9], v[150:153], v[212:215], v[6:9]
	v_mfma_f32_16x16x32_bf16 v[2:5], v[158:161], v[212:215], v[2:5]
	s_barrier
	s_add_i32 s78, s78, 2
	s_add_u32 s48, s48, 0x100
	s_addc_u32 s49, s49, 0
	s_add_u32 s76, s76, 0x100
	s_addc_u32 s77, s77, 0
	s_cmp_gt_u32 s78, 29
.LBB0_963:
	ds_read_b128 v[130:133], v208
	ds_read_b128 v[134:137], v208 offset:1024
	ds_read_b128 v[138:141], v208 offset:2048
	ds_read_b128 v[142:145], v208 offset:3072
	ds_read_b128 v[146:149], v209
	ds_read_b128 v[150:153], v209 offset:1024
	ds_read_b128 v[154:157], v209 offset:2048
	ds_read_b128 v[158:161], v209 offset:3072
	s_add_u32 s18, s48, 0xfff80080
	s_addc_u32 s19, s49, -1
	s_cmp_eq_u32 s78, 28
	s_cselect_b32 s53, s41, s19
	s_cselect_b32 s52, s47, s18
	s_cselect_b32 s51, s39, s77
	s_cselect_b32 s50, s75, s76
	s_add_i32 m0, s62, 0xc000
	ds_read_b128 v[162:165], v210
	ds_read_b128 v[166:169], v210 offset:1024
	ds_read_b128 v[170:173], v210 offset:2048
	ds_read_b128 v[174:177], v210 offset:3072
	ds_read_b128 v[194:197], v210 offset:4096
	ds_read_b128 v[198:201], v210 offset:5120
	ds_read_b128 v[202:205], v210 offset:6144
	ds_read_b128 v[212:215], v210 offset:7168
	global_load_lds_dwordx4 v186, s[48:49]
	s_add_i32 m0, s62, 0xe000
	s_nop 0
	global_load_lds_dwordx4 v188, s[48:49]
	s_waitcnt vmcnt(8)
	s_waitcnt lgkmcnt(0)
	s_barrier
	v_mfma_f32_16x16x32_bf16 v[126:129], v[130:133], v[162:165], v[126:129]
	v_mfma_f32_16x16x32_bf16 v[122:125], v[138:141], v[162:165], v[122:125]
	v_mfma_f32_16x16x32_bf16 v[110:113], v[130:133], v[170:173], v[110:113]
	v_mfma_f32_16x16x32_bf16 v[106:109], v[138:141], v[170:173], v[106:109]
	v_mfma_f32_16x16x32_bf16 v[94:97], v[130:133], v[194:197], v[94:97]
	v_mfma_f32_16x16x32_bf16 v[90:93], v[138:141], v[194:197], v[90:93]
	v_mfma_f32_16x16x32_bf16 v[78:81], v[130:133], v[202:205], v[78:81]
	v_mfma_f32_16x16x32_bf16 v[74:77], v[138:141], v[202:205], v[74:77]
	v_mfma_f32_16x16x32_bf16 v[126:129], v[134:137], v[166:169], v[126:129]
	v_mfma_f32_16x16x32_bf16 v[122:125], v[142:145], v[166:169], v[122:125]
	v_mfma_f32_16x16x32_bf16 v[110:113], v[134:137], v[174:177], v[110:113]
	v_mfma_f32_16x16x32_bf16 v[106:109], v[142:145], v[174:177], v[106:109]
	v_mfma_f32_16x16x32_bf16 v[94:97], v[134:137], v[198:201], v[94:97]
	v_mfma_f32_16x16x32_bf16 v[90:93], v[142:145], v[198:201], v[90:93]
	v_mfma_f32_16x16x32_bf16 v[78:81], v[134:137], v[212:215], v[78:81]
	v_mfma_f32_16x16x32_bf16 v[74:77], v[142:145], v[212:215], v[74:77]
	v_mfma_f32_16x16x32_bf16 v[118:121], v[146:149], v[162:165], v[118:121]
	v_mfma_f32_16x16x32_bf16 v[114:117], v[154:157], v[162:165], v[114:117]
	v_mfma_f32_16x16x32_bf16 v[102:105], v[146:149], v[170:173], v[102:105]
	v_mfma_f32_16x16x32_bf16 v[98:101], v[154:157], v[170:173], v[98:101]
	v_mfma_f32_16x16x32_bf16 v[86:89], v[146:149], v[194:197], v[86:89]
	v_mfma_f32_16x16x32_bf16 v[82:85], v[154:157], v[194:197], v[82:85]
	v_mfma_f32_16x16x32_bf16 v[70:73], v[146:149], v[202:205], v[70:73]
	v_mfma_f32_16x16x32_bf16 v[66:69], v[154:157], v[202:205], v[66:69]
	v_mfma_f32_16x16x32_bf16 v[118:121], v[150:153], v[166:169], v[118:121]
	v_mfma_f32_16x16x32_bf16 v[114:117], v[158:161], v[166:169], v[114:117]
	v_mfma_f32_16x16x32_bf16 v[102:105], v[150:153], v[174:177], v[102:105]
	v_mfma_f32_16x16x32_bf16 v[98:101], v[158:161], v[174:177], v[98:101]
	v_mfma_f32_16x16x32_bf16 v[86:89], v[150:153], v[198:201], v[86:89]
	v_mfma_f32_16x16x32_bf16 v[82:85], v[158:161], v[198:201], v[82:85]
	v_mfma_f32_16x16x32_bf16 v[70:73], v[150:153], v[212:215], v[70:73]
	v_mfma_f32_16x16x32_bf16 v[66:69], v[158:161], v[212:215], v[66:69]
	s_barrier
; #define PG8_STAGE(bufoff, gbase, voff) do { _Pragma("unroll") for (int _i = 0; _i < 2; ++_i) \
;         __builtin_amdgcn_global_load_lds((const unsigned*)((const char*)(gbase) + (voff)[_i]), (PG8_LAS unsigned*)(lds + (bufoff) + ldsw + _i * 8192), 16, 0, 0); } while (0)
; #define PG8_LDA(dst, b, h) do { _Pragma("unroll") for (int m = 0; m < 4; ++m) _Pragma("unroll") for (int k = 0; k < 2; ++k) dst[m][k] = *(const PG8_LAS bf16x8*)(lds + PG8_SA(b, h) + aoff + m * 2048 + k * 1024); } while (0)
; #define PG8_LDB(dst, b, h) do { _Pragma("unroll") for (int n = 0; n < 2; ++n) _Pragma("unroll") for (int k = 0; k < 2; ++k) dst[n][k] = *(const PG8_LAS bf16x8*)(lds + PG8_SB(b, h) + boff + n * 2048 + k * 1024); } while (0)
; #define PG8_MMA(ai, bj, At, Bt) do { __builtin_amdgcn_s_setprio(1); _Pragma("unroll") for (int m = 0; m < 4; ++m) _Pragma("unroll") for (int n = 0; n < 2; ++n) _Pragma("unroll") for (int k = 0; k < 2; ++k) \
;         acc[ai][bj][m][n] = __builtin_amdgcn_mfma_f32_16x16x32_bf16(Bt[n][k], At[m][k], acc[ai][bj][m][n], 0, 0, 0); __builtin_amdgcn_s_setprio(0); } while (0)
; #define PG8_WAIT_V(n) asm volatile("s_waitcnt vmcnt(" #n ")" ::: "memory")
; #define PG8_WAIT_L(n) asm volatile("s_waitcnt lgkmcnt(" #n ")" ::: "memory")
; #define PG8_BAR __builtin_amdgcn_s_barrier()
; #define PG8_SCHED __builtin_amdgcn_sched_barrier(0)
; template <class Epi, class Sched, bool ALIGN_EPI = false, bool SP2 = false>
; __device__ __forceinline__ void gemm_phase(PG8_LAS unsigned char* lds, const Gemm g, const Sched& S, const Epi& E) {
;     ...
;             PG8_LDA(At, 0, 1); PG8_STAGE(PG8_SB(0, 0), b2, voffB); PG8_STAGE(PG8_SB(0, 1), b2 + hB, voffB); PG8_STAGE(PG8_SA(0, 0), a2, voffA);
;             PG8_WAIT_V(8); PG8_WAIT_L(0); PG8_BAR; PG8_MMA(1, 0, At, B0); PG8_MMA(1, 1, At, B1); PG8_BAR; PG8_SCHED;
;             PG8_LDB(B0, 1, 0); PG8_LDB(B1, 1, 1); PG8_SCHED; PG8_LDA(At, 1, 0); PG8_STAGE(PG8_SA(0, 1), a2 + hA, voffA);
;             PG8_WAIT_V(8); PG8_WAIT_L(0); PG8_BAR; PG8_MMA(0, 0, At, B0); PG8_MMA(0, 1, At, B1); PG8_BAR; PG8_SCHED;
	s_add_i32 s18, s72, s61
	s_add_u32 s82, s50, s22
	s_addc_u32 s83, s51, s23
	s_mov_b32 m0, s18
	ds_read_b128 v[162:165], v210 offset:16384
	ds_read_b128 v[166:169], v210 offset:17408
	ds_read_b128 v[170:173], v210 offset:18432
	ds_read_b128 v[174:177], v210 offset:19456
	ds_read_b128 v[194:197], v210 offset:20480
	ds_read_b128 v[198:201], v210 offset:21504
	ds_read_b128 v[202:205], v210 offset:22528
	ds_read_b128 v[212:215], v210 offset:23552
	global_load_lds_dwordx4 v180, s[50:51]
	s_add_i32 m0, s18, 0x2000
	s_add_u32 s80, s50, 0x80000
	s_addc_u32 s81, s51, 0
	s_add_i32 s18, s73, s61
	global_load_lds_dwordx4 v184, s[50:51]
	s_mov_b32 m0, s18
	s_nop 0
	global_load_lds_dwordx4 v180, s[80:81]
	s_add_i32 m0, s18, 0x2000
	s_nop 0
	global_load_lds_dwordx4 v184, s[80:81]
	s_add_u32 s88, s52, s22
	s_addc_u32 s89, s53, s23
	s_mov_b32 m0, s62
	s_nop 0
	global_load_lds_dwordx4 v178, s[52:53]
	s_mov_b32 m0, s63
	s_nop 0
	global_load_lds_dwordx4 v182, s[52:53]
	s_waitcnt vmcnt(8)
	s_waitcnt lgkmcnt(0)
	s_barrier
	v_mfma_f32_16x16x32_bf16 v[62:65], v[130:133], v[162:165], v[62:65]
	v_mfma_f32_16x16x32_bf16 v[58:61], v[138:141], v[162:165], v[58:61]
	v_mfma_f32_16x16x32_bf16 v[46:49], v[130:133], v[170:173], v[46:49]
	v_mfma_f32_16x16x32_bf16 v[42:45], v[138:141], v[170:173], v[42:45]
	v_mfma_f32_16x16x32_bf16 v[30:33], v[130:133], v[194:197], v[30:33]
	v_mfma_f32_16x16x32_bf16 v[26:29], v[138:141], v[194:197], v[26:29]
	v_mfma_f32_16x16x32_bf16 v[14:17], v[130:133], v[202:205], v[14:17]
	v_mfma_f32_16x16x32_bf16 v[10:13], v[138:141], v[202:205], v[10:13]
	v_mfma_f32_16x16x32_bf16 v[62:65], v[134:137], v[166:169], v[62:65]
	v_mfma_f32_16x16x32_bf16 v[58:61], v[142:145], v[166:169], v[58:61]
	v_mfma_f32_16x16x32_bf16 v[46:49], v[134:137], v[174:177], v[46:49]
	v_mfma_f32_16x16x32_bf16 v[42:45], v[142:145], v[174:177], v[42:45]
	v_mfma_f32_16x16x32_bf16 v[30:33], v[134:137], v[198:201], v[30:33]
	v_mfma_f32_16x16x32_bf16 v[26:29], v[142:145], v[198:201], v[26:29]
	v_mfma_f32_16x16x32_bf16 v[14:17], v[134:137], v[212:215], v[14:17]
	v_mfma_f32_16x16x32_bf16 v[10:13], v[142:145], v[212:215], v[10:13]
	v_mfma_f32_16x16x32_bf16 v[54:57], v[146:149], v[162:165], v[54:57]
	v_mfma_f32_16x16x32_bf16 v[50:53], v[154:157], v[162:165], v[50:53]
	v_mfma_f32_16x16x32_bf16 v[38:41], v[146:149], v[170:173], v[38:41]
	v_mfma_f32_16x16x32_bf16 v[34:37], v[154:157], v[170:173], v[34:37]
	v_mfma_f32_16x16x32_bf16 v[22:25], v[146:149], v[194:197], v[22:25]
	v_mfma_f32_16x16x32_bf16 v[18:21], v[154:157], v[194:197], v[18:21]
	v_mfma_f32_16x16x32_bf16 v[6:9], v[146:149], v[202:205], v[6:9]
	v_mfma_f32_16x16x32_bf16 v[2:5], v[154:157], v[202:205], v[2:5]
	v_mfma_f32_16x16x32_bf16 v[54:57], v[150:153], v[166:169], v[54:57]
	v_mfma_f32_16x16x32_bf16 v[50:53], v[158:161], v[166:169], v[50:53]
	v_mfma_f32_16x16x32_bf16 v[38:41], v[150:153], v[174:177], v[38:41]
	v_mfma_f32_16x16x32_bf16 v[34:37], v[158:161], v[174:177], v[34:37]
	v_mfma_f32_16x16x32_bf16 v[22:25], v[150:153], v[198:201], v[22:25]
	v_mfma_f32_16x16x32_bf16 v[18:21], v[158:161], v[198:201], v[18:21]
	v_mfma_f32_16x16x32_bf16 v[6:9], v[150:153], v[212:215], v[6:9]
	v_mfma_f32_16x16x32_bf16 v[2:5], v[158:161], v[212:215], v[2:5]
	s_barrier
	s_add_i32 s18, 0, 0x18000
	s_add_i32 s19, 0, 0x1c000
	v_add_u32_e32 v142, s18, v206
	v_add_u32_e32 v158, s19, v206
	ds_read_b128 v[130:133], v142
	ds_read_b128 v[134:137], v142 offset:1024
	ds_read_b128 v[138:141], v142 offset:2048
	ds_read_b128 v[142:145], v142 offset:3072
	ds_read_b128 v[146:149], v158
	ds_read_b128 v[150:153], v158 offset:1024
	ds_read_b128 v[154:157], v158 offset:2048
	ds_read_b128 v[158:161], v158 offset:3072
	s_add_u32 s52, s52, 0x80000
	s_addc_u32 s53, s53, 0
	s_mov_b32 m0, s64
	ds_read_b128 v[162:165], v210 offset:32768
	ds_read_b128 v[166:169], v210 offset:33792
	ds_read_b128 v[170:173], v210 offset:34816
	ds_read_b128 v[174:177], v210 offset:35840
	ds_read_b128 v[194:197], v210 offset:36864
	ds_read_b128 v[198:201], v210 offset:37888
	ds_read_b128 v[202:205], v210 offset:38912
	ds_read_b128 v[212:215], v210 offset:39936
	global_load_lds_dwordx4 v178, s[52:53]
	s_mov_b32 m0, s65
	s_nop 0
	global_load_lds_dwordx4 v182, s[52:53]
	s_waitcnt vmcnt(8)
	s_waitcnt lgkmcnt(0)
	s_barrier
; #define PG8_STAGE(bufoff, gbase, voff) do { _Pragma("unroll") for (int _i = 0; _i < 2; ++_i) \
;         __builtin_amdgcn_global_load_lds((const unsigned*)((const char*)(gbase) + (voff)[_i]), (PG8_LAS unsigned*)(lds + (bufoff) + ldsw + _i * 8192), 16, 0, 0); } while (0)
; #define PG8_LDA(dst, b, h) do { _Pragma("unroll") for (int m = 0; m < 4; ++m) _Pragma("unroll") for (int k = 0; k < 2; ++k) dst[m][k] = *(const PG8_LAS bf16x8*)(lds + PG8_SA(b, h) + aoff + m * 2048 + k * 1024); } while (0)
; #define PG8_LDB(dst, b, h) do { _Pragma("unroll") for (int n = 0; n < 2; ++n) _Pragma("unroll") for (int k = 0; k < 2; ++k) dst[n][k] = *(const PG8_LAS bf16x8*)(lds + PG8_SB(b, h) + boff + n * 2048 + k * 1024); } while (0)
; #define PG8_MMA(ai, bj, At, Bt) do { __builtin_amdgcn_s_setprio(1); _Pragma("unroll") for (int m = 0; m < 4; ++m) _Pragma("unroll") for (int n = 0; n < 2; ++n) _Pragma("unroll") for (int k = 0; k < 2; ++k) \
;         acc[ai][bj][m][n] = __builtin_amdgcn_mfma_f32_16x16x32_bf16(Bt[n][k], At[m][k], acc[ai][bj][m][n], 0, 0, 0); __builtin_amdgcn_s_setprio(0); } while (0)
; #define PG8_WAIT_V(n) asm volatile("s_waitcnt vmcnt(" #n ")" ::: "memory")
; #define PG8_WAIT_L(n) asm volatile("s_waitcnt lgkmcnt(" #n ")" ::: "memory")
; #define PG8_BAR __builtin_amdgcn_s_barrier()
; #define PG8_SCHED __builtin_amdgcn_sched_barrier(0)
; template <class Epi, class Sched, bool ALIGN_EPI = false, bool SP2 = false>
; __device__ __forceinline__ void gemm_phase(PG8_LAS unsigned char* lds, const Gemm g, const Sched& S, const Epi& E) {
;     ...
;             PG8_LDB(B0, 1, 0); PG8_LDB(B1, 1, 1); PG8_SCHED; PG8_LDA(At, 1, 0); PG8_STAGE(PG8_SA(0, 1), a2 + hA, voffA);
;             PG8_WAIT_V(8); PG8_WAIT_L(0); PG8_BAR; PG8_MMA(0, 0, At, B0); PG8_MMA(0, 1, At, B1); PG8_BAR; PG8_SCHED;
;             PG8_LDA(At, 1, 1); PG8_STAGE(PG8_SB(1, 0), b3, voffB); PG8_STAGE(PG8_SB(1, 1), b3 + hB, voffB); PG8_STAGE(PG8_SA(1, 0), a3, voffA);
;             PG8_WAIT_V(8); PG8_WAIT_L(0); PG8_BAR; PG8_MMA(1, 0, At, B0); PG8_MMA(1, 1, At, B1); PG8_BAR; PG8_SCHED;
;     ...
;         if constexpr (ALIGN_EPI) { if (wr == 0) PG8_BAR; }
	v_mfma_f32_16x16x32_bf16 v[126:129], v[130:133], v[162:165], v[126:129]
	v_mfma_f32_16x16x32_bf16 v[122:125], v[138:141], v[162:165], v[122:125]
	v_mfma_f32_16x16x32_bf16 v[110:113], v[130:133], v[170:173], v[110:113]
	v_mfma_f32_16x16x32_bf16 v[106:109], v[138:141], v[170:173], v[106:109]
	v_mfma_f32_16x16x32_bf16 v[94:97], v[130:133], v[194:197], v[94:97]
	v_mfma_f32_16x16x32_bf16 v[90:93], v[138:141], v[194:197], v[90:93]
	v_mfma_f32_16x16x32_bf16 v[78:81], v[130:133], v[202:205], v[78:81]
	v_mfma_f32_16x16x32_bf16 v[74:77], v[138:141], v[202:205], v[74:77]
	v_mfma_f32_16x16x32_bf16 v[126:129], v[134:137], v[166:169], v[126:129]
	v_mfma_f32_16x16x32_bf16 v[122:125], v[142:145], v[166:169], v[122:125]
	v_mfma_f32_16x16x32_bf16 v[110:113], v[134:137], v[174:177], v[110:113]
	v_mfma_f32_16x16x32_bf16 v[106:109], v[142:145], v[174:177], v[106:109]
	v_mfma_f32_16x16x32_bf16 v[94:97], v[134:137], v[198:201], v[94:97]
	v_mfma_f32_16x16x32_bf16 v[90:93], v[142:145], v[198:201], v[90:93]
	v_mfma_f32_16x16x32_bf16 v[78:81], v[134:137], v[212:215], v[78:81]
	v_mfma_f32_16x16x32_bf16 v[74:77], v[142:145], v[212:215], v[74:77]
	v_mfma_f32_16x16x32_bf16 v[118:121], v[146:149], v[162:165], v[118:121]
	v_mfma_f32_16x16x32_bf16 v[114:117], v[154:157], v[162:165], v[114:117]
	v_mfma_f32_16x16x32_bf16 v[102:105], v[146:149], v[170:173], v[102:105]
	v_mfma_f32_16x16x32_bf16 v[98:101], v[154:157], v[170:173], v[98:101]
	v_mfma_f32_16x16x32_bf16 v[86:89], v[146:149], v[194:197], v[86:89]
	v_mfma_f32_16x16x32_bf16 v[82:85], v[154:157], v[194:197], v[82:85]
	v_mfma_f32_16x16x32_bf16 v[70:73], v[146:149], v[202:205], v[70:73]
	v_mfma_f32_16x16x32_bf16 v[66:69], v[154:157], v[202:205], v[66:69]
	v_mfma_f32_16x16x32_bf16 v[118:121], v[150:153], v[166:169], v[118:121]
	v_mfma_f32_16x16x32_bf16 v[114:117], v[158:161], v[166:169], v[114:117]
	v_mfma_f32_16x16x32_bf16 v[102:105], v[150:153], v[174:177], v[102:105]
	v_mfma_f32_16x16x32_bf16 v[98:101], v[158:161], v[174:177], v[98:101]
	v_mfma_f32_16x16x32_bf16 v[86:89], v[150:153], v[198:201], v[86:89]
	v_mfma_f32_16x16x32_bf16 v[82:85], v[158:161], v[198:201], v[82:85]
	v_mfma_f32_16x16x32_bf16 v[70:73], v[150:153], v[212:215], v[70:73]
	v_mfma_f32_16x16x32_bf16 v[66:69], v[158:161], v[212:215], v[66:69]
	s_barrier
	s_add_i32 s18, s18, s61
	s_mov_b32 m0, s18
	ds_read_b128 v[162:165], v210 offset:49152
	ds_read_b128 v[166:169], v210 offset:50176
	ds_read_b128 v[170:173], v210 offset:51200
	ds_read_b128 v[174:177], v210 offset:52224
	ds_read_b128 v[194:197], v210 offset:53248
	ds_read_b128 v[198:201], v210 offset:54272
	ds_read_b128 v[202:205], v210 offset:55296
	ds_read_b128 v[212:215], v210 offset:56320
	global_load_lds_dwordx4 v180, s[82:83]
	s_add_i32 m0, s18, 0x2000
	s_add_u32 s50, s50, 0x80080
	s_addc_u32 s51, s51, 0
	s_add_i32 s18, s19, s61
	global_load_lds_dwordx4 v184, s[82:83]
	s_mov_b32 m0, s18
	s_nop 0
	global_load_lds_dwordx4 v180, s[50:51]
	s_add_i32 m0, s18, 0x2000
	s_nop 0
	global_load_lds_dwordx4 v184, s[50:51]
	s_mov_b32 m0, s69
	s_nop 0
	global_load_lds_dwordx4 v178, s[88:89]
	s_mov_b32 m0, s70
	s_nop 0
	global_load_lds_dwordx4 v182, s[88:89]
	s_waitcnt vmcnt(8)
	s_waitcnt lgkmcnt(0)
	s_barrier
	v_mfma_f32_16x16x32_bf16 v[62:65], v[130:133], v[162:165], v[62:65]
	v_mfma_f32_16x16x32_bf16 v[58:61], v[138:141], v[162:165], v[58:61]
	v_mfma_f32_16x16x32_bf16 v[46:49], v[130:133], v[170:173], v[46:49]
	v_mfma_f32_16x16x32_bf16 v[42:45], v[138:141], v[170:173], v[42:45]
	v_mfma_f32_16x16x32_bf16 v[30:33], v[130:133], v[194:197], v[30:33]
	v_mfma_f32_16x16x32_bf16 v[26:29], v[138:141], v[194:197], v[26:29]
	v_mfma_f32_16x16x32_bf16 v[14:17], v[130:133], v[202:205], v[14:17]
	v_mfma_f32_16x16x32_bf16 v[10:13], v[138:141], v[202:205], v[10:13]
	v_mfma_f32_16x16x32_bf16 v[62:65], v[134:137], v[166:169], v[62:65]
	v_mfma_f32_16x16x32_bf16 v[58:61], v[142:145], v[166:169], v[58:61]
	v_mfma_f32_16x16x32_bf16 v[46:49], v[134:137], v[174:177], v[46:49]
	v_mfma_f32_16x16x32_bf16 v[42:45], v[142:145], v[174:177], v[42:45]
	v_mfma_f32_16x16x32_bf16 v[30:33], v[134:137], v[198:201], v[30:33]
	v_mfma_f32_16x16x32_bf16 v[26:29], v[142:145], v[198:201], v[26:29]
	v_mfma_f32_16x16x32_bf16 v[14:17], v[134:137], v[212:215], v[14:17]
	v_mfma_f32_16x16x32_bf16 v[10:13], v[142:145], v[212:215], v[10:13]
	v_mfma_f32_16x16x32_bf16 v[54:57], v[146:149], v[162:165], v[54:57]
	v_mfma_f32_16x16x32_bf16 v[50:53], v[154:157], v[162:165], v[50:53]
	v_mfma_f32_16x16x32_bf16 v[38:41], v[146:149], v[170:173], v[38:41]
	v_mfma_f32_16x16x32_bf16 v[34:37], v[154:157], v[170:173], v[34:37]
	v_mfma_f32_16x16x32_bf16 v[22:25], v[146:149], v[194:197], v[22:25]
	v_mfma_f32_16x16x32_bf16 v[18:21], v[154:157], v[194:197], v[18:21]
	v_mfma_f32_16x16x32_bf16 v[6:9], v[146:149], v[202:205], v[6:9]
	v_mfma_f32_16x16x32_bf16 v[2:5], v[154:157], v[202:205], v[2:5]
	v_mfma_f32_16x16x32_bf16 v[54:57], v[150:153], v[166:169], v[54:57]
	v_mfma_f32_16x16x32_bf16 v[50:53], v[158:161], v[166:169], v[50:53]
	v_mfma_f32_16x16x32_bf16 v[38:41], v[150:153], v[174:177], v[38:41]
	v_mfma_f32_16x16x32_bf16 v[34:37], v[158:161], v[174:177], v[34:37]
	v_mfma_f32_16x16x32_bf16 v[22:25], v[150:153], v[198:201], v[22:25]
	v_mfma_f32_16x16x32_bf16 v[18:21], v[158:161], v[198:201], v[18:21]
	v_mfma_f32_16x16x32_bf16 v[6:9], v[150:153], v[212:215], v[6:9]
	v_mfma_f32_16x16x32_bf16 v[2:5], v[158:161], v[212:215], v[2:5]
	s_barrier
	s_add_i32 s78, s78, 2
	s_add_u32 s48, s48, 0x100
	s_addc_u32 s49, s49, 0
	s_add_u32 s76, s76, 0x100
	s_addc_u32 s77, s77, 0
	s_cmp_gt_u32 s78, 29
	s_cbranch_scc0 .LBB0_963
	s_and_b64 vcc, exec, s[24:25]
	s_cbranch_vccz .LBB0_966
	s_barrier

; #define PG8_STAGE(bufoff, gbase, voff) do { _Pragma("unroll") for (int _i = 0; _i < 2; ++_i) \
;         __builtin_amdgcn_global_load_lds((const unsigned*)((const char*)(gbase) + (voff)[_i]), (PG8_LAS unsigned*)(lds + (bufoff) + ldsw + _i * 8192), 16, 0, 0); } while (0)
; #define PG8_LDA(dst, b, h) do { _Pragma("unroll") for (int m = 0; m < 4; ++m) _Pragma("unroll") for (int k = 0; k < 2; ++k) dst[m][k] = *(const PG8_LAS bf16x8*)(lds + PG8_SA(b, h) + aoff + m * 2048 + k * 1024); } while (0)
; #define PG8_LDB(dst, b, h) do { _Pragma("unroll") for (int n = 0; n < 2; ++n) _Pragma("unroll") for (int k = 0; k < 2; ++k) dst[n][k] = *(const PG8_LAS bf16x8*)(lds + PG8_SB(b, h) + boff + n * 2048 + k * 1024); } while (0)
; #define PG8_MMA(ai, bj, At, Bt) do { __builtin_amdgcn_s_setprio(1); _Pragma("unroll") for (int m = 0; m < 4; ++m) _Pragma("unroll") for (int n = 0; n < 2; ++n) _Pragma("unroll") for (int k = 0; k < 2; ++k) \
;         acc[ai][bj][m][n] = __builtin_amdgcn_mfma_f32_16x16x32_bf16(Bt[n][k], At[m][k], acc[ai][bj][m][n], 0, 0, 0); __builtin_amdgcn_s_setprio(0); } while (0)
; #define PG8_WAIT_V(n) asm volatile("s_waitcnt vmcnt(" #n ")" ::: "memory")
; #define PG8_BAR __builtin_amdgcn_s_barrier()
; template <class Epi, class Sched, bool ALIGN_EPI = false, bool SP2 = false>
; __device__ __forceinline__ void gemm_phase(PG8_LAS unsigned char* lds, const Gemm g, const Sched& S, const Epi& E) {
;     ...
;     for (;;) {
;         const bool has_next = S.next(ui + 1, nxt);
;         const char* nA = has_next ? (const char*)g.A + (size_t)nxt.pm * tA + (size_t)nxt.pn * pnA : cA; const char* nB = has_next ? (const char*)g.Bt + (size_t)nxt.pn * tB : cB;
; #pragma nounroll
;         for (int t = 0; t < nt; t += 2) {
;             const bool last = (t == nt - 2);
;             const char* a1 = cA + (size_t)(t + 1) * kstep;
;             const char* a2 = last ? nA : cA + (size_t)(t + 2) * kstep; const char* b2 = last ? nB : cB + (size_t)(t + 2) * kstep;
;             const char* a3 = a2 + kstep; const char* b3 = b2 + kstep;
;             if (last && has_next) S.a_ready(nxt);
;             if constexpr (SP2) {
;             PG8_LDB(B0, 0, 0); PG8_LDB(B1, 0, 1); PG8_SCHED; PG8_LDA(At, 0, 0); PG8_STAGE(PG8_SA(1, 1), a1 + hA, voffA);
;             PG8_WAIT_V(8); PG8_WAIT_L(0); PG8_BAR; PG8_MMA(0, 0, At, B0); PG8_MMA(0, 1, At, B1); PG8_BAR; PG8_SCHED;
.LBB0_1047:
	s_ashr_i32 s37, s36, 31
	s_lshl_b64 s[38:39], s[36:37], 20
	s_add_u32 s38, s33, s38
	s_addc_u32 s39, s46, s39
	s_and_b64 s[40:41], s[6:7], exec
	s_cselect_b32 s1, s39, s9
	s_cselect_b32 s37, s38, s8
	s_ashr_i32 s25, s24, 31
	s_lshl_b64 s[40:41], s[24:25], 20
	s_add_u32 s40, s47, s40
	s_addc_u32 s41, s48, s41
	s_and_b64 s[44:45], s[6:7], exec
	s_cselect_b32 s25, s41, s43
	s_cselect_b32 s69, s40, s42
	s_add_u32 s8, s8, 0x80080
	s_addc_u32 s9, s9, 0
	s_add_u32 s70, s42, 0x100
	v_mov_b32_e32 v2, 0
	s_addc_u32 s71, s43, 0
	s_mov_b32 s72, -2
	v_mov_b32_e32 v3, v2
	ds_read_b128 v[148:151], v169
	ds_read_b128 v[152:155], v169 offset:1024
	ds_read_b128 v[156:159], v169 offset:2048
	ds_read_b128 v[160:163], v169 offset:3072
	ds_read_b128 v[180:183], v171
	ds_read_b128 v[184:187], v171 offset:1024
	ds_read_b128 v[188:191], v171 offset:2048
	ds_read_b128 v[192:195], v171 offset:3072
	s_add_u32 s18, s8, 0xfff80080
	s_addc_u32 s19, s9, -1
	s_cmp_eq_u32 s72, 28
	s_cselect_b32 s45, s1, s19
	s_cselect_b32 s44, s37, s18
	s_cselect_b32 s43, s25, s71
	s_cselect_b32 s42, s69, s70
	s_add_i32 m0, s51, 0xc000
	ds_read_b128 v[196:199], v173
	ds_read_b128 v[200:203], v173 offset:1024
	ds_read_b128 v[204:207], v173 offset:2048
	ds_read_b128 v[208:211], v173 offset:3072
	ds_read_b128 v[212:215], v173 offset:4096
	ds_read_b128 v[216:219], v173 offset:5120
	ds_read_b128 v[224:227], v173 offset:6144
	ds_read_b128 v[228:231], v173 offset:7168
	global_load_lds_dwordx4 v140, s[8:9]
	s_add_i32 m0, s51, 0xe000
	s_nop 0
	global_load_lds_dwordx4 v142, s[8:9]
	s_waitcnt vmcnt(8)
	s_waitcnt lgkmcnt(0)
	s_barrier
	v_mfma_f32_16x16x32_bf16 v[126:129], v[148:151], v[196:199], 0
	v_mfma_f32_16x16x32_bf16 v[122:125], v[156:159], v[196:199], 0
	v_mfma_f32_16x16x32_bf16 v[110:113], v[148:151], v[204:207], 0
	v_mfma_f32_16x16x32_bf16 v[106:109], v[156:159], v[204:207], 0
	v_mfma_f32_16x16x32_bf16 v[94:97], v[148:151], v[212:215], 0
	v_mfma_f32_16x16x32_bf16 v[90:93], v[156:159], v[212:215], 0
	v_mfma_f32_16x16x32_bf16 v[78:81], v[148:151], v[224:227], 0
	v_mfma_f32_16x16x32_bf16 v[74:77], v[156:159], v[224:227], 0
	v_mfma_f32_16x16x32_bf16 v[126:129], v[152:155], v[200:203], v[126:129]
	v_mfma_f32_16x16x32_bf16 v[122:125], v[160:163], v[200:203], v[122:125]
	v_mfma_f32_16x16x32_bf16 v[110:113], v[152:155], v[208:211], v[110:113]
	v_mfma_f32_16x16x32_bf16 v[106:109], v[160:163], v[208:211], v[106:109]
	v_mfma_f32_16x16x32_bf16 v[94:97], v[152:155], v[216:219], v[94:97]
	v_mfma_f32_16x16x32_bf16 v[90:93], v[160:163], v[216:219], v[90:93]
	v_mfma_f32_16x16x32_bf16 v[78:81], v[152:155], v[228:231], v[78:81]
	v_mfma_f32_16x16x32_bf16 v[74:77], v[160:163], v[228:231], v[74:77]
	v_mfma_f32_16x16x32_bf16 v[118:121], v[180:183], v[196:199], 0
	v_mfma_f32_16x16x32_bf16 v[114:117], v[188:191], v[196:199], 0
	v_mfma_f32_16x16x32_bf16 v[102:105], v[180:183], v[204:207], 0
	v_mfma_f32_16x16x32_bf16 v[98:101], v[188:191], v[204:207], 0
	v_mfma_f32_16x16x32_bf16 v[86:89], v[180:183], v[212:215], 0
	v_mfma_f32_16x16x32_bf16 v[82:85], v[188:191], v[212:215], 0
	v_mfma_f32_16x16x32_bf16 v[70:73], v[180:183], v[224:227], 0
	v_mfma_f32_16x16x32_bf16 v[66:69], v[188:191], v[224:227], 0
	v_mfma_f32_16x16x32_bf16 v[118:121], v[184:187], v[200:203], v[118:121]
	v_mfma_f32_16x16x32_bf16 v[114:117], v[192:195], v[200:203], v[114:117]
	v_mfma_f32_16x16x32_bf16 v[102:105], v[184:187], v[208:211], v[102:105]
	v_mfma_f32_16x16x32_bf16 v[98:101], v[192:195], v[208:211], v[98:101]
	v_mfma_f32_16x16x32_bf16 v[86:89], v[184:187], v[216:219], v[86:89]
	v_mfma_f32_16x16x32_bf16 v[82:85], v[192:195], v[216:219], v[82:85]
	v_mfma_f32_16x16x32_bf16 v[70:73], v[184:187], v[228:231], v[70:73]
	v_mfma_f32_16x16x32_bf16 v[66:69], v[192:195], v[228:231], v[66:69]
	s_barrier
	s_add_i32 s18, s63, s49
	s_add_u32 s76, s42, s20
	s_addc_u32 s77, s43, s21
	s_mov_b32 m0, s18
	ds_read_b128 v[196:199], v173 offset:16384
	ds_read_b128 v[200:203], v173 offset:17408
	ds_read_b128 v[204:207], v173 offset:18432
	ds_read_b128 v[208:211], v173 offset:19456
	ds_read_b128 v[212:215], v173 offset:20480
	ds_read_b128 v[216:219], v173 offset:21504
	ds_read_b128 v[224:227], v173 offset:22528
	ds_read_b128 v[228:231], v173 offset:23552
	global_load_lds_dwordx4 v134, s[42:43]
	s_add_i32 m0, s18, 0x2000
	s_add_u32 s74, s42, 0x80000
	s_addc_u32 s75, s43, 0
	s_add_i32 s18, s64, s49
	global_load_lds_dwordx4 v130, s[42:43]
	s_mov_b32 m0, s18
	s_nop 0
	global_load_lds_dwordx4 v134, s[74:75]
	s_add_i32 m0, s18, 0x2000
	s_nop 0
	global_load_lds_dwordx4 v130, s[74:75]
	s_add_u32 s78, s44, s20
	s_addc_u32 s79, s45, s21
	s_mov_b32 m0, s51
	s_nop 0
	global_load_lds_dwordx4 v136, s[44:45]
	s_mov_b32 m0, s52
	s_nop 0
	global_load_lds_dwordx4 v132, s[44:45]
	s_waitcnt vmcnt(8)
	s_waitcnt lgkmcnt(0)
	s_barrier
; #define PG8_STAGE(bufoff, gbase, voff) do { _Pragma("unroll") for (int _i = 0; _i < 2; ++_i) \
;         __builtin_amdgcn_global_load_lds((const unsigned*)((const char*)(gbase) + (voff)[_i]), (PG8_LAS unsigned*)(lds + (bufoff) + ldsw + _i * 8192), 16, 0, 0); } while (0)
; #define PG8_LDA(dst, b, h) do { _Pragma("unroll") for (int m = 0; m < 4; ++m) _Pragma("unroll") for (int k = 0; k < 2; ++k) dst[m][k] = *(const PG8_LAS bf16x8*)(lds + PG8_SA(b, h) + aoff + m * 2048 + k * 1024); } while (0)
; #define PG8_LDB(dst, b, h) do { _Pragma("unroll") for (int n = 0; n < 2; ++n) _Pragma("unroll") for (int k = 0; k < 2; ++k) dst[n][k] = *(const PG8_LAS bf16x8*)(lds + PG8_SB(b, h) + boff + n * 2048 + k * 1024); } while (0)
; #define PG8_MMA(ai, bj, At, Bt) do { __builtin_amdgcn_s_setprio(1); _Pragma("unroll") for (int m = 0; m < 4; ++m) _Pragma("unroll") for (int n = 0; n < 2; ++n) _Pragma("unroll") for (int k = 0; k < 2; ++k) \
;         acc[ai][bj][m][n] = __builtin_amdgcn_mfma_f32_16x16x32_bf16(Bt[n][k], At[m][k], acc[ai][bj][m][n], 0, 0, 0); __builtin_amdgcn_s_setprio(0); } while (0)
; #define PG8_WAIT_V(n) asm volatile("s_waitcnt vmcnt(" #n ")" ::: "memory")
; #define PG8_WAIT_L(n) asm volatile("s_waitcnt lgkmcnt(" #n ")" ::: "memory")
; #define PG8_BAR __builtin_amdgcn_s_barrier()
; #define PG8_SCHED __builtin_amdgcn_sched_barrier(0)
; template <class Epi, class Sched, bool ALIGN_EPI = false, bool SP2 = false>
; __device__ __forceinline__ void gemm_phase(PG8_LAS unsigned char* lds, const Gemm g, const Sched& S, const Epi& E) {
;     ...
;             PG8_LDA(At, 0, 1); PG8_STAGE(PG8_SB(0, 0), b2, voffB); PG8_STAGE(PG8_SB(0, 1), b2 + hB, voffB); PG8_STAGE(PG8_SA(0, 0), a2, voffA);
;             PG8_WAIT_V(8); PG8_WAIT_L(0); PG8_BAR; PG8_MMA(1, 0, At, B0); PG8_MMA(1, 1, At, B1); PG8_BAR; PG8_SCHED;
;             PG8_LDB(B0, 1, 0); PG8_LDB(B1, 1, 1); PG8_SCHED; PG8_LDA(At, 1, 0); PG8_STAGE(PG8_SA(0, 1), a2 + hA, voffA);
;             PG8_WAIT_V(8); PG8_WAIT_L(0); PG8_BAR; PG8_MMA(0, 0, At, B0); PG8_MMA(0, 1, At, B1); PG8_BAR; PG8_SCHED;
	v_mfma_f32_16x16x32_bf16 v[62:65], v[148:151], v[196:199], 0
	v_mfma_f32_16x16x32_bf16 v[58:61], v[156:159], v[196:199], 0
	v_mfma_f32_16x16x32_bf16 v[46:49], v[148:151], v[204:207], 0
	v_mfma_f32_16x16x32_bf16 v[42:45], v[156:159], v[204:207], 0
	v_mfma_f32_16x16x32_bf16 v[30:33], v[148:151], v[212:215], 0
	v_mfma_f32_16x16x32_bf16 v[26:29], v[156:159], v[212:215], 0
	v_mfma_f32_16x16x32_bf16 v[14:17], v[148:151], v[224:227], 0
	v_mfma_f32_16x16x32_bf16 v[10:13], v[156:159], v[224:227], 0
	v_mfma_f32_16x16x32_bf16 v[62:65], v[152:155], v[200:203], v[62:65]
	v_mfma_f32_16x16x32_bf16 v[58:61], v[160:163], v[200:203], v[58:61]
	v_mfma_f32_16x16x32_bf16 v[46:49], v[152:155], v[208:211], v[46:49]
	v_mfma_f32_16x16x32_bf16 v[42:45], v[160:163], v[208:211], v[42:45]
	v_mfma_f32_16x16x32_bf16 v[30:33], v[152:155], v[216:219], v[30:33]
	v_mfma_f32_16x16x32_bf16 v[26:29], v[160:163], v[216:219], v[26:29]
	v_mfma_f32_16x16x32_bf16 v[14:17], v[152:155], v[228:231], v[14:17]
	v_mfma_f32_16x16x32_bf16 v[10:13], v[160:163], v[228:231], v[10:13]
	v_mfma_f32_16x16x32_bf16 v[54:57], v[180:183], v[196:199], 0
	v_mfma_f32_16x16x32_bf16 v[50:53], v[188:191], v[196:199], 0
	v_mfma_f32_16x16x32_bf16 v[38:41], v[180:183], v[204:207], 0
	v_mfma_f32_16x16x32_bf16 v[34:37], v[188:191], v[204:207], 0
	v_mfma_f32_16x16x32_bf16 v[22:25], v[180:183], v[212:215], 0
	v_mfma_f32_16x16x32_bf16 v[18:21], v[188:191], v[212:215], 0
	v_mfma_f32_16x16x32_bf16 v[6:9], v[180:183], v[224:227], 0
	v_mfma_f32_16x16x32_bf16 v[2:5], v[188:191], v[224:227], 0
	v_mfma_f32_16x16x32_bf16 v[54:57], v[184:187], v[200:203], v[54:57]
	v_mfma_f32_16x16x32_bf16 v[50:53], v[192:195], v[200:203], v[50:53]
	v_mfma_f32_16x16x32_bf16 v[38:41], v[184:187], v[208:211], v[38:41]
	v_mfma_f32_16x16x32_bf16 v[34:37], v[192:195], v[208:211], v[34:37]
	v_mfma_f32_16x16x32_bf16 v[22:25], v[184:187], v[216:219], v[22:25]
	v_mfma_f32_16x16x32_bf16 v[18:21], v[192:195], v[216:219], v[18:21]
	v_mfma_f32_16x16x32_bf16 v[6:9], v[184:187], v[228:231], v[6:9]
	v_mfma_f32_16x16x32_bf16 v[2:5], v[192:195], v[228:231], v[2:5]
	s_barrier
	s_add_i32 s18, 0, 0x18000
	s_add_i32 s19, 0, 0x1c000
	v_add_u32_e32 v160, s18, v165
	v_add_u32_e32 v164, s19, v165
	ds_read_b128 v[148:151], v160
	ds_read_b128 v[152:155], v160 offset:1024
	ds_read_b128 v[156:159], v160 offset:2048
	ds_read_b128 v[160:163], v160 offset:3072
	ds_read_b128 v[180:183], v164
	ds_read_b128 v[184:187], v164 offset:1024
	ds_read_b128 v[188:191], v164 offset:2048
	ds_read_b128 v[192:195], v164 offset:3072
	s_add_u32 s44, s44, 0x80000
	s_addc_u32 s45, s45, 0
	s_mov_b32 m0, s53
	ds_read_b128 v[196:199], v173 offset:32768
	ds_read_b128 v[200:203], v173 offset:33792
	ds_read_b128 v[204:207], v173 offset:34816
	ds_read_b128 v[208:211], v173 offset:35840
	ds_read_b128 v[212:215], v173 offset:36864
	ds_read_b128 v[216:219], v173 offset:37888
	ds_read_b128 v[224:227], v173 offset:38912
	ds_read_b128 v[228:231], v173 offset:39936
	global_load_lds_dwordx4 v136, s[44:45]
	s_mov_b32 m0, s57
	s_nop 0
	global_load_lds_dwordx4 v132, s[44:45]
	s_waitcnt vmcnt(8)
	s_waitcnt lgkmcnt(0)
	s_barrier
	v_mfma_f32_16x16x32_bf16 v[126:129], v[148:151], v[196:199], v[126:129]
	v_mfma_f32_16x16x32_bf16 v[122:125], v[156:159], v[196:199], v[122:125]
	v_mfma_f32_16x16x32_bf16 v[110:113], v[148:151], v[204:207], v[110:113]
	v_mfma_f32_16x16x32_bf16 v[106:109], v[156:159], v[204:207], v[106:109]
	v_mfma_f32_16x16x32_bf16 v[94:97], v[148:151], v[212:215], v[94:97]
	v_mfma_f32_16x16x32_bf16 v[90:93], v[156:159], v[212:215], v[90:93]
	v_mfma_f32_16x16x32_bf16 v[78:81], v[148:151], v[224:227], v[78:81]
	v_mfma_f32_16x16x32_bf16 v[74:77], v[156:159], v[224:227], v[74:77]
	v_mfma_f32_16x16x32_bf16 v[126:129], v[152:155], v[200:203], v[126:129]
	v_mfma_f32_16x16x32_bf16 v[122:125], v[160:163], v[200:203], v[122:125]
	v_mfma_f32_16x16x32_bf16 v[110:113], v[152:155], v[208:211], v[110:113]
	v_mfma_f32_16x16x32_bf16 v[106:109], v[160:163], v[208:211], v[106:109]
	v_mfma_f32_16x16x32_bf16 v[94:97], v[152:155], v[216:219], v[94:97]
	v_mfma_f32_16x16x32_bf16 v[90:93], v[160:163], v[216:219], v[90:93]
	v_mfma_f32_16x16x32_bf16 v[78:81], v[152:155], v[228:231], v[78:81]
	v_mfma_f32_16x16x32_bf16 v[74:77], v[160:163], v[228:231], v[74:77]
	v_mfma_f32_16x16x32_bf16 v[118:121], v[180:183], v[196:199], v[118:121]
	v_mfma_f32_16x16x32_bf16 v[114:117], v[188:191], v[196:199], v[114:117]
	v_mfma_f32_16x16x32_bf16 v[102:105], v[180:183], v[204:207], v[102:105]
	v_mfma_f32_16x16x32_bf16 v[98:101], v[188:191], v[204:207], v[98:101]
	v_mfma_f32_16x16x32_bf16 v[86:89], v[180:183], v[212:215], v[86:89]
	v_mfma_f32_16x16x32_bf16 v[82:85], v[188:191], v[212:215], v[82:85]
	v_mfma_f32_16x16x32_bf16 v[70:73], v[180:183], v[224:227], v[70:73]
	v_mfma_f32_16x16x32_bf16 v[66:69], v[188:191], v[224:227], v[66:69]
	v_mfma_f32_16x16x32_bf16 v[118:121], v[184:187], v[200:203], v[118:121]
	v_mfma_f32_16x16x32_bf16 v[114:117], v[192:195], v[200:203], v[114:117]
	v_mfma_f32_16x16x32_bf16 v[102:105], v[184:187], v[208:211], v[102:105]
	v_mfma_f32_16x16x32_bf16 v[98:101], v[192:195], v[208:211], v[98:101]
	v_mfma_f32_16x16x32_bf16 v[86:89], v[184:187], v[216:219], v[86:89]
	v_mfma_f32_16x16x32_bf16 v[82:85], v[192:195], v[216:219], v[82:85]
	v_mfma_f32_16x16x32_bf16 v[70:73], v[184:187], v[228:231], v[70:73]
	v_mfma_f32_16x16x32_bf16 v[66:69], v[192:195], v[228:231], v[66:69]
	s_barrier
; #define PG8_STAGE(bufoff, gbase, voff) do { _Pragma("unroll") for (int _i = 0; _i < 2; ++_i) \
;         __builtin_amdgcn_global_load_lds((const unsigned*)((const char*)(gbase) + (voff)[_i]), (PG8_LAS unsigned*)(lds + (bufoff) + ldsw + _i * 8192), 16, 0, 0); } while (0)
; #define PG8_LDA(dst, b, h) do { _Pragma("unroll") for (int m = 0; m < 4; ++m) _Pragma("unroll") for (int k = 0; k < 2; ++k) dst[m][k] = *(const PG8_LAS bf16x8*)(lds + PG8_SA(b, h) + aoff + m * 2048 + k * 1024); } while (0)
; #define PG8_LDB(dst, b, h) do { _Pragma("unroll") for (int n = 0; n < 2; ++n) _Pragma("unroll") for (int k = 0; k < 2; ++k) dst[n][k] = *(const PG8_LAS bf16x8*)(lds + PG8_SB(b, h) + boff + n * 2048 + k * 1024); } while (0)
; #define PG8_MMA(ai, bj, At, Bt) do { __builtin_amdgcn_s_setprio(1); _Pragma("unroll") for (int m = 0; m < 4; ++m) _Pragma("unroll") for (int n = 0; n < 2; ++n) _Pragma("unroll") for (int k = 0; k < 2; ++k) \
;         acc[ai][bj][m][n] = __builtin_amdgcn_mfma_f32_16x16x32_bf16(Bt[n][k], At[m][k], acc[ai][bj][m][n], 0, 0, 0); __builtin_amdgcn_s_setprio(0); } while (0)
; #define PG8_WAIT_V(n) asm volatile("s_waitcnt vmcnt(" #n ")" ::: "memory")
; template <class Epi, class Sched, bool ALIGN_EPI = false, bool SP2 = false>
; __device__ __forceinline__ void gemm_phase(PG8_LAS unsigned char* lds, const Gemm g, const Sched& S, const Epi& E) {
;     ...
;             PG8_LDB(B0, 0, 0); PG8_LDB(B1, 0, 1); PG8_SCHED; PG8_LDA(At, 0, 0); PG8_STAGE(PG8_SA(1, 1), a1 + hA, voffA);
;             PG8_WAIT_V(8); PG8_WAIT_L(0); PG8_BAR; PG8_MMA(0, 0, At, B0); PG8_MMA(0, 1, At, B1); PG8_BAR; PG8_SCHED;
;             PG8_LDA(At, 0, 1); PG8_STAGE(PG8_SB(0, 0), b2, voffB); PG8_STAGE(PG8_SB(0, 1), b2 + hB, voffB); PG8_STAGE(PG8_SA(0, 0), a2, voffA);
;             PG8_WAIT_V(8); PG8_WAIT_L(0); PG8_BAR; PG8_MMA(1, 0, At, B0); PG8_MMA(1, 1, At, B1); PG8_BAR; PG8_SCHED;
;             PG8_LDB(B0, 1, 0); PG8_LDB(B1, 1, 1); PG8_SCHED; PG8_LDA(At, 1, 0); PG8_STAGE(PG8_SA(0, 1), a2 + hA, voffA);
;             PG8_WAIT_V(8); PG8_WAIT_L(0); PG8_BAR; PG8_MMA(0, 0, At, B0); PG8_MMA(0, 1, At, B1); PG8_BAR; PG8_SCHED;
;             PG8_LDA(At, 1, 1); PG8_STAGE(PG8_SB(1, 0), b3, voffB); PG8_STAGE(PG8_SB(1, 1), b3 + hB, voffB); PG8_STAGE(PG8_SA(1, 0), a3, voffA);
;             PG8_WAIT_V(8); PG8_WAIT_L(0); PG8_BAR; PG8_MMA(1, 0, At, B0); PG8_MMA(1, 1, At, B1); PG8_BAR; PG8_SCHED;
	s_add_i32 s18, s18, s49
	s_mov_b32 m0, s18
	ds_read_b128 v[196:199], v173 offset:49152
	ds_read_b128 v[200:203], v173 offset:50176
	ds_read_b128 v[204:207], v173 offset:51200
	ds_read_b128 v[208:211], v173 offset:52224
	ds_read_b128 v[212:215], v173 offset:53248
	ds_read_b128 v[216:219], v173 offset:54272
	ds_read_b128 v[224:227], v173 offset:55296
	ds_read_b128 v[228:231], v173 offset:56320
	global_load_lds_dwordx4 v134, s[76:77]
	s_add_i32 m0, s18, 0x2000
	s_add_u32 s42, s42, 0x80080
	s_addc_u32 s43, s43, 0
	s_add_i32 s18, s19, s49
	global_load_lds_dwordx4 v130, s[76:77]
	s_mov_b32 m0, s18
	s_nop 0
	global_load_lds_dwordx4 v134, s[42:43]
	s_add_i32 m0, s18, 0x2000
	s_nop 0
	global_load_lds_dwordx4 v130, s[42:43]
	s_mov_b32 m0, s60
	s_nop 0
	global_load_lds_dwordx4 v136, s[78:79]
	s_mov_b32 m0, s61
	s_nop 0
	global_load_lds_dwordx4 v132, s[78:79]
	s_waitcnt vmcnt(8)
	s_waitcnt lgkmcnt(0)
	s_barrier
	v_mfma_f32_16x16x32_bf16 v[62:65], v[148:151], v[196:199], v[62:65]
	v_mfma_f32_16x16x32_bf16 v[58:61], v[156:159], v[196:199], v[58:61]
	v_mfma_f32_16x16x32_bf16 v[46:49], v[148:151], v[204:207], v[46:49]
	v_mfma_f32_16x16x32_bf16 v[42:45], v[156:159], v[204:207], v[42:45]
	v_mfma_f32_16x16x32_bf16 v[30:33], v[148:151], v[212:215], v[30:33]
	v_mfma_f32_16x16x32_bf16 v[26:29], v[156:159], v[212:215], v[26:29]
	v_mfma_f32_16x16x32_bf16 v[14:17], v[148:151], v[224:227], v[14:17]
	v_mfma_f32_16x16x32_bf16 v[10:13], v[156:159], v[224:227], v[10:13]
	v_mfma_f32_16x16x32_bf16 v[62:65], v[152:155], v[200:203], v[62:65]
	v_mfma_f32_16x16x32_bf16 v[58:61], v[160:163], v[200:203], v[58:61]
	v_mfma_f32_16x16x32_bf16 v[46:49], v[152:155], v[208:211], v[46:49]
	v_mfma_f32_16x16x32_bf16 v[42:45], v[160:163], v[208:211], v[42:45]
	v_mfma_f32_16x16x32_bf16 v[30:33], v[152:155], v[216:219], v[30:33]
	v_mfma_f32_16x16x32_bf16 v[26:29], v[160:163], v[216:219], v[26:29]
	v_mfma_f32_16x16x32_bf16 v[14:17], v[152:155], v[228:231], v[14:17]
	v_mfma_f32_16x16x32_bf16 v[10:13], v[160:163], v[228:231], v[10:13]
	v_mfma_f32_16x16x32_bf16 v[54:57], v[180:183], v[196:199], v[54:57]
	v_mfma_f32_16x16x32_bf16 v[50:53], v[188:191], v[196:199], v[50:53]
	v_mfma_f32_16x16x32_bf16 v[38:41], v[180:183], v[204:207], v[38:41]
	v_mfma_f32_16x16x32_bf16 v[34:37], v[188:191], v[204:207], v[34:37]
	v_mfma_f32_16x16x32_bf16 v[22:25], v[180:183], v[212:215], v[22:25]
	v_mfma_f32_16x16x32_bf16 v[18:21], v[188:191], v[212:215], v[18:21]
	v_mfma_f32_16x16x32_bf16 v[6:9], v[180:183], v[224:227], v[6:9]
	v_mfma_f32_16x16x32_bf16 v[2:5], v[188:191], v[224:227], v[2:5]
	v_mfma_f32_16x16x32_bf16 v[54:57], v[184:187], v[200:203], v[54:57]
	v_mfma_f32_16x16x32_bf16 v[50:53], v[192:195], v[200:203], v[50:53]
	v_mfma_f32_16x16x32_bf16 v[38:41], v[184:187], v[208:211], v[38:41]
	v_mfma_f32_16x16x32_bf16 v[34:37], v[192:195], v[208:211], v[34:37]
	v_mfma_f32_16x16x32_bf16 v[22:25], v[184:187], v[216:219], v[22:25]
	v_mfma_f32_16x16x32_bf16 v[18:21], v[192:195], v[216:219], v[18:21]
	v_mfma_f32_16x16x32_bf16 v[6:9], v[184:187], v[228:231], v[6:9]
	v_mfma_f32_16x16x32_bf16 v[2:5], v[192:195], v[228:231], v[2:5]
	s_barrier
	s_add_i32 s72, s72, 2
	s_add_u32 s8, s8, 0x100
	s_addc_u32 s9, s9, 0
	s_add_u32 s70, s70, 0x100
	s_addc_u32 s71, s71, 0
	s_cmp_gt_u32 s72, 29
.LBB0_1048:
	ds_read_b128 v[148:151], v169
	ds_read_b128 v[152:155], v169 offset:1024
	ds_read_b128 v[156:159], v169 offset:2048
	ds_read_b128 v[160:163], v169 offset:3072
	ds_read_b128 v[180:183], v171
	ds_read_b128 v[184:187], v171 offset:1024
	ds_read_b128 v[188:191], v171 offset:2048
	ds_read_b128 v[192:195], v171 offset:3072
	s_add_u32 s18, s8, 0xfff80080
	s_addc_u32 s19, s9, -1
	s_cmp_eq_u32 s72, 28
	s_cselect_b32 s45, s1, s19
	s_cselect_b32 s44, s37, s18
	s_cselect_b32 s43, s25, s71
	s_cselect_b32 s42, s69, s70
	s_add_i32 m0, s51, 0xc000
	ds_read_b128 v[196:199], v173
	ds_read_b128 v[200:203], v173 offset:1024
	ds_read_b128 v[204:207], v173 offset:2048
	ds_read_b128 v[208:211], v173 offset:3072
	ds_read_b128 v[212:215], v173 offset:4096
	ds_read_b128 v[216:219], v173 offset:5120
	ds_read_b128 v[224:227], v173 offset:6144
	ds_read_b128 v[228:231], v173 offset:7168
	global_load_lds_dwordx4 v140, s[8:9]
	s_add_i32 m0, s51, 0xe000
	s_nop 0
	global_load_lds_dwordx4 v142, s[8:9]
	s_waitcnt vmcnt(8)
	s_waitcnt lgkmcnt(0)
	s_barrier
	v_mfma_f32_16x16x32_bf16 v[126:129], v[148:151], v[196:199], v[126:129]
	v_mfma_f32_16x16x32_bf16 v[122:125], v[156:159], v[196:199], v[122:125]
	v_mfma_f32_16x16x32_bf16 v[110:113], v[148:151], v[204:207], v[110:113]
	v_mfma_f32_16x16x32_bf16 v[106:109], v[156:159], v[204:207], v[106:109]
	v_mfma_f32_16x16x32_bf16 v[94:97], v[148:151], v[212:215], v[94:97]
	v_mfma_f32_16x16x32_bf16 v[90:93], v[156:159], v[212:215], v[90:93]
	v_mfma_f32_16x16x32_bf16 v[78:81], v[148:151], v[224:227], v[78:81]
	v_mfma_f32_16x16x32_bf16 v[74:77], v[156:159], v[224:227], v[74:77]
	v_mfma_f32_16x16x32_bf16 v[126:129], v[152:155], v[200:203], v[126:129]
	v_mfma_f32_16x16x32_bf16 v[122:125], v[160:163], v[200:203], v[122:125]
	v_mfma_f32_16x16x32_bf16 v[110:113], v[152:155], v[208:211], v[110:113]
	v_mfma_f32_16x16x32_bf16 v[106:109], v[160:163], v[208:211], v[106:109]
	v_mfma_f32_16x16x32_bf16 v[94:97], v[152:155], v[216:219], v[94:97]
	v_mfma_f32_16x16x32_bf16 v[90:93], v[160:163], v[216:219], v[90:93]
	v_mfma_f32_16x16x32_bf16 v[78:81], v[152:155], v[228:231], v[78:81]
	v_mfma_f32_16x16x32_bf16 v[74:77], v[160:163], v[228:231], v[74:77]
	v_mfma_f32_16x16x32_bf16 v[118:121], v[180:183], v[196:199], v[118:121]
	v_mfma_f32_16x16x32_bf16 v[114:117], v[188:191], v[196:199], v[114:117]
	v_mfma_f32_16x16x32_bf16 v[102:105], v[180:183], v[204:207], v[102:105]
	v_mfma_f32_16x16x32_bf16 v[98:101], v[188:191], v[204:207], v[98:101]
	v_mfma_f32_16x16x32_bf16 v[86:89], v[180:183], v[212:215], v[86:89]
	v_mfma_f32_16x16x32_bf16 v[82:85], v[188:191], v[212:215], v[82:85]
	v_mfma_f32_16x16x32_bf16 v[70:73], v[180:183], v[224:227], v[70:73]
	v_mfma_f32_16x16x32_bf16 v[66:69], v[188:191], v[224:227], v[66:69]
	v_mfma_f32_16x16x32_bf16 v[118:121], v[184:187], v[200:203], v[118:121]
	v_mfma_f32_16x16x32_bf16 v[114:117], v[192:195], v[200:203], v[114:117]
	v_mfma_f32_16x16x32_bf16 v[102:105], v[184:187], v[208:211], v[102:105]
	v_mfma_f32_16x16x32_bf16 v[98:101], v[192:195], v[208:211], v[98:101]
	v_mfma_f32_16x16x32_bf16 v[86:89], v[184:187], v[216:219], v[86:89]
	v_mfma_f32_16x16x32_bf16 v[82:85], v[192:195], v[216:219], v[82:85]
	v_mfma_f32_16x16x32_bf16 v[70:73], v[184:187], v[228:231], v[70:73]
	v_mfma_f32_16x16x32_bf16 v[66:69], v[192:195], v[228:231], v[66:69]
	s_barrier
; #define PG8_STAGE(bufoff, gbase, voff) do { _Pragma("unroll") for (int _i = 0; _i < 2; ++_i) \
;         __builtin_amdgcn_global_load_lds((const unsigned*)((const char*)(gbase) + (voff)[_i]), (PG8_LAS unsigned*)(lds + (bufoff) + ldsw + _i * 8192), 16, 0, 0); } while (0)
; #define PG8_LDA(dst, b, h) do { _Pragma("unroll") for (int m = 0; m < 4; ++m) _Pragma("unroll") for (int k = 0; k < 2; ++k) dst[m][k] = *(const PG8_LAS bf16x8*)(lds + PG8_SA(b, h) + aoff + m * 2048 + k * 1024); } while (0)
; #define PG8_LDB(dst, b, h) do { _Pragma("unroll") for (int n = 0; n < 2; ++n) _Pragma("unroll") for (int k = 0; k < 2; ++k) dst[n][k] = *(const PG8_LAS bf16x8*)(lds + PG8_SB(b, h) + boff + n * 2048 + k * 1024); } while (0)
; #define PG8_MMA(ai, bj, At, Bt) do { __builtin_amdgcn_s_setprio(1); _Pragma("unroll") for (int m = 0; m < 4; ++m) _Pragma("unroll") for (int n = 0; n < 2; ++n) _Pragma("unroll") for (int k = 0; k < 2; ++k) \
;         acc[ai][bj][m][n] = __builtin_amdgcn_mfma_f32_16x16x32_bf16(Bt[n][k], At[m][k], acc[ai][bj][m][n], 0, 0, 0); __builtin_amdgcn_s_setprio(0); } while (0)
; #define PG8_WAIT_V(n) asm volatile("s_waitcnt vmcnt(" #n ")" ::: "memory")
; #define PG8_WAIT_L(n) asm volatile("s_waitcnt lgkmcnt(" #n ")" ::: "memory")
; #define PG8_BAR __builtin_amdgcn_s_barrier()
; #define PG8_SCHED __builtin_amdgcn_sched_barrier(0)
; template <class Epi, class Sched, bool ALIGN_EPI = false, bool SP2 = false>
; __device__ __forceinline__ void gemm_phase(PG8_LAS unsigned char* lds, const Gemm g, const Sched& S, const Epi& E) {
;     ...
;             PG8_LDA(At, 0, 1); PG8_STAGE(PG8_SB(0, 0), b2, voffB); PG8_STAGE(PG8_SB(0, 1), b2 + hB, voffB); PG8_STAGE(PG8_SA(0, 0), a2, voffA);
;             PG8_WAIT_V(8); PG8_WAIT_L(0); PG8_BAR; PG8_MMA(1, 0, At, B0); PG8_MMA(1, 1, At, B1); PG8_BAR; PG8_SCHED;
;             PG8_LDB(B0, 1, 0); PG8_LDB(B1, 1, 1); PG8_SCHED; PG8_LDA(At, 1, 0); PG8_STAGE(PG8_SA(0, 1), a2 + hA, voffA);
;             PG8_WAIT_V(8); PG8_WAIT_L(0); PG8_BAR; PG8_MMA(0, 0, At, B0); PG8_MMA(0, 1, At, B1); PG8_BAR; PG8_SCHED;
	s_add_i32 s18, s63, s49
	s_add_u32 s76, s42, s20
	s_addc_u32 s77, s43, s21
	s_mov_b32 m0, s18
	ds_read_b128 v[196:199], v173 offset:16384
	ds_read_b128 v[200:203], v173 offset:17408
	ds_read_b128 v[204:207], v173 offset:18432
	ds_read_b128 v[208:211], v173 offset:19456
	ds_read_b128 v[212:215], v173 offset:20480
	ds_read_b128 v[216:219], v173 offset:21504
	ds_read_b128 v[224:227], v173 offset:22528
	ds_read_b128 v[228:231], v173 offset:23552
	global_load_lds_dwordx4 v134, s[42:43]
	s_add_i32 m0, s18, 0x2000
	s_add_u32 s74, s42, 0x80000
	s_addc_u32 s75, s43, 0
	s_add_i32 s18, s64, s49
	global_load_lds_dwordx4 v130, s[42:43]
	s_mov_b32 m0, s18
	s_nop 0
	global_load_lds_dwordx4 v134, s[74:75]
	s_add_i32 m0, s18, 0x2000
	s_nop 0
	global_load_lds_dwordx4 v130, s[74:75]
	s_add_u32 s78, s44, s20
	s_addc_u32 s79, s45, s21
	s_mov_b32 m0, s51
	s_nop 0
	global_load_lds_dwordx4 v136, s[44:45]
	s_mov_b32 m0, s52
	s_nop 0
	global_load_lds_dwordx4 v132, s[44:45]
	s_waitcnt vmcnt(8)
	s_waitcnt lgkmcnt(0)
	s_barrier
	v_mfma_f32_16x16x32_bf16 v[62:65], v[148:151], v[196:199], v[62:65]
	v_mfma_f32_16x16x32_bf16 v[58:61], v[156:159], v[196:199], v[58:61]
	v_mfma_f32_16x16x32_bf16 v[46:49], v[148:151], v[204:207], v[46:49]
	v_mfma_f32_16x16x32_bf16 v[42:45], v[156:159], v[204:207], v[42:45]
	v_mfma_f32_16x16x32_bf16 v[30:33], v[148:151], v[212:215], v[30:33]
	v_mfma_f32_16x16x32_bf16 v[26:29], v[156:159], v[212:215], v[26:29]
	v_mfma_f32_16x16x32_bf16 v[14:17], v[148:151], v[224:227], v[14:17]
	v_mfma_f32_16x16x32_bf16 v[10:13], v[156:159], v[224:227], v[10:13]
	v_mfma_f32_16x16x32_bf16 v[62:65], v[152:155], v[200:203], v[62:65]
	v_mfma_f32_16x16x32_bf16 v[58:61], v[160:163], v[200:203], v[58:61]
	v_mfma_f32_16x16x32_bf16 v[46:49], v[152:155], v[208:211], v[46:49]
	v_mfma_f32_16x16x32_bf16 v[42:45], v[160:163], v[208:211], v[42:45]
	v_mfma_f32_16x16x32_bf16 v[30:33], v[152:155], v[216:219], v[30:33]
	v_mfma_f32_16x16x32_bf16 v[26:29], v[160:163], v[216:219], v[26:29]
	v_mfma_f32_16x16x32_bf16 v[14:17], v[152:155], v[228:231], v[14:17]
	v_mfma_f32_16x16x32_bf16 v[10:13], v[160:163], v[228:231], v[10:13]
	v_mfma_f32_16x16x32_bf16 v[54:57], v[180:183], v[196:199], v[54:57]
	v_mfma_f32_16x16x32_bf16 v[50:53], v[188:191], v[196:199], v[50:53]
	v_mfma_f32_16x16x32_bf16 v[38:41], v[180:183], v[204:207], v[38:41]
	v_mfma_f32_16x16x32_bf16 v[34:37], v[188:191], v[204:207], v[34:37]
	v_mfma_f32_16x16x32_bf16 v[22:25], v[180:183], v[212:215], v[22:25]
	v_mfma_f32_16x16x32_bf16 v[18:21], v[188:191], v[212:215], v[18:21]
	v_mfma_f32_16x16x32_bf16 v[6:9], v[180:183], v[224:227], v[6:9]
	v_mfma_f32_16x16x32_bf16 v[2:5], v[188:191], v[224:227], v[2:5]
	v_mfma_f32_16x16x32_bf16 v[54:57], v[184:187], v[200:203], v[54:57]
	v_mfma_f32_16x16x32_bf16 v[50:53], v[192:195], v[200:203], v[50:53]
	v_mfma_f32_16x16x32_bf16 v[38:41], v[184:187], v[208:211], v[38:41]
	v_mfma_f32_16x16x32_bf16 v[34:37], v[192:195], v[208:211], v[34:37]
	v_mfma_f32_16x16x32_bf16 v[22:25], v[184:187], v[216:219], v[22:25]
	v_mfma_f32_16x16x32_bf16 v[18:21], v[192:195], v[216:219], v[18:21]
	v_mfma_f32_16x16x32_bf16 v[6:9], v[184:187], v[228:231], v[6:9]
	v_mfma_f32_16x16x32_bf16 v[2:5], v[192:195], v[228:231], v[2:5]
	s_barrier
	s_add_i32 s18, 0, 0x18000
	s_add_i32 s19, 0, 0x1c000
	v_add_u32_e32 v160, s18, v165
	v_add_u32_e32 v164, s19, v165
	ds_read_b128 v[148:151], v160
	ds_read_b128 v[152:155], v160 offset:1024
	ds_read_b128 v[156:159], v160 offset:2048
	ds_read_b128 v[160:163], v160 offset:3072
	ds_read_b128 v[180:183], v164
	ds_read_b128 v[184:187], v164 offset:1024
	ds_read_b128 v[188:191], v164 offset:2048
	ds_read_b128 v[192:195], v164 offset:3072
	s_add_u32 s44, s44, 0x80000
	s_addc_u32 s45, s45, 0
	s_mov_b32 m0, s53
	ds_read_b128 v[196:199], v173 offset:32768
	ds_read_b128 v[200:203], v173 offset:33792
	ds_read_b128 v[204:207], v173 offset:34816
	ds_read_b128 v[208:211], v173 offset:35840
	ds_read_b128 v[212:215], v173 offset:36864
	ds_read_b128 v[216:219], v173 offset:37888
	ds_read_b128 v[224:227], v173 offset:38912
	ds_read_b128 v[228:231], v173 offset:39936
	global_load_lds_dwordx4 v136, s[44:45]
	s_mov_b32 m0, s57
	s_nop 0
	global_load_lds_dwordx4 v132, s[44:45]
	s_waitcnt vmcnt(8)
	s_waitcnt lgkmcnt(0)
	s_barrier
; #define PG8_STAGE(bufoff, gbase, voff) do { _Pragma("unroll") for (int _i = 0; _i < 2; ++_i) \
;         __builtin_amdgcn_global_load_lds((const unsigned*)((const char*)(gbase) + (voff)[_i]), (PG8_LAS unsigned*)(lds + (bufoff) + ldsw + _i * 8192), 16, 0, 0); } while (0)
; #define PG8_LDA(dst, b, h) do { _Pragma("unroll") for (int m = 0; m < 4; ++m) _Pragma("unroll") for (int k = 0; k < 2; ++k) dst[m][k] = *(const PG8_LAS bf16x8*)(lds + PG8_SA(b, h) + aoff + m * 2048 + k * 1024); } while (0)
; #define PG8_LDB(dst, b, h) do { _Pragma("unroll") for (int n = 0; n < 2; ++n) _Pragma("unroll") for (int k = 0; k < 2; ++k) dst[n][k] = *(const PG8_LAS bf16x8*)(lds + PG8_SB(b, h) + boff + n * 2048 + k * 1024); } while (0)
; #define PG8_MMA(ai, bj, At, Bt) do { __builtin_amdgcn_s_setprio(1); _Pragma("unroll") for (int m = 0; m < 4; ++m) _Pragma("unroll") for (int n = 0; n < 2; ++n) _Pragma("unroll") for (int k = 0; k < 2; ++k) \
;         acc[ai][bj][m][n] = __builtin_amdgcn_mfma_f32_16x16x32_bf16(Bt[n][k], At[m][k], acc[ai][bj][m][n], 0, 0, 0); __builtin_amdgcn_s_setprio(0); } while (0)
; #define PG8_WAIT_V(n) asm volatile("s_waitcnt vmcnt(" #n ")" ::: "memory")
; #define PG8_WAIT_L(n) asm volatile("s_waitcnt lgkmcnt(" #n ")" ::: "memory")
; #define PG8_BAR __builtin_amdgcn_s_barrier()
; #define PG8_SCHED __builtin_amdgcn_sched_barrier(0)
; template <class Epi, class Sched, bool ALIGN_EPI = false, bool SP2 = false>
; __device__ __forceinline__ void gemm_phase(PG8_LAS unsigned char* lds, const Gemm g, const Sched& S, const Epi& E) {
;     ...
;             PG8_LDB(B0, 1, 0); PG8_LDB(B1, 1, 1); PG8_SCHED; PG8_LDA(At, 1, 0); PG8_STAGE(PG8_SA(0, 1), a2 + hA, voffA);
;             PG8_WAIT_V(8); PG8_WAIT_L(0); PG8_BAR; PG8_MMA(0, 0, At, B0); PG8_MMA(0, 1, At, B1); PG8_BAR; PG8_SCHED;
;             PG8_LDA(At, 1, 1); PG8_STAGE(PG8_SB(1, 0), b3, voffB); PG8_STAGE(PG8_SB(1, 1), b3 + hB, voffB); PG8_STAGE(PG8_SA(1, 0), a3, voffA);
;             PG8_WAIT_V(8); PG8_WAIT_L(0); PG8_BAR; PG8_MMA(1, 0, At, B0); PG8_MMA(1, 1, At, B1); PG8_BAR; PG8_SCHED;
;     ...
;         if constexpr (ALIGN_EPI) { if (wr == 0) PG8_BAR; }
	v_mfma_f32_16x16x32_bf16 v[126:129], v[148:151], v[196:199], v[126:129]
	v_mfma_f32_16x16x32_bf16 v[122:125], v[156:159], v[196:199], v[122:125]
	v_mfma_f32_16x16x32_bf16 v[110:113], v[148:151], v[204:207], v[110:113]
	v_mfma_f32_16x16x32_bf16 v[106:109], v[156:159], v[204:207], v[106:109]
	v_mfma_f32_16x16x32_bf16 v[94:97], v[148:151], v[212:215], v[94:97]
	v_mfma_f32_16x16x32_bf16 v[90:93], v[156:159], v[212:215], v[90:93]
	v_mfma_f32_16x16x32_bf16 v[78:81], v[148:151], v[224:227], v[78:81]
	v_mfma_f32_16x16x32_bf16 v[74:77], v[156:159], v[224:227], v[74:77]
	v_mfma_f32_16x16x32_bf16 v[126:129], v[152:155], v[200:203], v[126:129]
	v_mfma_f32_16x16x32_bf16 v[122:125], v[160:163], v[200:203], v[122:125]
	v_mfma_f32_16x16x32_bf16 v[110:113], v[152:155], v[208:211], v[110:113]
	v_mfma_f32_16x16x32_bf16 v[106:109], v[160:163], v[208:211], v[106:109]
	v_mfma_f32_16x16x32_bf16 v[94:97], v[152:155], v[216:219], v[94:97]
	v_mfma_f32_16x16x32_bf16 v[90:93], v[160:163], v[216:219], v[90:93]
	v_mfma_f32_16x16x32_bf16 v[78:81], v[152:155], v[228:231], v[78:81]
	v_mfma_f32_16x16x32_bf16 v[74:77], v[160:163], v[228:231], v[74:77]
	v_mfma_f32_16x16x32_bf16 v[118:121], v[180:183], v[196:199], v[118:121]
	v_mfma_f32_16x16x32_bf16 v[114:117], v[188:191], v[196:199], v[114:117]
	v_mfma_f32_16x16x32_bf16 v[102:105], v[180:183], v[204:207], v[102:105]
	v_mfma_f32_16x16x32_bf16 v[98:101], v[188:191], v[204:207], v[98:101]
	v_mfma_f32_16x16x32_bf16 v[86:89], v[180:183], v[212:215], v[86:89]
	v_mfma_f32_16x16x32_bf16 v[82:85], v[188:191], v[212:215], v[82:85]
	v_mfma_f32_16x16x32_bf16 v[70:73], v[180:183], v[224:227], v[70:73]
	v_mfma_f32_16x16x32_bf16 v[66:69], v[188:191], v[224:227], v[66:69]
	v_mfma_f32_16x16x32_bf16 v[118:121], v[184:187], v[200:203], v[118:121]
	v_mfma_f32_16x16x32_bf16 v[114:117], v[192:195], v[200:203], v[114:117]
	v_mfma_f32_16x16x32_bf16 v[102:105], v[184:187], v[208:211], v[102:105]
	v_mfma_f32_16x16x32_bf16 v[98:101], v[192:195], v[208:211], v[98:101]
	v_mfma_f32_16x16x32_bf16 v[86:89], v[184:187], v[216:219], v[86:89]
	v_mfma_f32_16x16x32_bf16 v[82:85], v[192:195], v[216:219], v[82:85]
	v_mfma_f32_16x16x32_bf16 v[70:73], v[184:187], v[228:231], v[70:73]
	v_mfma_f32_16x16x32_bf16 v[66:69], v[192:195], v[228:231], v[66:69]
	s_barrier
	s_add_i32 s18, s18, s49
	s_mov_b32 m0, s18
	ds_read_b128 v[196:199], v173 offset:49152
	ds_read_b128 v[200:203], v173 offset:50176
	ds_read_b128 v[204:207], v173 offset:51200
	ds_read_b128 v[208:211], v173 offset:52224
	ds_read_b128 v[212:215], v173 offset:53248
	ds_read_b128 v[216:219], v173 offset:54272
	ds_read_b128 v[224:227], v173 offset:55296
	ds_read_b128 v[228:231], v173 offset:56320
	global_load_lds_dwordx4 v134, s[76:77]
	s_add_i32 m0, s18, 0x2000
	s_add_u32 s42, s42, 0x80080
	s_addc_u32 s43, s43, 0
	s_add_i32 s18, s19, s49
	global_load_lds_dwordx4 v130, s[76:77]
	s_mov_b32 m0, s18
	s_nop 0
	global_load_lds_dwordx4 v134, s[42:43]
	s_add_i32 m0, s18, 0x2000
	s_nop 0
	global_load_lds_dwordx4 v130, s[42:43]
	s_mov_b32 m0, s60
	s_nop 0
	global_load_lds_dwordx4 v136, s[78:79]
	s_mov_b32 m0, s61
	s_nop 0
	global_load_lds_dwordx4 v132, s[78:79]
	s_waitcnt vmcnt(8)
	s_waitcnt lgkmcnt(0)
	s_barrier
	v_mfma_f32_16x16x32_bf16 v[62:65], v[148:151], v[196:199], v[62:65]
	v_mfma_f32_16x16x32_bf16 v[58:61], v[156:159], v[196:199], v[58:61]
	v_mfma_f32_16x16x32_bf16 v[46:49], v[148:151], v[204:207], v[46:49]
	v_mfma_f32_16x16x32_bf16 v[42:45], v[156:159], v[204:207], v[42:45]
	v_mfma_f32_16x16x32_bf16 v[30:33], v[148:151], v[212:215], v[30:33]
	v_mfma_f32_16x16x32_bf16 v[26:29], v[156:159], v[212:215], v[26:29]
	v_mfma_f32_16x16x32_bf16 v[14:17], v[148:151], v[224:227], v[14:17]
	v_mfma_f32_16x16x32_bf16 v[10:13], v[156:159], v[224:227], v[10:13]
	v_mfma_f32_16x16x32_bf16 v[62:65], v[152:155], v[200:203], v[62:65]
	v_mfma_f32_16x16x32_bf16 v[58:61], v[160:163], v[200:203], v[58:61]
	v_mfma_f32_16x16x32_bf16 v[46:49], v[152:155], v[208:211], v[46:49]
	v_mfma_f32_16x16x32_bf16 v[42:45], v[160:163], v[208:211], v[42:45]
	v_mfma_f32_16x16x32_bf16 v[30:33], v[152:155], v[216:219], v[30:33]
	v_mfma_f32_16x16x32_bf16 v[26:29], v[160:163], v[216:219], v[26:29]
	v_mfma_f32_16x16x32_bf16 v[14:17], v[152:155], v[228:231], v[14:17]
	v_mfma_f32_16x16x32_bf16 v[10:13], v[160:163], v[228:231], v[10:13]
	v_mfma_f32_16x16x32_bf16 v[54:57], v[180:183], v[196:199], v[54:57]
	v_mfma_f32_16x16x32_bf16 v[50:53], v[188:191], v[196:199], v[50:53]
	v_mfma_f32_16x16x32_bf16 v[38:41], v[180:183], v[204:207], v[38:41]
	v_mfma_f32_16x16x32_bf16 v[34:37], v[188:191], v[204:207], v[34:37]
	v_mfma_f32_16x16x32_bf16 v[22:25], v[180:183], v[212:215], v[22:25]
	v_mfma_f32_16x16x32_bf16 v[18:21], v[188:191], v[212:215], v[18:21]
	v_mfma_f32_16x16x32_bf16 v[6:9], v[180:183], v[224:227], v[6:9]
	v_mfma_f32_16x16x32_bf16 v[2:5], v[188:191], v[224:227], v[2:5]
	v_mfma_f32_16x16x32_bf16 v[54:57], v[184:187], v[200:203], v[54:57]
	v_mfma_f32_16x16x32_bf16 v[50:53], v[192:195], v[200:203], v[50:53]
	v_mfma_f32_16x16x32_bf16 v[38:41], v[184:187], v[208:211], v[38:41]
	v_mfma_f32_16x16x32_bf16 v[34:37], v[192:195], v[208:211], v[34:37]
	v_mfma_f32_16x16x32_bf16 v[22:25], v[184:187], v[216:219], v[22:25]
	v_mfma_f32_16x16x32_bf16 v[18:21], v[192:195], v[216:219], v[18:21]
	v_mfma_f32_16x16x32_bf16 v[6:9], v[184:187], v[228:231], v[6:9]
	v_mfma_f32_16x16x32_bf16 v[2:5], v[192:195], v[228:231], v[2:5]
	s_barrier
	s_add_i32 s72, s72, 2
	s_add_u32 s8, s8, 0x100
	s_addc_u32 s9, s9, 0
	s_add_u32 s70, s70, 0x100
	s_addc_u32 s71, s71, 0
	s_cmp_gt_u32 s72, 29
	s_cbranch_scc0 .LBB0_1048
	s_and_b64 vcc, exec, s[22:23]
	s_cbranch_vccz .LBB0_1051
	s_barrier

; #define PG8_STAGE(bufoff, gbase, voff) do { _Pragma("unroll") for (int _i = 0; _i < 2; ++_i) \
;         __builtin_amdgcn_global_load_lds((const unsigned*)((const char*)(gbase) + (voff)[_i]), (PG8_LAS unsigned*)(lds + (bufoff) + ldsw + _i * 8192), 16, 0, 0); } while (0)
; #define PG8_LDA(dst, b, h) do { _Pragma("unroll") for (int m = 0; m < 4; ++m) _Pragma("unroll") for (int k = 0; k < 2; ++k) dst[m][k] = *(const PG8_LAS bf16x8*)(lds + PG8_SA(b, h) + aoff + m * 2048 + k * 1024); } while (0)
; #define PG8_LDB(dst, b, h) do { _Pragma("unroll") for (int n = 0; n < 2; ++n) _Pragma("unroll") for (int k = 0; k < 2; ++k) dst[n][k] = *(const PG8_LAS bf16x8*)(lds + PG8_SB(b, h) + boff + n * 2048 + k * 1024); } while (0)
; #define PG8_WAIT_V(n) asm volatile("s_waitcnt vmcnt(" #n ")" ::: "memory")
; #define PG8_WAIT_L(n) asm volatile("s_waitcnt lgkmcnt(" #n ")" ::: "memory")
; #define PG8_BAR __builtin_amdgcn_s_barrier()
; #define PG8_SCHED __builtin_amdgcn_sched_barrier(0)
; template <class Epi, class Sched, bool ALIGN_EPI = false, bool SP2 = false>
; __device__ __forceinline__ void gemm_phase(PG8_LAS unsigned char* lds, const Gemm g, const Sched& S, const Epi& E) {
;     ...
;     for (;;) {
;         const bool has_next = S.next(ui + 1, nxt);
;         const char* nA = has_next ? (const char*)g.A + (size_t)nxt.pm * tA + (size_t)nxt.pn * pnA : cA; const char* nB = has_next ? (const char*)g.Bt + (size_t)nxt.pn * tB : cB;
; #pragma nounroll
;         for (int t = 0; t < nt; t += 2) {
;             const bool last = (t == nt - 2);
;             const char* a1 = cA + (size_t)(t + 1) * kstep;
;             const char* a2 = last ? nA : cA + (size_t)(t + 2) * kstep; const char* b2 = last ? nB : cB + (size_t)(t + 2) * kstep;
;             const char* a3 = a2 + kstep; const char* b3 = b2 + kstep;
;             if (last && has_next) S.a_ready(nxt);
;             if constexpr (SP2) {
;             PG8_LDB(B0, 0, 0); PG8_LDB(B1, 0, 1); PG8_SCHED; PG8_LDA(At, 0, 0); PG8_STAGE(PG8_SA(1, 1), a1 + hA, voffA);
;             PG8_WAIT_V(8); PG8_WAIT_L(0); PG8_BAR; PG8_MMA(0, 0, At, B0); PG8_MMA(0, 1, At, B1); PG8_BAR; PG8_SCHED;
;             PG8_LDA(At, 0, 1); PG8_STAGE(PG8_SB(0, 0), b2, voffB); PG8_STAGE(PG8_SB(0, 1), b2 + hB, voffB); PG8_STAGE(PG8_SA(0, 0), a2, voffA);
;             PG8_WAIT_V(8); PG8_WAIT_L(0); PG8_BAR; PG8_MMA(1, 0, At, B0); PG8_MMA(1, 1, At, B1); PG8_BAR; PG8_SCHED;
.LBB0_1126:
	s_add_u32 s61, s36, 0x100
	v_mov_b32_e32 v2, 0
	s_addc_u32 s62, s37, 0
	s_mov_b32 s63, -2
	s_waitcnt lgkmcnt(0)
	v_mov_b32_e32 v3, v2
	ds_read_b128 v[130:133], v190
	ds_read_b128 v[134:137], v190 offset:1024
	ds_read_b128 v[138:141], v190 offset:2048
	ds_read_b128 v[142:145], v190 offset:3072
	ds_read_b128 v[146:149], v191
	ds_read_b128 v[150:153], v191 offset:1024
	ds_read_b128 v[170:173], v191 offset:2048
	ds_read_b128 v[174:177], v191 offset:3072
	s_add_u32 s36, s24, 0x100
	s_addc_u32 s37, s25, 0
	s_cmpk_eq_i32 s63, 0x54
	s_cselect_b32 s41, s9, s37
	s_cselect_b32 s40, s8, s36
	s_cselect_b32 s39, s23, s62
	s_cselect_b32 s38, s22, s61
	s_add_i32 m0, s46, 0xc000
	ds_read_b128 v[178:181], v192
	ds_read_b128 v[182:185], v192 offset:1024
	ds_read_b128 v[194:197], v192 offset:2048
	ds_read_b128 v[198:201], v192 offset:3072
	ds_read_b128 v[202:205], v192 offset:4096
	ds_read_b128 v[206:209], v192 offset:5120
	ds_read_b128 v[210:213], v192 offset:6144
	ds_read_b128 v[214:217], v192 offset:7168
	global_load_lds_dwordx4 v162, s[24:25]
	s_add_i32 m0, s46, 0xe000
	s_nop 0
	global_load_lds_dwordx4 v164, s[24:25]
	s_waitcnt vmcnt(8)
	s_waitcnt lgkmcnt(0)
	s_barrier
	v_mfma_f32_16x16x32_bf16 v[126:129], v[130:133], v[178:181], 0
	v_mfma_f32_16x16x32_bf16 v[122:125], v[138:141], v[178:181], 0
	v_mfma_f32_16x16x32_bf16 v[110:113], v[130:133], v[194:197], 0
	v_mfma_f32_16x16x32_bf16 v[106:109], v[138:141], v[194:197], 0
	v_mfma_f32_16x16x32_bf16 v[94:97], v[130:133], v[202:205], 0
	v_mfma_f32_16x16x32_bf16 v[90:93], v[138:141], v[202:205], 0
	v_mfma_f32_16x16x32_bf16 v[78:81], v[130:133], v[210:213], 0
	v_mfma_f32_16x16x32_bf16 v[74:77], v[138:141], v[210:213], 0
	v_mfma_f32_16x16x32_bf16 v[126:129], v[134:137], v[182:185], v[126:129]
	v_mfma_f32_16x16x32_bf16 v[122:125], v[142:145], v[182:185], v[122:125]
	v_mfma_f32_16x16x32_bf16 v[110:113], v[134:137], v[198:201], v[110:113]
	v_mfma_f32_16x16x32_bf16 v[106:109], v[142:145], v[198:201], v[106:109]
	v_mfma_f32_16x16x32_bf16 v[94:97], v[134:137], v[206:209], v[94:97]
	v_mfma_f32_16x16x32_bf16 v[90:93], v[142:145], v[206:209], v[90:93]
	v_mfma_f32_16x16x32_bf16 v[78:81], v[134:137], v[214:217], v[78:81]
	v_mfma_f32_16x16x32_bf16 v[74:77], v[142:145], v[214:217], v[74:77]
	v_mfma_f32_16x16x32_bf16 v[118:121], v[146:149], v[178:181], 0
	v_mfma_f32_16x16x32_bf16 v[114:117], v[170:173], v[178:181], 0
	v_mfma_f32_16x16x32_bf16 v[102:105], v[146:149], v[194:197], 0
	v_mfma_f32_16x16x32_bf16 v[98:101], v[170:173], v[194:197], 0
	v_mfma_f32_16x16x32_bf16 v[86:89], v[146:149], v[202:205], 0
	v_mfma_f32_16x16x32_bf16 v[82:85], v[170:173], v[202:205], 0
	v_mfma_f32_16x16x32_bf16 v[70:73], v[146:149], v[210:213], 0
	v_mfma_f32_16x16x32_bf16 v[66:69], v[170:173], v[210:213], 0
	v_mfma_f32_16x16x32_bf16 v[118:121], v[150:153], v[182:185], v[118:121]
	v_mfma_f32_16x16x32_bf16 v[114:117], v[174:177], v[182:185], v[114:117]
	v_mfma_f32_16x16x32_bf16 v[102:105], v[150:153], v[198:201], v[102:105]
	v_mfma_f32_16x16x32_bf16 v[98:101], v[174:177], v[198:201], v[98:101]
	v_mfma_f32_16x16x32_bf16 v[86:89], v[150:153], v[206:209], v[86:89]
	v_mfma_f32_16x16x32_bf16 v[82:85], v[174:177], v[206:209], v[82:85]
	v_mfma_f32_16x16x32_bf16 v[70:73], v[150:153], v[214:217], v[70:73]
	v_mfma_f32_16x16x32_bf16 v[66:69], v[174:177], v[214:217], v[66:69]
	s_barrier
	s_add_i32 s18, s55, s45
	s_add_u32 s76, s38, s16
	s_addc_u32 s77, s39, s17
	s_mov_b32 m0, s18
	ds_read_b128 v[178:181], v192 offset:16384
	ds_read_b128 v[182:185], v192 offset:17408
	ds_read_b128 v[194:197], v192 offset:18432
	ds_read_b128 v[198:201], v192 offset:19456
	ds_read_b128 v[202:205], v192 offset:20480
	ds_read_b128 v[206:209], v192 offset:21504
	ds_read_b128 v[210:213], v192 offset:22528
	ds_read_b128 v[214:217], v192 offset:23552
	global_load_lds_dwordx4 v156, s[38:39]
	s_add_i32 m0, s18, 0x2000
	s_add_u32 s24, s38, 0x160000
	s_addc_u32 s25, s39, 0
	s_add_i32 s18, s56, s45
	global_load_lds_dwordx4 v160, s[38:39]
	s_mov_b32 m0, s18
	s_nop 0
	global_load_lds_dwordx4 v156, s[24:25]
	s_add_i32 m0, s18, 0x2000
	s_nop 0
	global_load_lds_dwordx4 v160, s[24:25]
	s_add_u32 s78, s40, s16
	s_addc_u32 s79, s41, s17
	s_mov_b32 m0, s46
	s_nop 0
	global_load_lds_dwordx4 v154, s[40:41]
	s_mov_b32 m0, s47
	s_nop 0
	global_load_lds_dwordx4 v158, s[40:41]
	s_waitcnt vmcnt(8)
	s_waitcnt lgkmcnt(0)
	s_barrier
	v_mfma_f32_16x16x32_bf16 v[62:65], v[130:133], v[178:181], 0
	v_mfma_f32_16x16x32_bf16 v[58:61], v[138:141], v[178:181], 0
	v_mfma_f32_16x16x32_bf16 v[46:49], v[130:133], v[194:197], 0
	v_mfma_f32_16x16x32_bf16 v[42:45], v[138:141], v[194:197], 0
	v_mfma_f32_16x16x32_bf16 v[30:33], v[130:133], v[202:205], 0
	v_mfma_f32_16x16x32_bf16 v[26:29], v[138:141], v[202:205], 0
	v_mfma_f32_16x16x32_bf16 v[14:17], v[130:133], v[210:213], 0
	v_mfma_f32_16x16x32_bf16 v[10:13], v[138:141], v[210:213], 0
	v_mfma_f32_16x16x32_bf16 v[62:65], v[134:137], v[182:185], v[62:65]
	v_mfma_f32_16x16x32_bf16 v[58:61], v[142:145], v[182:185], v[58:61]
	v_mfma_f32_16x16x32_bf16 v[46:49], v[134:137], v[198:201], v[46:49]
	v_mfma_f32_16x16x32_bf16 v[42:45], v[142:145], v[198:201], v[42:45]
	v_mfma_f32_16x16x32_bf16 v[30:33], v[134:137], v[206:209], v[30:33]
	v_mfma_f32_16x16x32_bf16 v[26:29], v[142:145], v[206:209], v[26:29]
	v_mfma_f32_16x16x32_bf16 v[14:17], v[134:137], v[214:217], v[14:17]
	v_mfma_f32_16x16x32_bf16 v[10:13], v[142:145], v[214:217], v[10:13]
	v_mfma_f32_16x16x32_bf16 v[54:57], v[146:149], v[178:181], 0
	v_mfma_f32_16x16x32_bf16 v[50:53], v[170:173], v[178:181], 0
	v_mfma_f32_16x16x32_bf16 v[38:41], v[146:149], v[194:197], 0
	v_mfma_f32_16x16x32_bf16 v[34:37], v[170:173], v[194:197], 0
	v_mfma_f32_16x16x32_bf16 v[22:25], v[146:149], v[202:205], 0
	v_mfma_f32_16x16x32_bf16 v[18:21], v[170:173], v[202:205], 0
	v_mfma_f32_16x16x32_bf16 v[6:9], v[146:149], v[210:213], 0
	v_mfma_f32_16x16x32_bf16 v[2:5], v[170:173], v[210:213], 0
	v_mfma_f32_16x16x32_bf16 v[54:57], v[150:153], v[182:185], v[54:57]
	v_mfma_f32_16x16x32_bf16 v[50:53], v[174:177], v[182:185], v[50:53]
	v_mfma_f32_16x16x32_bf16 v[38:41], v[150:153], v[198:201], v[38:41]
	v_mfma_f32_16x16x32_bf16 v[34:37], v[174:177], v[198:201], v[34:37]
	v_mfma_f32_16x16x32_bf16 v[22:25], v[150:153], v[206:209], v[22:25]
	v_mfma_f32_16x16x32_bf16 v[18:21], v[174:177], v[206:209], v[18:21]
	v_mfma_f32_16x16x32_bf16 v[6:9], v[150:153], v[214:217], v[6:9]
	v_mfma_f32_16x16x32_bf16 v[2:5], v[174:177], v[214:217], v[2:5]
	s_barrier
; #define PG8_STAGE(bufoff, gbase, voff) do { _Pragma("unroll") for (int _i = 0; _i < 2; ++_i) \
;         __builtin_amdgcn_global_load_lds((const unsigned*)((const char*)(gbase) + (voff)[_i]), (PG8_LAS unsigned*)(lds + (bufoff) + ldsw + _i * 8192), 16, 0, 0); } while (0)
; #define PG8_LDA(dst, b, h) do { _Pragma("unroll") for (int m = 0; m < 4; ++m) _Pragma("unroll") for (int k = 0; k < 2; ++k) dst[m][k] = *(const PG8_LAS bf16x8*)(lds + PG8_SA(b, h) + aoff + m * 2048 + k * 1024); } while (0)
; #define PG8_LDB(dst, b, h) do { _Pragma("unroll") for (int n = 0; n < 2; ++n) _Pragma("unroll") for (int k = 0; k < 2; ++k) dst[n][k] = *(const PG8_LAS bf16x8*)(lds + PG8_SB(b, h) + boff + n * 2048 + k * 1024); } while (0)
; #define PG8_MMA(ai, bj, At, Bt) do { __builtin_amdgcn_s_setprio(1); _Pragma("unroll") for (int m = 0; m < 4; ++m) _Pragma("unroll") for (int n = 0; n < 2; ++n) _Pragma("unroll") for (int k = 0; k < 2; ++k) \
;         acc[ai][bj][m][n] = __builtin_amdgcn_mfma_f32_16x16x32_bf16(Bt[n][k], At[m][k], acc[ai][bj][m][n], 0, 0, 0); __builtin_amdgcn_s_setprio(0); } while (0)
; #define PG8_WAIT_V(n) asm volatile("s_waitcnt vmcnt(" #n ")" ::: "memory")
; #define PG8_WAIT_L(n) asm volatile("s_waitcnt lgkmcnt(" #n ")" ::: "memory")
; #define PG8_BAR __builtin_amdgcn_s_barrier()
; #define PG8_SCHED __builtin_amdgcn_sched_barrier(0)
; template <class Epi, class Sched, bool ALIGN_EPI = false, bool SP2 = false>
; __device__ __forceinline__ void gemm_phase(PG8_LAS unsigned char* lds, const Gemm g, const Sched& S, const Epi& E) {
;     ...
;             PG8_LDB(B0, 1, 0); PG8_LDB(B1, 1, 1); PG8_SCHED; PG8_LDA(At, 1, 0); PG8_STAGE(PG8_SA(0, 1), a2 + hA, voffA);
;             PG8_WAIT_V(8); PG8_WAIT_L(0); PG8_BAR; PG8_MMA(0, 0, At, B0); PG8_MMA(0, 1, At, B1); PG8_BAR; PG8_SCHED;
;             PG8_LDA(At, 1, 1); PG8_STAGE(PG8_SB(1, 0), b3, voffB); PG8_STAGE(PG8_SB(1, 1), b3 + hB, voffB); PG8_STAGE(PG8_SA(1, 0), a3, voffA);
;             PG8_WAIT_V(8); PG8_WAIT_L(0); PG8_BAR; PG8_MMA(1, 0, At, B0); PG8_MMA(1, 1, At, B1); PG8_BAR; PG8_SCHED;
	s_add_i32 s18, 0, 0x18000
	s_add_i32 s19, 0, 0x1c000
	v_add_u32_e32 v142, s18, v188
	v_add_u32_e32 v174, s19, v188
	ds_read_b128 v[130:133], v142
	ds_read_b128 v[134:137], v142 offset:1024
	ds_read_b128 v[138:141], v142 offset:2048
	ds_read_b128 v[142:145], v142 offset:3072
	ds_read_b128 v[146:149], v174
	ds_read_b128 v[150:153], v174 offset:1024
	ds_read_b128 v[170:173], v174 offset:2048
	ds_read_b128 v[174:177], v174 offset:3072
	s_add_u32 s24, s40, 0x160000
	s_addc_u32 s25, s41, 0
	s_mov_b32 m0, s48
	ds_read_b128 v[178:181], v192 offset:32768
	ds_read_b128 v[182:185], v192 offset:33792
	ds_read_b128 v[194:197], v192 offset:34816
	ds_read_b128 v[198:201], v192 offset:35840
	ds_read_b128 v[202:205], v192 offset:36864
	ds_read_b128 v[206:209], v192 offset:37888
	ds_read_b128 v[210:213], v192 offset:38912
	ds_read_b128 v[214:217], v192 offset:39936
	global_load_lds_dwordx4 v154, s[24:25]
	s_mov_b32 m0, s49
	s_nop 0
	global_load_lds_dwordx4 v158, s[24:25]
	s_waitcnt vmcnt(8)
	s_waitcnt lgkmcnt(0)
	s_barrier
	v_mfma_f32_16x16x32_bf16 v[126:129], v[130:133], v[178:181], v[126:129]
	v_mfma_f32_16x16x32_bf16 v[122:125], v[138:141], v[178:181], v[122:125]
	v_mfma_f32_16x16x32_bf16 v[110:113], v[130:133], v[194:197], v[110:113]
	v_mfma_f32_16x16x32_bf16 v[106:109], v[138:141], v[194:197], v[106:109]
	v_mfma_f32_16x16x32_bf16 v[94:97], v[130:133], v[202:205], v[94:97]
	v_mfma_f32_16x16x32_bf16 v[90:93], v[138:141], v[202:205], v[90:93]
	v_mfma_f32_16x16x32_bf16 v[78:81], v[130:133], v[210:213], v[78:81]
	v_mfma_f32_16x16x32_bf16 v[74:77], v[138:141], v[210:213], v[74:77]
	v_mfma_f32_16x16x32_bf16 v[126:129], v[134:137], v[182:185], v[126:129]
	v_mfma_f32_16x16x32_bf16 v[122:125], v[142:145], v[182:185], v[122:125]
	v_mfma_f32_16x16x32_bf16 v[110:113], v[134:137], v[198:201], v[110:113]
	v_mfma_f32_16x16x32_bf16 v[106:109], v[142:145], v[198:201], v[106:109]
	v_mfma_f32_16x16x32_bf16 v[94:97], v[134:137], v[206:209], v[94:97]
	v_mfma_f32_16x16x32_bf16 v[90:93], v[142:145], v[206:209], v[90:93]
	v_mfma_f32_16x16x32_bf16 v[78:81], v[134:137], v[214:217], v[78:81]
	v_mfma_f32_16x16x32_bf16 v[74:77], v[142:145], v[214:217], v[74:77]
	v_mfma_f32_16x16x32_bf16 v[118:121], v[146:149], v[178:181], v[118:121]
	v_mfma_f32_16x16x32_bf16 v[114:117], v[170:173], v[178:181], v[114:117]
	v_mfma_f32_16x16x32_bf16 v[102:105], v[146:149], v[194:197], v[102:105]
	v_mfma_f32_16x16x32_bf16 v[98:101], v[170:173], v[194:197], v[98:101]
	v_mfma_f32_16x16x32_bf16 v[86:89], v[146:149], v[202:205], v[86:89]
	v_mfma_f32_16x16x32_bf16 v[82:85], v[170:173], v[202:205], v[82:85]
	v_mfma_f32_16x16x32_bf16 v[70:73], v[146:149], v[210:213], v[70:73]
	v_mfma_f32_16x16x32_bf16 v[66:69], v[170:173], v[210:213], v[66:69]
	v_mfma_f32_16x16x32_bf16 v[118:121], v[150:153], v[182:185], v[118:121]
	v_mfma_f32_16x16x32_bf16 v[114:117], v[174:177], v[182:185], v[114:117]
	v_mfma_f32_16x16x32_bf16 v[102:105], v[150:153], v[198:201], v[102:105]
	v_mfma_f32_16x16x32_bf16 v[98:101], v[174:177], v[198:201], v[98:101]
	v_mfma_f32_16x16x32_bf16 v[86:89], v[150:153], v[206:209], v[86:89]
	v_mfma_f32_16x16x32_bf16 v[82:85], v[174:177], v[206:209], v[82:85]
	v_mfma_f32_16x16x32_bf16 v[70:73], v[150:153], v[214:217], v[70:73]
	v_mfma_f32_16x16x32_bf16 v[66:69], v[174:177], v[214:217], v[66:69]
	s_barrier
	s_add_i32 s18, s18, s45
	s_mov_b32 m0, s18
	ds_read_b128 v[178:181], v192 offset:49152
	ds_read_b128 v[182:185], v192 offset:50176
	ds_read_b128 v[194:197], v192 offset:51200
	ds_read_b128 v[198:201], v192 offset:52224
	ds_read_b128 v[202:205], v192 offset:53248
	ds_read_b128 v[206:209], v192 offset:54272
	ds_read_b128 v[210:213], v192 offset:55296
	ds_read_b128 v[214:217], v192 offset:56320
	global_load_lds_dwordx4 v156, s[76:77]
	s_add_i32 m0, s18, 0x2000
	s_add_u32 s24, s38, 0x160080
	s_addc_u32 s25, s39, 0
	s_add_i32 s18, s19, s45
	global_load_lds_dwordx4 v160, s[76:77]
	s_mov_b32 m0, s18
	s_nop 0
	global_load_lds_dwordx4 v156, s[24:25]
	s_add_i32 m0, s18, 0x2000
	s_nop 0
	global_load_lds_dwordx4 v160, s[24:25]
	s_mov_b32 m0, s52
	s_nop 0
	global_load_lds_dwordx4 v154, s[78:79]
	s_mov_b32 m0, s53
	s_nop 0
	global_load_lds_dwordx4 v158, s[78:79]
	s_waitcnt vmcnt(8)
	s_waitcnt lgkmcnt(0)
	s_barrier
	v_mfma_f32_16x16x32_bf16 v[62:65], v[130:133], v[178:181], v[62:65]
	v_mfma_f32_16x16x32_bf16 v[58:61], v[138:141], v[178:181], v[58:61]
	v_mfma_f32_16x16x32_bf16 v[46:49], v[130:133], v[194:197], v[46:49]
	v_mfma_f32_16x16x32_bf16 v[42:45], v[138:141], v[194:197], v[42:45]
	v_mfma_f32_16x16x32_bf16 v[30:33], v[130:133], v[202:205], v[30:33]
	v_mfma_f32_16x16x32_bf16 v[26:29], v[138:141], v[202:205], v[26:29]
	v_mfma_f32_16x16x32_bf16 v[14:17], v[130:133], v[210:213], v[14:17]
	v_mfma_f32_16x16x32_bf16 v[10:13], v[138:141], v[210:213], v[10:13]
	v_mfma_f32_16x16x32_bf16 v[62:65], v[134:137], v[182:185], v[62:65]
	v_mfma_f32_16x16x32_bf16 v[58:61], v[142:145], v[182:185], v[58:61]
	v_mfma_f32_16x16x32_bf16 v[46:49], v[134:137], v[198:201], v[46:49]
	v_mfma_f32_16x16x32_bf16 v[42:45], v[142:145], v[198:201], v[42:45]
	v_mfma_f32_16x16x32_bf16 v[30:33], v[134:137], v[206:209], v[30:33]
	v_mfma_f32_16x16x32_bf16 v[26:29], v[142:145], v[206:209], v[26:29]
	v_mfma_f32_16x16x32_bf16 v[14:17], v[134:137], v[214:217], v[14:17]
	v_mfma_f32_16x16x32_bf16 v[10:13], v[142:145], v[214:217], v[10:13]
	v_mfma_f32_16x16x32_bf16 v[54:57], v[146:149], v[178:181], v[54:57]
	v_mfma_f32_16x16x32_bf16 v[50:53], v[170:173], v[178:181], v[50:53]
	v_mfma_f32_16x16x32_bf16 v[38:41], v[146:149], v[194:197], v[38:41]
	v_mfma_f32_16x16x32_bf16 v[34:37], v[170:173], v[194:197], v[34:37]
	v_mfma_f32_16x16x32_bf16 v[22:25], v[146:149], v[202:205], v[22:25]
	v_mfma_f32_16x16x32_bf16 v[18:21], v[170:173], v[202:205], v[18:21]
	v_mfma_f32_16x16x32_bf16 v[6:9], v[146:149], v[210:213], v[6:9]
	v_mfma_f32_16x16x32_bf16 v[2:5], v[170:173], v[210:213], v[2:5]
	v_mfma_f32_16x16x32_bf16 v[54:57], v[150:153], v[182:185], v[54:57]
	v_mfma_f32_16x16x32_bf16 v[50:53], v[174:177], v[182:185], v[50:53]
	v_mfma_f32_16x16x32_bf16 v[38:41], v[150:153], v[198:201], v[38:41]
	v_mfma_f32_16x16x32_bf16 v[34:37], v[174:177], v[198:201], v[34:37]
	v_mfma_f32_16x16x32_bf16 v[22:25], v[150:153], v[206:209], v[22:25]
	v_mfma_f32_16x16x32_bf16 v[18:21], v[174:177], v[206:209], v[18:21]
	v_mfma_f32_16x16x32_bf16 v[6:9], v[150:153], v[214:217], v[6:9]
	v_mfma_f32_16x16x32_bf16 v[2:5], v[174:177], v[214:217], v[2:5]
	s_barrier
	s_add_i32 s63, s63, 2
	s_add_u32 s61, s61, 0x100
	s_addc_u32 s62, s62, 0
	s_cmpk_gt_u32 s63, 0x55
	s_mov_b64 s[24:25], s[36:37]
; #define PG8_STAGE(bufoff, gbase, voff) do { _Pragma("unroll") for (int _i = 0; _i < 2; ++_i) \
;         __builtin_amdgcn_global_load_lds((const unsigned*)((const char*)(gbase) + (voff)[_i]), (PG8_LAS unsigned*)(lds + (bufoff) + ldsw + _i * 8192), 16, 0, 0); } while (0)
; #define PG8_LDA(dst, b, h) do { _Pragma("unroll") for (int m = 0; m < 4; ++m) _Pragma("unroll") for (int k = 0; k < 2; ++k) dst[m][k] = *(const PG8_LAS bf16x8*)(lds + PG8_SA(b, h) + aoff + m * 2048 + k * 1024); } while (0)
; #define PG8_LDB(dst, b, h) do { _Pragma("unroll") for (int n = 0; n < 2; ++n) _Pragma("unroll") for (int k = 0; k < 2; ++k) dst[n][k] = *(const PG8_LAS bf16x8*)(lds + PG8_SB(b, h) + boff + n * 2048 + k * 1024); } while (0)
; #define PG8_MMA(ai, bj, At, Bt) do { __builtin_amdgcn_s_setprio(1); _Pragma("unroll") for (int m = 0; m < 4; ++m) _Pragma("unroll") for (int n = 0; n < 2; ++n) _Pragma("unroll") for (int k = 0; k < 2; ++k) \
;         acc[ai][bj][m][n] = __builtin_amdgcn_mfma_f32_16x16x32_bf16(Bt[n][k], At[m][k], acc[ai][bj][m][n], 0, 0, 0); __builtin_amdgcn_s_setprio(0); } while (0)
; #define PG8_WAIT_V(n) asm volatile("s_waitcnt vmcnt(" #n ")" ::: "memory")
; #define PG8_WAIT_L(n) asm volatile("s_waitcnt lgkmcnt(" #n ")" ::: "memory")
; #define PG8_BAR __builtin_amdgcn_s_barrier()
; #define PG8_SCHED __builtin_amdgcn_sched_barrier(0)
; template <class Epi, class Sched, bool ALIGN_EPI = false, bool SP2 = false>
; __device__ __forceinline__ void gemm_phase(PG8_LAS unsigned char* lds, const Gemm g, const Sched& S, const Epi& E) {
;     ...
;             PG8_LDB(B0, 0, 0); PG8_LDB(B1, 0, 1); PG8_SCHED; PG8_LDA(At, 0, 0); PG8_STAGE(PG8_SA(1, 1), a1 + hA, voffA);
;             PG8_WAIT_V(8); PG8_WAIT_L(0); PG8_BAR; PG8_MMA(0, 0, At, B0); PG8_MMA(0, 1, At, B1); PG8_BAR; PG8_SCHED;
;             PG8_LDA(At, 0, 1); PG8_STAGE(PG8_SB(0, 0), b2, voffB); PG8_STAGE(PG8_SB(0, 1), b2 + hB, voffB); PG8_STAGE(PG8_SA(0, 0), a2, voffA);
;             PG8_WAIT_V(8); PG8_WAIT_L(0); PG8_BAR; PG8_MMA(1, 0, At, B0); PG8_MMA(1, 1, At, B1); PG8_BAR; PG8_SCHED;
.LBB0_1127:
	ds_read_b128 v[130:133], v190
	ds_read_b128 v[134:137], v190 offset:1024
	ds_read_b128 v[138:141], v190 offset:2048
	ds_read_b128 v[142:145], v190 offset:3072
	ds_read_b128 v[146:149], v191
	ds_read_b128 v[150:153], v191 offset:1024
	ds_read_b128 v[170:173], v191 offset:2048
	ds_read_b128 v[174:177], v191 offset:3072
	s_add_u32 s36, s24, 0x100
	s_addc_u32 s37, s25, 0
	s_cmpk_eq_i32 s63, 0x54
	s_cselect_b32 s41, s9, s37
	s_cselect_b32 s40, s8, s36
	s_cselect_b32 s39, s23, s62
	s_cselect_b32 s38, s22, s61
	s_add_i32 m0, s46, 0xc000
	ds_read_b128 v[178:181], v192
	ds_read_b128 v[182:185], v192 offset:1024
	ds_read_b128 v[194:197], v192 offset:2048
	ds_read_b128 v[198:201], v192 offset:3072
	ds_read_b128 v[202:205], v192 offset:4096
	ds_read_b128 v[206:209], v192 offset:5120
	ds_read_b128 v[210:213], v192 offset:6144
	ds_read_b128 v[214:217], v192 offset:7168
	global_load_lds_dwordx4 v162, s[24:25]
	s_add_i32 m0, s46, 0xe000
	s_nop 0
	global_load_lds_dwordx4 v164, s[24:25]
	s_waitcnt vmcnt(8)
	s_waitcnt lgkmcnt(0)
	s_barrier
	v_mfma_f32_16x16x32_bf16 v[126:129], v[130:133], v[178:181], v[126:129]
	v_mfma_f32_16x16x32_bf16 v[122:125], v[138:141], v[178:181], v[122:125]
	v_mfma_f32_16x16x32_bf16 v[110:113], v[130:133], v[194:197], v[110:113]
	v_mfma_f32_16x16x32_bf16 v[106:109], v[138:141], v[194:197], v[106:109]
	v_mfma_f32_16x16x32_bf16 v[94:97], v[130:133], v[202:205], v[94:97]
	v_mfma_f32_16x16x32_bf16 v[90:93], v[138:141], v[202:205], v[90:93]
	v_mfma_f32_16x16x32_bf16 v[78:81], v[130:133], v[210:213], v[78:81]
	v_mfma_f32_16x16x32_bf16 v[74:77], v[138:141], v[210:213], v[74:77]
	v_mfma_f32_16x16x32_bf16 v[126:129], v[134:137], v[182:185], v[126:129]
	v_mfma_f32_16x16x32_bf16 v[122:125], v[142:145], v[182:185], v[122:125]
	v_mfma_f32_16x16x32_bf16 v[110:113], v[134:137], v[198:201], v[110:113]
	v_mfma_f32_16x16x32_bf16 v[106:109], v[142:145], v[198:201], v[106:109]
	v_mfma_f32_16x16x32_bf16 v[94:97], v[134:137], v[206:209], v[94:97]
	v_mfma_f32_16x16x32_bf16 v[90:93], v[142:145], v[206:209], v[90:93]
	v_mfma_f32_16x16x32_bf16 v[78:81], v[134:137], v[214:217], v[78:81]
	v_mfma_f32_16x16x32_bf16 v[74:77], v[142:145], v[214:217], v[74:77]
	v_mfma_f32_16x16x32_bf16 v[118:121], v[146:149], v[178:181], v[118:121]
	v_mfma_f32_16x16x32_bf16 v[114:117], v[170:173], v[178:181], v[114:117]
	v_mfma_f32_16x16x32_bf16 v[102:105], v[146:149], v[194:197], v[102:105]
	v_mfma_f32_16x16x32_bf16 v[98:101], v[170:173], v[194:197], v[98:101]
	v_mfma_f32_16x16x32_bf16 v[86:89], v[146:149], v[202:205], v[86:89]
	v_mfma_f32_16x16x32_bf16 v[82:85], v[170:173], v[202:205], v[82:85]
	v_mfma_f32_16x16x32_bf16 v[70:73], v[146:149], v[210:213], v[70:73]
	v_mfma_f32_16x16x32_bf16 v[66:69], v[170:173], v[210:213], v[66:69]
	v_mfma_f32_16x16x32_bf16 v[118:121], v[150:153], v[182:185], v[118:121]
	v_mfma_f32_16x16x32_bf16 v[114:117], v[174:177], v[182:185], v[114:117]
	v_mfma_f32_16x16x32_bf16 v[102:105], v[150:153], v[198:201], v[102:105]
	v_mfma_f32_16x16x32_bf16 v[98:101], v[174:177], v[198:201], v[98:101]
	v_mfma_f32_16x16x32_bf16 v[86:89], v[150:153], v[206:209], v[86:89]
	v_mfma_f32_16x16x32_bf16 v[82:85], v[174:177], v[206:209], v[82:85]
	v_mfma_f32_16x16x32_bf16 v[70:73], v[150:153], v[214:217], v[70:73]
	v_mfma_f32_16x16x32_bf16 v[66:69], v[174:177], v[214:217], v[66:69]
	s_barrier
	s_add_i32 s18, s55, s45
	s_add_u32 s76, s38, s16
	s_addc_u32 s77, s39, s17
	s_mov_b32 m0, s18
	ds_read_b128 v[178:181], v192 offset:16384
	ds_read_b128 v[182:185], v192 offset:17408
	ds_read_b128 v[194:197], v192 offset:18432
	ds_read_b128 v[198:201], v192 offset:19456
	ds_read_b128 v[202:205], v192 offset:20480
	ds_read_b128 v[206:209], v192 offset:21504
	ds_read_b128 v[210:213], v192 offset:22528
	ds_read_b128 v[214:217], v192 offset:23552
	global_load_lds_dwordx4 v156, s[38:39]
	s_add_i32 m0, s18, 0x2000
	s_add_u32 s24, s38, 0x160000
	s_addc_u32 s25, s39, 0
	s_add_i32 s18, s56, s45
	global_load_lds_dwordx4 v160, s[38:39]
	s_mov_b32 m0, s18
	s_nop 0
	global_load_lds_dwordx4 v156, s[24:25]
	s_add_i32 m0, s18, 0x2000
	s_nop 0
	global_load_lds_dwordx4 v160, s[24:25]
	s_add_u32 s78, s40, s16
	s_addc_u32 s79, s41, s17
	s_mov_b32 m0, s46
	s_nop 0
	global_load_lds_dwordx4 v154, s[40:41]
	s_mov_b32 m0, s47
	s_nop 0
	global_load_lds_dwordx4 v158, s[40:41]
	s_waitcnt vmcnt(8)
	s_waitcnt lgkmcnt(0)
	s_barrier
	v_mfma_f32_16x16x32_bf16 v[62:65], v[130:133], v[178:181], v[62:65]
	v_mfma_f32_16x16x32_bf16 v[58:61], v[138:141], v[178:181], v[58:61]
	v_mfma_f32_16x16x32_bf16 v[46:49], v[130:133], v[194:197], v[46:49]
	v_mfma_f32_16x16x32_bf16 v[42:45], v[138:141], v[194:197], v[42:45]
	v_mfma_f32_16x16x32_bf16 v[30:33], v[130:133], v[202:205], v[30:33]
	v_mfma_f32_16x16x32_bf16 v[26:29], v[138:141], v[202:205], v[26:29]
	v_mfma_f32_16x16x32_bf16 v[14:17], v[130:133], v[210:213], v[14:17]
	v_mfma_f32_16x16x32_bf16 v[10:13], v[138:141], v[210:213], v[10:13]
	v_mfma_f32_16x16x32_bf16 v[62:65], v[134:137], v[182:185], v[62:65]
	v_mfma_f32_16x16x32_bf16 v[58:61], v[142:145], v[182:185], v[58:61]
	v_mfma_f32_16x16x32_bf16 v[46:49], v[134:137], v[198:201], v[46:49]
	v_mfma_f32_16x16x32_bf16 v[42:45], v[142:145], v[198:201], v[42:45]
	v_mfma_f32_16x16x32_bf16 v[30:33], v[134:137], v[206:209], v[30:33]
	v_mfma_f32_16x16x32_bf16 v[26:29], v[142:145], v[206:209], v[26:29]
	v_mfma_f32_16x16x32_bf16 v[14:17], v[134:137], v[214:217], v[14:17]
	v_mfma_f32_16x16x32_bf16 v[10:13], v[142:145], v[214:217], v[10:13]
	v_mfma_f32_16x16x32_bf16 v[54:57], v[146:149], v[178:181], v[54:57]
	v_mfma_f32_16x16x32_bf16 v[50:53], v[170:173], v[178:181], v[50:53]
	v_mfma_f32_16x16x32_bf16 v[38:41], v[146:149], v[194:197], v[38:41]
	v_mfma_f32_16x16x32_bf16 v[34:37], v[170:173], v[194:197], v[34:37]
	v_mfma_f32_16x16x32_bf16 v[22:25], v[146:149], v[202:205], v[22:25]
	v_mfma_f32_16x16x32_bf16 v[18:21], v[170:173], v[202:205], v[18:21]
	v_mfma_f32_16x16x32_bf16 v[6:9], v[146:149], v[210:213], v[6:9]
	v_mfma_f32_16x16x32_bf16 v[2:5], v[170:173], v[210:213], v[2:5]
	v_mfma_f32_16x16x32_bf16 v[54:57], v[150:153], v[182:185], v[54:57]
	v_mfma_f32_16x16x32_bf16 v[50:53], v[174:177], v[182:185], v[50:53]
	v_mfma_f32_16x16x32_bf16 v[38:41], v[150:153], v[198:201], v[38:41]
	v_mfma_f32_16x16x32_bf16 v[34:37], v[174:177], v[198:201], v[34:37]
	v_mfma_f32_16x16x32_bf16 v[22:25], v[150:153], v[206:209], v[22:25]
	v_mfma_f32_16x16x32_bf16 v[18:21], v[174:177], v[206:209], v[18:21]
	v_mfma_f32_16x16x32_bf16 v[6:9], v[150:153], v[214:217], v[6:9]
	v_mfma_f32_16x16x32_bf16 v[2:5], v[174:177], v[214:217], v[2:5]
	s_barrier
; #define PG8_STAGE(bufoff, gbase, voff) do { _Pragma("unroll") for (int _i = 0; _i < 2; ++_i) \
;         __builtin_amdgcn_global_load_lds((const unsigned*)((const char*)(gbase) + (voff)[_i]), (PG8_LAS unsigned*)(lds + (bufoff) + ldsw + _i * 8192), 16, 0, 0); } while (0)
; #define PG8_LDA(dst, b, h) do { _Pragma("unroll") for (int m = 0; m < 4; ++m) _Pragma("unroll") for (int k = 0; k < 2; ++k) dst[m][k] = *(const PG8_LAS bf16x8*)(lds + PG8_SA(b, h) + aoff + m * 2048 + k * 1024); } while (0)
; #define PG8_LDB(dst, b, h) do { _Pragma("unroll") for (int n = 0; n < 2; ++n) _Pragma("unroll") for (int k = 0; k < 2; ++k) dst[n][k] = *(const PG8_LAS bf16x8*)(lds + PG8_SB(b, h) + boff + n * 2048 + k * 1024); } while (0)
; #define PG8_MMA(ai, bj, At, Bt) do { __builtin_amdgcn_s_setprio(1); _Pragma("unroll") for (int m = 0; m < 4; ++m) _Pragma("unroll") for (int n = 0; n < 2; ++n) _Pragma("unroll") for (int k = 0; k < 2; ++k) \
;         acc[ai][bj][m][n] = __builtin_amdgcn_mfma_f32_16x16x32_bf16(Bt[n][k], At[m][k], acc[ai][bj][m][n], 0, 0, 0); __builtin_amdgcn_s_setprio(0); } while (0)
; #define PG8_WAIT_V(n) asm volatile("s_waitcnt vmcnt(" #n ")" ::: "memory")
; #define PG8_WAIT_L(n) asm volatile("s_waitcnt lgkmcnt(" #n ")" ::: "memory")
; #define PG8_BAR __builtin_amdgcn_s_barrier()
; #define PG8_SCHED __builtin_amdgcn_sched_barrier(0)
; template <class Epi, class Sched, bool ALIGN_EPI = false, bool SP2 = false>
; __device__ __forceinline__ void gemm_phase(PG8_LAS unsigned char* lds, const Gemm g, const Sched& S, const Epi& E) {
;     ...
;             PG8_LDB(B0, 1, 0); PG8_LDB(B1, 1, 1); PG8_SCHED; PG8_LDA(At, 1, 0); PG8_STAGE(PG8_SA(0, 1), a2 + hA, voffA);
;             PG8_WAIT_V(8); PG8_WAIT_L(0); PG8_BAR; PG8_MMA(0, 0, At, B0); PG8_MMA(0, 1, At, B1); PG8_BAR; PG8_SCHED;
;             PG8_LDA(At, 1, 1); PG8_STAGE(PG8_SB(1, 0), b3, voffB); PG8_STAGE(PG8_SB(1, 1), b3 + hB, voffB); PG8_STAGE(PG8_SA(1, 0), a3, voffA);
;             PG8_WAIT_V(8); PG8_WAIT_L(0); PG8_BAR; PG8_MMA(1, 0, At, B0); PG8_MMA(1, 1, At, B1); PG8_BAR; PG8_SCHED;
;     ...
;         if constexpr (ALIGN_EPI) { if (wr == 0) PG8_BAR; }
	s_add_i32 s18, 0, 0x18000
	s_add_i32 s19, 0, 0x1c000
	v_add_u32_e32 v142, s18, v188
	v_add_u32_e32 v174, s19, v188
	ds_read_b128 v[130:133], v142
	ds_read_b128 v[134:137], v142 offset:1024
	ds_read_b128 v[138:141], v142 offset:2048
	ds_read_b128 v[142:145], v142 offset:3072
	ds_read_b128 v[146:149], v174
	ds_read_b128 v[150:153], v174 offset:1024
	ds_read_b128 v[170:173], v174 offset:2048
	ds_read_b128 v[174:177], v174 offset:3072
	s_add_u32 s24, s40, 0x160000
	s_addc_u32 s25, s41, 0
	s_mov_b32 m0, s48
	ds_read_b128 v[178:181], v192 offset:32768
	ds_read_b128 v[182:185], v192 offset:33792
	ds_read_b128 v[194:197], v192 offset:34816
	ds_read_b128 v[198:201], v192 offset:35840
	ds_read_b128 v[202:205], v192 offset:36864
	ds_read_b128 v[206:209], v192 offset:37888
	ds_read_b128 v[210:213], v192 offset:38912
	ds_read_b128 v[214:217], v192 offset:39936
	global_load_lds_dwordx4 v154, s[24:25]
	s_mov_b32 m0, s49
	s_nop 0
	global_load_lds_dwordx4 v158, s[24:25]
	s_waitcnt vmcnt(8)
	s_waitcnt lgkmcnt(0)
	s_barrier
	v_mfma_f32_16x16x32_bf16 v[126:129], v[130:133], v[178:181], v[126:129]
	v_mfma_f32_16x16x32_bf16 v[122:125], v[138:141], v[178:181], v[122:125]
	v_mfma_f32_16x16x32_bf16 v[110:113], v[130:133], v[194:197], v[110:113]
	v_mfma_f32_16x16x32_bf16 v[106:109], v[138:141], v[194:197], v[106:109]
	v_mfma_f32_16x16x32_bf16 v[94:97], v[130:133], v[202:205], v[94:97]
	v_mfma_f32_16x16x32_bf16 v[90:93], v[138:141], v[202:205], v[90:93]
	v_mfma_f32_16x16x32_bf16 v[78:81], v[130:133], v[210:213], v[78:81]
	v_mfma_f32_16x16x32_bf16 v[74:77], v[138:141], v[210:213], v[74:77]
	v_mfma_f32_16x16x32_bf16 v[126:129], v[134:137], v[182:185], v[126:129]
	v_mfma_f32_16x16x32_bf16 v[122:125], v[142:145], v[182:185], v[122:125]
	v_mfma_f32_16x16x32_bf16 v[110:113], v[134:137], v[198:201], v[110:113]
	v_mfma_f32_16x16x32_bf16 v[106:109], v[142:145], v[198:201], v[106:109]
	v_mfma_f32_16x16x32_bf16 v[94:97], v[134:137], v[206:209], v[94:97]
	v_mfma_f32_16x16x32_bf16 v[90:93], v[142:145], v[206:209], v[90:93]
	v_mfma_f32_16x16x32_bf16 v[78:81], v[134:137], v[214:217], v[78:81]
	v_mfma_f32_16x16x32_bf16 v[74:77], v[142:145], v[214:217], v[74:77]
	v_mfma_f32_16x16x32_bf16 v[118:121], v[146:149], v[178:181], v[118:121]
	v_mfma_f32_16x16x32_bf16 v[114:117], v[170:173], v[178:181], v[114:117]
	v_mfma_f32_16x16x32_bf16 v[102:105], v[146:149], v[194:197], v[102:105]
	v_mfma_f32_16x16x32_bf16 v[98:101], v[170:173], v[194:197], v[98:101]
	v_mfma_f32_16x16x32_bf16 v[86:89], v[146:149], v[202:205], v[86:89]
	v_mfma_f32_16x16x32_bf16 v[82:85], v[170:173], v[202:205], v[82:85]
	v_mfma_f32_16x16x32_bf16 v[70:73], v[146:149], v[210:213], v[70:73]
	v_mfma_f32_16x16x32_bf16 v[66:69], v[170:173], v[210:213], v[66:69]
	v_mfma_f32_16x16x32_bf16 v[118:121], v[150:153], v[182:185], v[118:121]
	v_mfma_f32_16x16x32_bf16 v[114:117], v[174:177], v[182:185], v[114:117]
	v_mfma_f32_16x16x32_bf16 v[102:105], v[150:153], v[198:201], v[102:105]
	v_mfma_f32_16x16x32_bf16 v[98:101], v[174:177], v[198:201], v[98:101]
	v_mfma_f32_16x16x32_bf16 v[86:89], v[150:153], v[206:209], v[86:89]
	v_mfma_f32_16x16x32_bf16 v[82:85], v[174:177], v[206:209], v[82:85]
	v_mfma_f32_16x16x32_bf16 v[70:73], v[150:153], v[214:217], v[70:73]
	v_mfma_f32_16x16x32_bf16 v[66:69], v[174:177], v[214:217], v[66:69]
	s_barrier
	s_add_i32 s18, s18, s45
	s_mov_b32 m0, s18
	ds_read_b128 v[178:181], v192 offset:49152
	ds_read_b128 v[182:185], v192 offset:50176
	ds_read_b128 v[194:197], v192 offset:51200
	ds_read_b128 v[198:201], v192 offset:52224
	ds_read_b128 v[202:205], v192 offset:53248
	ds_read_b128 v[206:209], v192 offset:54272
	ds_read_b128 v[210:213], v192 offset:55296
	ds_read_b128 v[214:217], v192 offset:56320
	global_load_lds_dwordx4 v156, s[76:77]
	s_add_i32 m0, s18, 0x2000
	s_add_u32 s24, s38, 0x160080
	s_addc_u32 s25, s39, 0
	s_add_i32 s18, s19, s45
	global_load_lds_dwordx4 v160, s[76:77]
	s_mov_b32 m0, s18
	s_nop 0
	global_load_lds_dwordx4 v156, s[24:25]
	s_add_i32 m0, s18, 0x2000
	s_nop 0
	global_load_lds_dwordx4 v160, s[24:25]
	s_mov_b32 m0, s52
	s_nop 0
	global_load_lds_dwordx4 v154, s[78:79]
	s_mov_b32 m0, s53
	s_nop 0
	global_load_lds_dwordx4 v158, s[78:79]
	s_waitcnt vmcnt(8)
	s_waitcnt lgkmcnt(0)
	s_barrier
	v_mfma_f32_16x16x32_bf16 v[62:65], v[130:133], v[178:181], v[62:65]
	v_mfma_f32_16x16x32_bf16 v[58:61], v[138:141], v[178:181], v[58:61]
	v_mfma_f32_16x16x32_bf16 v[46:49], v[130:133], v[194:197], v[46:49]
	v_mfma_f32_16x16x32_bf16 v[42:45], v[138:141], v[194:197], v[42:45]
	v_mfma_f32_16x16x32_bf16 v[30:33], v[130:133], v[202:205], v[30:33]
	v_mfma_f32_16x16x32_bf16 v[26:29], v[138:141], v[202:205], v[26:29]
	v_mfma_f32_16x16x32_bf16 v[14:17], v[130:133], v[210:213], v[14:17]
	v_mfma_f32_16x16x32_bf16 v[10:13], v[138:141], v[210:213], v[10:13]
	v_mfma_f32_16x16x32_bf16 v[62:65], v[134:137], v[182:185], v[62:65]
	v_mfma_f32_16x16x32_bf16 v[58:61], v[142:145], v[182:185], v[58:61]
	v_mfma_f32_16x16x32_bf16 v[46:49], v[134:137], v[198:201], v[46:49]
	v_mfma_f32_16x16x32_bf16 v[42:45], v[142:145], v[198:201], v[42:45]
	v_mfma_f32_16x16x32_bf16 v[30:33], v[134:137], v[206:209], v[30:33]
	v_mfma_f32_16x16x32_bf16 v[26:29], v[142:145], v[206:209], v[26:29]
	v_mfma_f32_16x16x32_bf16 v[14:17], v[134:137], v[214:217], v[14:17]
	v_mfma_f32_16x16x32_bf16 v[10:13], v[142:145], v[214:217], v[10:13]
	v_mfma_f32_16x16x32_bf16 v[54:57], v[146:149], v[178:181], v[54:57]
	v_mfma_f32_16x16x32_bf16 v[50:53], v[170:173], v[178:181], v[50:53]
	v_mfma_f32_16x16x32_bf16 v[38:41], v[146:149], v[194:197], v[38:41]
	v_mfma_f32_16x16x32_bf16 v[34:37], v[170:173], v[194:197], v[34:37]
	v_mfma_f32_16x16x32_bf16 v[22:25], v[146:149], v[202:205], v[22:25]
	v_mfma_f32_16x16x32_bf16 v[18:21], v[170:173], v[202:205], v[18:21]
	v_mfma_f32_16x16x32_bf16 v[6:9], v[146:149], v[210:213], v[6:9]
	v_mfma_f32_16x16x32_bf16 v[2:5], v[170:173], v[210:213], v[2:5]
	v_mfma_f32_16x16x32_bf16 v[54:57], v[150:153], v[182:185], v[54:57]
	v_mfma_f32_16x16x32_bf16 v[50:53], v[174:177], v[182:185], v[50:53]
	v_mfma_f32_16x16x32_bf16 v[38:41], v[150:153], v[198:201], v[38:41]
	v_mfma_f32_16x16x32_bf16 v[34:37], v[174:177], v[198:201], v[34:37]
	v_mfma_f32_16x16x32_bf16 v[22:25], v[150:153], v[206:209], v[22:25]
	v_mfma_f32_16x16x32_bf16 v[18:21], v[174:177], v[206:209], v[18:21]
	v_mfma_f32_16x16x32_bf16 v[6:9], v[150:153], v[214:217], v[6:9]
	v_mfma_f32_16x16x32_bf16 v[2:5], v[174:177], v[214:217], v[2:5]
	s_barrier
	s_add_i32 s63, s63, 2
	s_add_u32 s61, s61, 0x100
	s_addc_u32 s62, s62, 0
	s_cmpk_gt_u32 s63, 0x55
	s_mov_b64 s[24:25], s[36:37]
	s_cbranch_scc0 .LBB0_1127
	s_and_b64 vcc, exec, s[20:21]
	s_cbranch_vccz .LBB0_1130
	s_barrier
